# GEMM loops: LDS-DMA loads use SGPR base + 32-bit lane offset (saddr form) instead of a per-load 64-bit VALU address add
# speedup vs baseline: 1.0082x; 1.0082x over previous
; #define PG8_STAGE(bufoff, gbase, voff) do { _Pragma("unroll") for (int _i = 0; _i < 2; ++_i) \
;         __builtin_amdgcn_global_load_lds((const unsigned*)((const char*)(gbase) + (voff)[_i]), (PG8_LAS unsigned*)(lds + (bufoff) + ldsw + _i * 8192), 16, 0, 0); } while (0)
; #define PG8_WAIT_V(n) asm volatile("s_waitcnt vmcnt(" #n ")" ::: "memory")
; #define PG8_BAR __builtin_amdgcn_s_barrier()
; template <class Epi, class Sched, bool ALIGN_EPI = false, bool SP2 = false>
; __device__ __forceinline__ void gemm_phase(PG8_LAS unsigned char* lds, const Gemm g, const Sched& S, const Epi& E) {
;     ...
;     for (int i = 0; i < 2; ++i) { int R, C; stage_rc(tid * 16 + i * 8192, R, C); const int Rb = Epi::PERM ? ((R & ~31) + perm32(R & 31)) : R;
;         voffA[i] = (unsigned)(R * g.lda + C) * 2u; voffB[i] = (unsigned)(Rb * g.ldb + C) * 2u; }
;     const size_t kstep = (size_t)(BK * 2);
;     const size_t hstepA = (size_t)HALF * g.lda * 2, hstepB = (size_t)HALF * g.ldb * 2;
;     const size_t tstepA = 2 * hstepA, tstepB = 2 * hstepB;
;     const unsigned ldsw = (unsigned)wid * 1024u;
;     const int aoff = lds_byte(wr * 64 + fr, fq * 8), boff = lds_byte(wc * 32 + fr, fq * 8);
;     ...
;         PG8_WAIT_V(2); PG8_BAR;
;         PG8_STAGE(PG8_SB(1, 0), cB + kstep, voffB); PG8_STAGE(PG8_SA(1, 0), cA + kstep, voffA); PG8_STAGE(PG8_SB(1, 1), cB + hstepB + kstep, voffB);
;         PG8_WAIT_V(6); PG8_BAR;
.LBB0_129:
	s_lshl_b32 s1, s14, 5
	s_and_b32 s25, s1, 0x60
	s_add_i32 m0, s26, 0x18000
	v_lshl_add_u64 v[6:7], v[6:7], 0, s[10:11]
	s_lshl_b32 s24, s12, 13
	s_lshl_b32 s28, s25, 7
	s_waitcnt vmcnt(2)
	s_barrier
	global_load_lds_dwordx4 v[6:7], off
	v_lshl_add_u64 v[4:5], v[4:5], 0, s[10:11]
	s_add_i32 m0, s26, 0x1a000
	s_add_i32 s50, s26, 0x8000
	s_add_i32 s51, s26, 0xa000
	global_load_lds_dwordx4 v[4:5], off
	v_lshl_add_u64 v[0:1], v[0:1], 0, s[10:11]
	s_mov_b32 m0, s50
	s_add_u32 s14, s22, 0x40080
	global_load_lds_dwordx4 v[0:1], off
	v_lshl_add_u64 v[0:1], v[2:3], 0, s[10:11]
	s_mov_b32 m0, s51
	s_addc_u32 s15, s23, 0
	global_load_lds_dwordx4 v[0:1], off
	s_add_i32 m0, s26, 0x1c000
	v_lshl_add_u64 v[0:1], s[14:15], 0, v[208:209]
	global_load_lds_dwordx4 v208, s[14:15]
	v_lshl_add_u64 v[0:1], s[14:15], 0, v[128:129]
	s_add_i32 m0, s26, 0x1e000
	s_cmpk_lt_u32 s7, 0x100
	global_load_lds_dwordx4 v128, s[14:15]
	v_lshrrev_b32_e32 v1, 1, v9
	v_and_b32_e32 v1, 24, v1
	v_and_b32_e32 v0, 15, v9
	v_lshlrev_b32_e32 v2, 1, v1
	v_lshl_or_b32 v140, s12, 6, v0
	v_lshl_or_b32 v0, v0, 6, v2
	v_lshlrev_b32_e32 v2, 2, v9
	v_and_b32_e32 v2, 32, v2
	v_bitop3_b32 v3, v0, s24, v2 bitop3:0xde
	v_bitop3_b32 v141, v0, s28, v2 bitop3:0xde
	v_lshlrev_b32_e32 v0, 14, v13
	v_and_b32_e32 v0, 0xffff8000, v0
	v_or_b32_e32 v142, s25, v1
	v_lshl_add_u32 v0, v12, 11, v0
	v_and_b32_e32 v1, 1, v13
	v_lshl_or_b32 v0, v1, 6, v0
	v_lshl_add_u32 v134, v14, 1, v0
	v_lshlrev_b32_e32 v0, 14, v8
	v_and_b32_e32 v0, 0xffff8000, v0
	s_waitcnt vmcnt(6)
	v_lshl_add_u32 v0, v10, 11, v0
	v_and_b32_e32 v1, 1, v8
	v_lshl_or_b32 v0, v1, 6, v0
	s_sext_i32_i16 s1, s6
	s_cselect_b64 s[6:7], -1, 0
	v_mov_b32_e32 v135, v209
	v_lshl_add_u32 v136, v11, 1, v0
	v_mov_b32_e32 v137, v209
	s_mov_b32 s52, 0
	v_add_u32_e32 v143, 0, v3
	s_barrier
	s_branch .LBB0_132

; #define PG8_STAGE(bufoff, gbase, voff) do { _Pragma("unroll") for (int _i = 0; _i < 2; ++_i) \
;         __builtin_amdgcn_global_load_lds((const unsigned*)((const char*)(gbase) + (voff)[_i]), (PG8_LAS unsigned*)(lds + (bufoff) + ldsw + _i * 8192), 16, 0, 0); } while (0)
; #define PG8_LDA(dst, b, h) do { _Pragma("unroll") for (int m = 0; m < 4; ++m) _Pragma("unroll") for (int k = 0; k < 2; ++k) dst[m][k] = *(const PG8_LAS bf16x8*)(lds + PG8_SA(b, h) + aoff + m * 2048 + k * 1024); } while (0)
; #define PG8_LDB(dst, b, h) do { _Pragma("unroll") for (int n = 0; n < 2; ++n) _Pragma("unroll") for (int k = 0; k < 2; ++k) dst[n][k] = *(const PG8_LAS bf16x8*)(lds + PG8_SB(b, h) + boff + n * 2048 + k * 1024); } while (0)
; #define PG8_MMA(ai, bj, At, Bt) do { __builtin_amdgcn_s_setprio(1); _Pragma("unroll") for (int m = 0; m < 4; ++m) _Pragma("unroll") for (int n = 0; n < 2; ++n) _Pragma("unroll") for (int k = 0; k < 2; ++k) \
;         acc[ai][bj][m][n] = __builtin_amdgcn_mfma_f32_16x16x32_bf16(Bt[n][k], At[m][k], acc[ai][bj][m][n], 0, 0, 0); __builtin_amdgcn_s_setprio(0); } while (0)
; #define PG8_WAIT_V(n) asm volatile("s_waitcnt vmcnt(" #n ")" ::: "memory")
; #define PG8_WAIT_L(n) asm volatile("s_waitcnt lgkmcnt(" #n ")" ::: "memory")
; #define PG8_BAR __builtin_amdgcn_s_barrier()
; #define PG8_SCHED __builtin_amdgcn_sched_barrier(0)
; template <class Epi, class Sched, bool ALIGN_EPI = false, bool SP2 = false>
; __device__ __forceinline__ void gemm_phase(PG8_LAS unsigned char* lds, const Gemm g, const Sched& S, const Epi& E) {
;     ...
;             const bool last = (t == nt - 2);
;             const char* a1 = cA + (size_t)(t + 1) * kstep;
;             const char* a2 = last ? nA : cA + (size_t)(t + 2) * kstep; const char* b2 = last ? nB : cB + (size_t)(t + 2) * kstep;
;             const char* a3 = a2 + kstep; const char* b3 = b2 + kstep;
;             if (last && has_next) S.a_ready(nxt);
;             if constexpr (SP2) {
;             PG8_LDB(B0, 0, 0); PG8_LDB(B1, 0, 1); PG8_SCHED; PG8_LDA(At, 0, 0); PG8_STAGE(PG8_SA(1, 1), a1 + hstepA, voffA);
;             PG8_WAIT_V(8); PG8_WAIT_L(0); PG8_BAR; PG8_MMA(0, 0, At, B0); PG8_MMA(0, 1, At, B1); PG8_BAR; PG8_SCHED;
;             PG8_LDA(At, 0, 1); PG8_STAGE(PG8_SB(0, 0), b2, voffB); PG8_STAGE(PG8_SB(0, 1), b2 + hstepB, voffB); PG8_STAGE(PG8_SA(0, 0), a2, voffA);
.LBB0_135:
	s_add_u32 s22, s20, 0xfffc0080
	s_addc_u32 s23, s21, -1
	s_add_i32 s28, 0, 0x10000
	s_cmp_eq_u32 s53, 12
	s_cselect_b32 s25, s12, s23
	s_cselect_b32 s24, s14, s22
	v_add_u32_e32 v138, s28, v141
	s_cselect_b32 s23, s15, s45
	s_cselect_b32 s22, s38, s43
	s_add_i32 s29, 0, 0x14000
	ds_read_b128 v[144:147], v138
	ds_read_b128 v[148:151], v138 offset:1024
	ds_read_b128 v[152:155], v138 offset:2048
	ds_read_b128 v[156:159], v138 offset:3072
	v_add_u32_e32 v138, s29, v141
	ds_read_b128 v[160:163], v138
	ds_read_b128 v[164:167], v138 offset:1024
	ds_read_b128 v[168:171], v138 offset:2048
	ds_read_b128 v[172:175], v138 offset:3072
	s_add_i32 m0, s26, 0xc000
	ds_read_b128 v[176:179], v143
	ds_read_b128 v[180:183], v143 offset:1024
	ds_read_b128 v[184:187], v143 offset:2048
	ds_read_b128 v[188:191], v143 offset:3072
	ds_read_b128 v[192:195], v143 offset:4096
	ds_read_b128 v[196:199], v143 offset:5120
	ds_read_b128 v[200:203], v143 offset:6144
	ds_read_b128 v[204:207], v143 offset:7168
	global_load_lds_dwordx4 v134, s[20:21]
	s_add_i32 m0, s26, 0xe000
	s_nop 0
	global_load_lds_dwordx4 v136, s[20:21]
	s_waitcnt vmcnt(8)
	s_waitcnt lgkmcnt(0)
	s_barrier
	s_waitcnt lgkmcnt(0)
	v_mfma_f32_16x16x32_bf16 v[124:127], v[144:147], v[176:179], v[124:127]
	v_mfma_f32_16x16x32_bf16 v[120:123], v[152:155], v[176:179], v[120:123]
	v_mfma_f32_16x16x32_bf16 v[108:111], v[144:147], v[184:187], v[108:111]
	v_mfma_f32_16x16x32_bf16 v[104:107], v[152:155], v[184:187], v[104:107]
	v_mfma_f32_16x16x32_bf16 v[92:95], v[144:147], v[192:195], v[92:95]
	v_mfma_f32_16x16x32_bf16 v[88:91], v[152:155], v[192:195], v[88:91]
	v_mfma_f32_16x16x32_bf16 v[76:79], v[144:147], v[200:203], v[76:79]
	v_mfma_f32_16x16x32_bf16 v[72:75], v[152:155], v[200:203], v[72:75]
	v_mfma_f32_16x16x32_bf16 v[124:127], v[148:151], v[180:183], v[124:127]
	v_mfma_f32_16x16x32_bf16 v[120:123], v[156:159], v[180:183], v[120:123]
	v_mfma_f32_16x16x32_bf16 v[108:111], v[148:151], v[188:191], v[108:111]
	v_mfma_f32_16x16x32_bf16 v[104:107], v[156:159], v[188:191], v[104:107]
	v_mfma_f32_16x16x32_bf16 v[92:95], v[148:151], v[196:199], v[92:95]
	v_mfma_f32_16x16x32_bf16 v[88:91], v[156:159], v[196:199], v[88:91]
	v_mfma_f32_16x16x32_bf16 v[76:79], v[148:151], v[204:207], v[76:79]
	v_mfma_f32_16x16x32_bf16 v[72:75], v[156:159], v[204:207], v[72:75]
	v_mfma_f32_16x16x32_bf16 v[116:119], v[160:163], v[176:179], v[116:119]
	v_mfma_f32_16x16x32_bf16 v[112:115], v[168:171], v[176:179], v[112:115]
	v_mfma_f32_16x16x32_bf16 v[100:103], v[160:163], v[184:187], v[100:103]
	v_mfma_f32_16x16x32_bf16 v[96:99], v[168:171], v[184:187], v[96:99]
	v_mfma_f32_16x16x32_bf16 v[84:87], v[160:163], v[192:195], v[84:87]
	v_mfma_f32_16x16x32_bf16 v[80:83], v[168:171], v[192:195], v[80:83]
	v_mfma_f32_16x16x32_bf16 v[68:71], v[160:163], v[200:203], v[68:71]
	v_mfma_f32_16x16x32_bf16 v[64:67], v[168:171], v[200:203], v[64:67]
	v_mfma_f32_16x16x32_bf16 v[116:119], v[164:167], v[180:183], v[116:119]
	v_mfma_f32_16x16x32_bf16 v[112:115], v[172:175], v[180:183], v[112:115]
	v_mfma_f32_16x16x32_bf16 v[100:103], v[164:167], v[188:191], v[100:103]
	v_mfma_f32_16x16x32_bf16 v[96:99], v[172:175], v[188:191], v[96:99]
	v_mfma_f32_16x16x32_bf16 v[84:87], v[164:167], v[196:199], v[84:87]
	v_mfma_f32_16x16x32_bf16 v[80:83], v[172:175], v[196:199], v[80:83]
	v_mfma_f32_16x16x32_bf16 v[68:71], v[164:167], v[204:207], v[68:71]
	v_mfma_f32_16x16x32_bf16 v[64:67], v[172:175], v[204:207], v[64:67]
	s_barrier
	s_add_i32 s28, s28, s18
	v_lshl_add_u64 v[138:139], s[22:23], 0, v[208:209]
	s_mov_b32 m0, s28
	ds_read_b128 v[176:179], v143 offset:16384
	ds_read_b128 v[180:183], v143 offset:17408
	ds_read_b128 v[184:187], v143 offset:18432
	ds_read_b128 v[188:191], v143 offset:19456
	ds_read_b128 v[192:195], v143 offset:20480
	ds_read_b128 v[196:199], v143 offset:21504
	ds_read_b128 v[200:203], v143 offset:22528
	ds_read_b128 v[204:207], v143 offset:23552
	global_load_lds_dwordx4 v208, s[22:23]
	s_add_i32 m0, s28, 0x2000
	s_add_u32 s54, s22, 0x40000
	v_lshl_add_u64 v[210:211], s[22:23], 0, v[128:129]
	s_addc_u32 s55, s23, 0
	s_add_i32 s28, s29, s18
	global_load_lds_dwordx4 v128, s[22:23]
	s_mov_b32 m0, s28
	v_lshl_add_u64 v[222:223], s[24:25], 0, v[130:131]
	global_load_lds_dwordx4 v208, s[54:55]
	s_add_i32 m0, s28, 0x2000
	s_nop 0
	global_load_lds_dwordx4 v128, s[54:55]
	v_lshl_add_u64 v[212:213], s[24:25], 0, v[132:133]
	s_mov_b32 m0, s26
	s_nop 0
	global_load_lds_dwordx4 v132, s[24:25]
	s_mov_b32 m0, s34
	s_nop 0
	global_load_lds_dwordx4 v130, s[24:25]
	s_waitcnt vmcnt(8)
	s_waitcnt lgkmcnt(0)
	s_barrier
; #define PG8_STAGE(bufoff, gbase, voff) do { _Pragma("unroll") for (int _i = 0; _i < 2; ++_i) \
;         __builtin_amdgcn_global_load_lds((const unsigned*)((const char*)(gbase) + (voff)[_i]), (PG8_LAS unsigned*)(lds + (bufoff) + ldsw + _i * 8192), 16, 0, 0); } while (0)
; #define PG8_LDA(dst, b, h) do { _Pragma("unroll") for (int m = 0; m < 4; ++m) _Pragma("unroll") for (int k = 0; k < 2; ++k) dst[m][k] = *(const PG8_LAS bf16x8*)(lds + PG8_SA(b, h) + aoff + m * 2048 + k * 1024); } while (0)
; #define PG8_LDB(dst, b, h) do { _Pragma("unroll") for (int n = 0; n < 2; ++n) _Pragma("unroll") for (int k = 0; k < 2; ++k) dst[n][k] = *(const PG8_LAS bf16x8*)(lds + PG8_SB(b, h) + boff + n * 2048 + k * 1024); } while (0)
; #define PG8_MMA(ai, bj, At, Bt) do { __builtin_amdgcn_s_setprio(1); _Pragma("unroll") for (int m = 0; m < 4; ++m) _Pragma("unroll") for (int n = 0; n < 2; ++n) _Pragma("unroll") for (int k = 0; k < 2; ++k) \
;         acc[ai][bj][m][n] = __builtin_amdgcn_mfma_f32_16x16x32_bf16(Bt[n][k], At[m][k], acc[ai][bj][m][n], 0, 0, 0); __builtin_amdgcn_s_setprio(0); } while (0)
; #define PG8_WAIT_V(n) asm volatile("s_waitcnt vmcnt(" #n ")" ::: "memory")
; #define PG8_WAIT_L(n) asm volatile("s_waitcnt lgkmcnt(" #n ")" ::: "memory")
; #define PG8_BAR __builtin_amdgcn_s_barrier()
; #define PG8_SCHED __builtin_amdgcn_sched_barrier(0)
; template <class Epi, class Sched, bool ALIGN_EPI = false, bool SP2 = false>
; __device__ __forceinline__ void gemm_phase(PG8_LAS unsigned char* lds, const Gemm g, const Sched& S, const Epi& E) {
;     ...
;             PG8_WAIT_V(8); PG8_WAIT_L(0); PG8_BAR; PG8_MMA(1, 0, At, B0); PG8_MMA(1, 1, At, B1); PG8_BAR; PG8_SCHED;
;             PG8_LDB(B0, 1, 0); PG8_LDB(B1, 1, 1); PG8_SCHED; PG8_LDA(At, 1, 0); PG8_STAGE(PG8_SA(0, 1), a2 + hstepA, voffA);
;             PG8_WAIT_V(8); PG8_WAIT_L(0); PG8_BAR; PG8_MMA(0, 0, At, B0); PG8_MMA(0, 1, At, B1); PG8_BAR; PG8_SCHED;
	s_waitcnt lgkmcnt(0)
	v_mfma_f32_16x16x32_bf16 v[60:63], v[144:147], v[176:179], v[60:63]
	v_mfma_f32_16x16x32_bf16 v[56:59], v[152:155], v[176:179], v[56:59]
	v_mfma_f32_16x16x32_bf16 v[44:47], v[144:147], v[184:187], v[44:47]
	v_mfma_f32_16x16x32_bf16 v[40:43], v[152:155], v[184:187], v[40:43]
	v_mfma_f32_16x16x32_bf16 v[28:31], v[144:147], v[192:195], v[28:31]
	v_mfma_f32_16x16x32_bf16 v[24:27], v[152:155], v[192:195], v[24:27]
	v_mfma_f32_16x16x32_bf16 v[12:15], v[144:147], v[200:203], v[12:15]
	v_mfma_f32_16x16x32_bf16 v[8:11], v[152:155], v[200:203], v[8:11]
	v_mfma_f32_16x16x32_bf16 v[60:63], v[148:151], v[180:183], v[60:63]
	v_mfma_f32_16x16x32_bf16 v[56:59], v[156:159], v[180:183], v[56:59]
	v_mfma_f32_16x16x32_bf16 v[44:47], v[148:151], v[188:191], v[44:47]
	v_mfma_f32_16x16x32_bf16 v[40:43], v[156:159], v[188:191], v[40:43]
	v_mfma_f32_16x16x32_bf16 v[28:31], v[148:151], v[196:199], v[28:31]
	v_mfma_f32_16x16x32_bf16 v[24:27], v[156:159], v[196:199], v[24:27]
	v_mfma_f32_16x16x32_bf16 v[12:15], v[148:151], v[204:207], v[12:15]
	v_mfma_f32_16x16x32_bf16 v[8:11], v[156:159], v[204:207], v[8:11]
	v_mfma_f32_16x16x32_bf16 v[52:55], v[160:163], v[176:179], v[52:55]
	v_mfma_f32_16x16x32_bf16 v[48:51], v[168:171], v[176:179], v[48:51]
	v_mfma_f32_16x16x32_bf16 v[36:39], v[160:163], v[184:187], v[36:39]
	v_mfma_f32_16x16x32_bf16 v[32:35], v[168:171], v[184:187], v[32:35]
	v_mfma_f32_16x16x32_bf16 v[20:23], v[160:163], v[192:195], v[20:23]
	v_mfma_f32_16x16x32_bf16 v[16:19], v[168:171], v[192:195], v[16:19]
	v_mfma_f32_16x16x32_bf16 v[4:7], v[160:163], v[200:203], v[4:7]
	v_mfma_f32_16x16x32_bf16 v[0:3], v[168:171], v[200:203], v[0:3]
	v_mfma_f32_16x16x32_bf16 v[52:55], v[164:167], v[180:183], v[52:55]
	v_mfma_f32_16x16x32_bf16 v[48:51], v[172:175], v[180:183], v[48:51]
	v_mfma_f32_16x16x32_bf16 v[36:39], v[164:167], v[188:191], v[36:39]
	v_mfma_f32_16x16x32_bf16 v[32:35], v[172:175], v[188:191], v[32:35]
	v_mfma_f32_16x16x32_bf16 v[20:23], v[164:167], v[196:199], v[20:23]
	v_mfma_f32_16x16x32_bf16 v[16:19], v[172:175], v[196:199], v[16:19]
	v_mfma_f32_16x16x32_bf16 v[4:7], v[164:167], v[204:207], v[4:7]
	v_mfma_f32_16x16x32_bf16 v[0:3], v[172:175], v[204:207], v[0:3]
	s_barrier
	s_add_i32 s28, 0, 0x18000
	s_add_i32 s29, 0, 0x1c000
	v_add_u32_e32 v156, s28, v141
	v_add_u32_e32 v172, s29, v141
	ds_read_b128 v[144:147], v156
	ds_read_b128 v[148:151], v156 offset:1024
	ds_read_b128 v[152:155], v156 offset:2048
	ds_read_b128 v[156:159], v156 offset:3072
	ds_read_b128 v[160:163], v172
	ds_read_b128 v[164:167], v172 offset:1024
	ds_read_b128 v[168:171], v172 offset:2048
	ds_read_b128 v[172:175], v172 offset:3072
	s_add_u32 s24, s24, 0x40000
	s_addc_u32 s25, s25, 0
	s_mov_b32 m0, s35
	ds_read_b128 v[176:179], v143 offset:32768
	ds_read_b128 v[180:183], v143 offset:33792
	ds_read_b128 v[184:187], v143 offset:34816
	ds_read_b128 v[188:191], v143 offset:35840
	ds_read_b128 v[192:195], v143 offset:36864
	ds_read_b128 v[196:199], v143 offset:37888
	ds_read_b128 v[200:203], v143 offset:38912
	ds_read_b128 v[204:207], v143 offset:39936
	global_load_lds_dwordx4 v132, s[24:25]
	v_lshl_add_u64 v[224:225], s[24:25], 0, v[130:131]
	s_mov_b32 m0, s39
	s_nop 0
	global_load_lds_dwordx4 v130, s[24:25]
	s_waitcnt vmcnt(8)
	s_waitcnt lgkmcnt(0)
	s_barrier
	s_waitcnt lgkmcnt(0)
	v_mfma_f32_16x16x32_bf16 v[124:127], v[144:147], v[176:179], v[124:127]
	v_mfma_f32_16x16x32_bf16 v[120:123], v[152:155], v[176:179], v[120:123]
	v_mfma_f32_16x16x32_bf16 v[108:111], v[144:147], v[184:187], v[108:111]
	v_mfma_f32_16x16x32_bf16 v[104:107], v[152:155], v[184:187], v[104:107]
	v_mfma_f32_16x16x32_bf16 v[92:95], v[144:147], v[192:195], v[92:95]
	v_mfma_f32_16x16x32_bf16 v[88:91], v[152:155], v[192:195], v[88:91]
	v_mfma_f32_16x16x32_bf16 v[76:79], v[144:147], v[200:203], v[76:79]
	v_mfma_f32_16x16x32_bf16 v[72:75], v[152:155], v[200:203], v[72:75]
	v_mfma_f32_16x16x32_bf16 v[124:127], v[148:151], v[180:183], v[124:127]
	v_mfma_f32_16x16x32_bf16 v[120:123], v[156:159], v[180:183], v[120:123]
	v_mfma_f32_16x16x32_bf16 v[108:111], v[148:151], v[188:191], v[108:111]
	v_mfma_f32_16x16x32_bf16 v[104:107], v[156:159], v[188:191], v[104:107]
	v_mfma_f32_16x16x32_bf16 v[92:95], v[148:151], v[196:199], v[92:95]
	v_mfma_f32_16x16x32_bf16 v[88:91], v[156:159], v[196:199], v[88:91]
	v_mfma_f32_16x16x32_bf16 v[76:79], v[148:151], v[204:207], v[76:79]
	v_mfma_f32_16x16x32_bf16 v[72:75], v[156:159], v[204:207], v[72:75]
	v_mfma_f32_16x16x32_bf16 v[116:119], v[160:163], v[176:179], v[116:119]
	v_mfma_f32_16x16x32_bf16 v[112:115], v[168:171], v[176:179], v[112:115]
	v_mfma_f32_16x16x32_bf16 v[100:103], v[160:163], v[184:187], v[100:103]
	v_mfma_f32_16x16x32_bf16 v[96:99], v[168:171], v[184:187], v[96:99]
	v_mfma_f32_16x16x32_bf16 v[84:87], v[160:163], v[192:195], v[84:87]
	v_mfma_f32_16x16x32_bf16 v[80:83], v[168:171], v[192:195], v[80:83]
	v_mfma_f32_16x16x32_bf16 v[68:71], v[160:163], v[200:203], v[68:71]
	v_mfma_f32_16x16x32_bf16 v[64:67], v[168:171], v[200:203], v[64:67]
	v_mfma_f32_16x16x32_bf16 v[116:119], v[164:167], v[180:183], v[116:119]
	v_mfma_f32_16x16x32_bf16 v[112:115], v[172:175], v[180:183], v[112:115]
	v_mfma_f32_16x16x32_bf16 v[100:103], v[164:167], v[188:191], v[100:103]
	v_mfma_f32_16x16x32_bf16 v[96:99], v[172:175], v[188:191], v[96:99]
	v_mfma_f32_16x16x32_bf16 v[84:87], v[164:167], v[196:199], v[84:87]
	v_mfma_f32_16x16x32_bf16 v[80:83], v[172:175], v[196:199], v[80:83]
	v_mfma_f32_16x16x32_bf16 v[68:71], v[164:167], v[204:207], v[68:71]
	v_mfma_f32_16x16x32_bf16 v[64:67], v[172:175], v[204:207], v[64:67]
	s_barrier
; #define PG8_STAGE(bufoff, gbase, voff) do { _Pragma("unroll") for (int _i = 0; _i < 2; ++_i) \
;         __builtin_amdgcn_global_load_lds((const unsigned*)((const char*)(gbase) + (voff)[_i]), (PG8_LAS unsigned*)(lds + (bufoff) + ldsw + _i * 8192), 16, 0, 0); } while (0)
; #define PG8_LDA(dst, b, h) do { _Pragma("unroll") for (int m = 0; m < 4; ++m) _Pragma("unroll") for (int k = 0; k < 2; ++k) dst[m][k] = *(const PG8_LAS bf16x8*)(lds + PG8_SA(b, h) + aoff + m * 2048 + k * 1024); } while (0)
; #define PG8_MMA(ai, bj, At, Bt) do { __builtin_amdgcn_s_setprio(1); _Pragma("unroll") for (int m = 0; m < 4; ++m) _Pragma("unroll") for (int n = 0; n < 2; ++n) _Pragma("unroll") for (int k = 0; k < 2; ++k) \
;         acc[ai][bj][m][n] = __builtin_amdgcn_mfma_f32_16x16x32_bf16(Bt[n][k], At[m][k], acc[ai][bj][m][n], 0, 0, 0); __builtin_amdgcn_s_setprio(0); } while (0)
; #define PG8_WAIT_V(n) asm volatile("s_waitcnt vmcnt(" #n ")" ::: "memory")
; #define PG8_WAIT_L(n) asm volatile("s_waitcnt lgkmcnt(" #n ")" ::: "memory")
; #define PG8_BAR __builtin_amdgcn_s_barrier()
; #define PG8_SCHED __builtin_amdgcn_sched_barrier(0)
; template <class Epi, class Sched, bool ALIGN_EPI = false, bool SP2 = false>
; __device__ __forceinline__ void gemm_phase(PG8_LAS unsigned char* lds, const Gemm g, const Sched& S, const Epi& E) {
;     ...
;             PG8_LDA(At, 1, 1); PG8_STAGE(PG8_SB(1, 0), b3, voffB); PG8_STAGE(PG8_SB(1, 1), b3 + hstepB, voffB); PG8_STAGE(PG8_SA(1, 0), a3, voffA);
;             PG8_WAIT_V(8); PG8_WAIT_L(0); PG8_BAR; PG8_MMA(1, 0, At, B0); PG8_MMA(1, 1, At, B1); PG8_BAR; PG8_SCHED;
;     ...
;         }
;         if constexpr (ALIGN_EPI) { if (wr == 0) PG8_BAR; }
	s_add_i32 s24, s28, s18
	v_lshl_add_u64 v[138:139], v[138:139], 0, s[10:11]
	s_mov_b32 m0, s24
	ds_read_b128 v[176:179], v143 offset:49152
	ds_read_b128 v[180:183], v143 offset:50176
	ds_read_b128 v[184:187], v143 offset:51200
	ds_read_b128 v[188:191], v143 offset:52224
	ds_read_b128 v[192:195], v143 offset:53248
	ds_read_b128 v[196:199], v143 offset:54272
	ds_read_b128 v[200:203], v143 offset:55296
	ds_read_b128 v[204:207], v143 offset:56320
	global_load_lds_dwordx4 v[138:139], off
	s_add_i32 m0, s24, 0x2000
	s_add_u32 s22, s22, 0x40080
	v_lshl_add_u64 v[138:139], v[210:211], 0, s[10:11]
	s_addc_u32 s23, s23, 0
	s_add_i32 s24, s29, s18
	global_load_lds_dwordx4 v[138:139], off
	s_mov_b32 m0, s24
	s_nop 0
	global_load_lds_dwordx4 v208, s[22:23]
	s_add_i32 m0, s24, 0x2000
	s_nop 0
	global_load_lds_dwordx4 v128, s[22:23]
	v_lshl_add_u64 v[138:139], v[212:213], 0, s[10:11]
	s_mov_b32 m0, s50
	s_nop 0
	global_load_lds_dwordx4 v[138:139], off
	v_lshl_add_u64 v[138:139], v[222:223], 0, s[10:11]
	s_mov_b32 m0, s51
	s_nop 0
	global_load_lds_dwordx4 v[138:139], off
	s_waitcnt vmcnt(8)
	s_waitcnt lgkmcnt(0)
	s_barrier
	s_waitcnt lgkmcnt(0)
	v_mfma_f32_16x16x32_bf16 v[60:63], v[144:147], v[176:179], v[60:63]
	v_mfma_f32_16x16x32_bf16 v[56:59], v[152:155], v[176:179], v[56:59]
	v_mfma_f32_16x16x32_bf16 v[44:47], v[144:147], v[184:187], v[44:47]
	v_mfma_f32_16x16x32_bf16 v[40:43], v[152:155], v[184:187], v[40:43]
	v_mfma_f32_16x16x32_bf16 v[28:31], v[144:147], v[192:195], v[28:31]
	v_mfma_f32_16x16x32_bf16 v[24:27], v[152:155], v[192:195], v[24:27]
	v_mfma_f32_16x16x32_bf16 v[12:15], v[144:147], v[200:203], v[12:15]
	v_mfma_f32_16x16x32_bf16 v[8:11], v[152:155], v[200:203], v[8:11]
	v_mfma_f32_16x16x32_bf16 v[60:63], v[148:151], v[180:183], v[60:63]
	v_mfma_f32_16x16x32_bf16 v[56:59], v[156:159], v[180:183], v[56:59]
	v_mfma_f32_16x16x32_bf16 v[44:47], v[148:151], v[188:191], v[44:47]
	v_mfma_f32_16x16x32_bf16 v[40:43], v[156:159], v[188:191], v[40:43]
	v_mfma_f32_16x16x32_bf16 v[28:31], v[148:151], v[196:199], v[28:31]
	v_mfma_f32_16x16x32_bf16 v[24:27], v[156:159], v[196:199], v[24:27]
	v_mfma_f32_16x16x32_bf16 v[12:15], v[148:151], v[204:207], v[12:15]
	v_mfma_f32_16x16x32_bf16 v[8:11], v[156:159], v[204:207], v[8:11]
	v_mfma_f32_16x16x32_bf16 v[52:55], v[160:163], v[176:179], v[52:55]
	v_mfma_f32_16x16x32_bf16 v[48:51], v[168:171], v[176:179], v[48:51]
	v_mfma_f32_16x16x32_bf16 v[36:39], v[160:163], v[184:187], v[36:39]
	v_mfma_f32_16x16x32_bf16 v[32:35], v[168:171], v[184:187], v[32:35]
	v_mfma_f32_16x16x32_bf16 v[20:23], v[160:163], v[192:195], v[20:23]
	v_mfma_f32_16x16x32_bf16 v[16:19], v[168:171], v[192:195], v[16:19]
	v_mfma_f32_16x16x32_bf16 v[4:7], v[160:163], v[200:203], v[4:7]
	v_mfma_f32_16x16x32_bf16 v[0:3], v[168:171], v[200:203], v[0:3]
	v_mfma_f32_16x16x32_bf16 v[52:55], v[164:167], v[180:183], v[52:55]
	v_mfma_f32_16x16x32_bf16 v[48:51], v[172:175], v[180:183], v[48:51]
	v_mfma_f32_16x16x32_bf16 v[36:39], v[164:167], v[188:191], v[36:39]
	v_mfma_f32_16x16x32_bf16 v[32:35], v[172:175], v[188:191], v[32:35]
	v_mfma_f32_16x16x32_bf16 v[20:23], v[164:167], v[196:199], v[20:23]
	v_mfma_f32_16x16x32_bf16 v[16:19], v[172:175], v[196:199], v[16:19]
	v_mfma_f32_16x16x32_bf16 v[4:7], v[164:167], v[204:207], v[4:7]
	v_mfma_f32_16x16x32_bf16 v[0:3], v[172:175], v[204:207], v[0:3]
	s_barrier
	s_add_i32 s53, s53, 2
	s_add_u32 s20, s20, 0x100
	s_addc_u32 s21, s21, 0
	s_add_u32 s43, s43, 0x100
	s_addc_u32 s45, s45, 0
	s_cmp_gt_u32 s53, 13
	s_cbranch_scc0 .LBB0_135
	s_and_b64 vcc, exec, s[6:7]
	s_cbranch_vccz .LBB0_138
	s_barrier

; #define PG8_STAGE(bufoff, gbase, voff) do { _Pragma("unroll") for (int _i = 0; _i < 2; ++_i) \
;         __builtin_amdgcn_global_load_lds((const unsigned*)((const char*)(gbase) + (voff)[_i]), (PG8_LAS unsigned*)(lds + (bufoff) + ldsw + _i * 8192), 16, 0, 0); } while (0)
; #define PG8_WAIT_V(n) asm volatile("s_waitcnt vmcnt(" #n ")" ::: "memory")
; #define PG8_BAR __builtin_amdgcn_s_barrier()
; template <class Epi, class Sched, bool ALIGN_EPI = false, bool SP2 = false>
; __device__ __forceinline__ void gemm_phase(PG8_LAS unsigned char* lds, const Gemm g, const Sched& S, const Epi& E) {
;     ...
;     for (int i = 0; i < 2; ++i) { int R, C; stage_rc(tid * 16 + i * 8192, R, C); const int Rb = Epi::PERM ? ((R & ~31) + perm32(R & 31)) : R;
;         voffA[i] = (unsigned)(R * g.lda + C) * 2u; voffB[i] = (unsigned)(Rb * g.ldb + C) * 2u; }
;     const size_t kstep = (size_t)(BK * 2);
;     const size_t hstepA = (size_t)HALF * g.lda * 2, hstepB = (size_t)HALF * g.ldb * 2;
;     const size_t tstepA = 2 * hstepA, tstepB = 2 * hstepB;
;     const unsigned ldsw = (unsigned)wid * 1024u;
;     const int aoff = lds_byte(wr * 64 + fr, fq * 8), boff = lds_byte(wc * 32 + fr, fq * 8);
;     ...
;         PG8_WAIT_V(2); PG8_BAR;
;         PG8_STAGE(PG8_SB(1, 0), cB + kstep, voffB); PG8_STAGE(PG8_SA(1, 0), cA + kstep, voffA); PG8_STAGE(PG8_SB(1, 1), cB + hstepB + kstep, voffB);
;         PG8_WAIT_V(6); PG8_BAR;
.LBB0_201:
	v_readlane_b32 s40, v254, 60
	v_bfe_u32 v17, v16, 4, 2
	s_and_b64 s[8:9], s[8:9], exec
	v_readlane_b32 s41, v254, 61
	v_and_b32_e32 v18, 15, v16
	v_lshlrev_b32_e32 v19, 4, v17
	v_lshlrev_b32_e32 v16, 2, v16
	s_cselect_b32 s9, s41, s69
	s_cselect_b32 s8, s40, s68
	v_lshl_or_b32 v140, s5, 6, v18
	v_lshl_or_b32 v18, v18, 6, v19
	s_lshl_b32 s5, s5, 13
	v_and_b32_e32 v16, 32, v16
	v_bitop3_b32 v19, v18, s5, v16 bitop3:0xde
	s_lshl_b32 s5, s14, 5
	s_and_b32 s5, s5, 0x60
	s_add_i32 m0, s26, 0x18000
	v_lshl_add_u64 v[6:7], v[6:7], 0, s[10:11]
	s_lshl_b32 s14, s5, 7
	s_waitcnt vmcnt(2)
	s_barrier
	global_load_lds_dwordx4 v[6:7], off
	v_lshl_add_u64 v[4:5], v[4:5], 0, s[10:11]
	s_add_i32 m0, s26, 0x1a000
	s_add_i32 s46, s26, 0x8000
	s_add_i32 s47, s26, 0xa000
	v_bitop3_b32 v141, v18, s14, v16 bitop3:0xde
	global_load_lds_dwordx4 v[4:5], off
	v_lshl_add_u64 v[0:1], v[0:1], 0, s[10:11]
	s_mov_b32 m0, s46
	s_add_u32 s14, s20, 0xb0080
	s_sext_i32_i8 s38, s15
	global_load_lds_dwordx4 v[0:1], off
	v_lshl_add_u64 v[0:1], v[2:3], 0, s[10:11]
	s_mov_b32 m0, s47
	s_addc_u32 s15, s21, 0
	global_load_lds_dwordx4 v[0:1], off
	s_add_i32 m0, s26, 0x1c000
	v_lshl_add_u64 v[0:1], s[14:15], 0, v[208:209]
	global_load_lds_dwordx4 v208, s[14:15]
	v_lshl_add_u64 v[0:1], s[14:15], 0, v[128:129]
	s_add_i32 m0, s26, 0x1e000
	s_movk_i32 s14, 0xb00
	global_load_lds_dwordx4 v[0:1], off
	v_lshrrev_b32_e32 v1, 1, v8
	v_mul_lo_u32 v0, v10, s14
	s_mov_b32 s15, 0xb000
	s_cmpk_lt_u32 s4, 0x100
	v_lshl_or_b32 v142, v17, 2, s5
	v_mad_u64_u32 v[0:1], s[4:5], v1, s15, v[0:1]
	v_or_b32_e32 v0, v0, v9
	v_add_lshl_u32 v0, v0, v11, 1
	v_mov_b32_e32 v1, v209
	s_mov_b64 s[22:23], 0xb0080
	v_lshl_add_u64 v[130:131], v[0:1], 0, s[22:23]
	v_lshrrev_b32_e32 v1, 1, v12
	v_mul_lo_u32 v0, v14, s14
	v_mad_u64_u32 v[0:1], s[4:5], v1, s15, v[0:1]
	s_waitcnt vmcnt(6)
	v_or_b32_e32 v0, v0, v13
	v_readlane_b32 s42, v254, 62
	v_readlane_b32 s43, v254, 63
	v_add_lshl_u32 v0, v0, v15, 1
	v_mov_b32_e32 v1, v209
	s_cselect_b64 s[42:43], -1, 0
	v_lshl_add_u64 v[132:133], v[0:1], 0, s[22:23]
	s_mov_b32 s48, 0
	v_add_u32_e32 v143, 0, v19
	s_barrier
	s_branch .LBB0_204

; #define PG8_STAGE(bufoff, gbase, voff) do { _Pragma("unroll") for (int _i = 0; _i < 2; ++_i) \
;         __builtin_amdgcn_global_load_lds((const unsigned*)((const char*)(gbase) + (voff)[_i]), (PG8_LAS unsigned*)(lds + (bufoff) + ldsw + _i * 8192), 16, 0, 0); } while (0)
; #define PG8_LDA(dst, b, h) do { _Pragma("unroll") for (int m = 0; m < 4; ++m) _Pragma("unroll") for (int k = 0; k < 2; ++k) dst[m][k] = *(const PG8_LAS bf16x8*)(lds + PG8_SA(b, h) + aoff + m * 2048 + k * 1024); } while (0)
; #define PG8_LDB(dst, b, h) do { _Pragma("unroll") for (int n = 0; n < 2; ++n) _Pragma("unroll") for (int k = 0; k < 2; ++k) dst[n][k] = *(const PG8_LAS bf16x8*)(lds + PG8_SB(b, h) + boff + n * 2048 + k * 1024); } while (0)
; #define PG8_MMA(ai, bj, At, Bt) do { __builtin_amdgcn_s_setprio(1); _Pragma("unroll") for (int m = 0; m < 4; ++m) _Pragma("unroll") for (int n = 0; n < 2; ++n) _Pragma("unroll") for (int k = 0; k < 2; ++k) \
;         acc[ai][bj][m][n] = __builtin_amdgcn_mfma_f32_16x16x32_bf16(Bt[n][k], At[m][k], acc[ai][bj][m][n], 0, 0, 0); __builtin_amdgcn_s_setprio(0); } while (0)
; #define PG8_WAIT_V(n) asm volatile("s_waitcnt vmcnt(" #n ")" ::: "memory")
; #define PG8_WAIT_L(n) asm volatile("s_waitcnt lgkmcnt(" #n ")" ::: "memory")
; #define PG8_BAR __builtin_amdgcn_s_barrier()
; #define PG8_SCHED __builtin_amdgcn_sched_barrier(0)
; template <class Epi, class Sched, bool ALIGN_EPI = false, bool SP2 = false>
; __device__ __forceinline__ void gemm_phase(PG8_LAS unsigned char* lds, const Gemm g, const Sched& S, const Epi& E) {
;     ...
;             const bool last = (t == nt - 2);
;             const char* a1 = cA + (size_t)(t + 1) * kstep;
;             const char* a2 = last ? nA : cA + (size_t)(t + 2) * kstep; const char* b2 = last ? nB : cB + (size_t)(t + 2) * kstep;
;             const char* a3 = a2 + kstep; const char* b3 = b2 + kstep;
;             if (last && has_next) S.a_ready(nxt);
;             if constexpr (SP2) {
;             PG8_LDB(B0, 0, 0); PG8_LDB(B1, 0, 1); PG8_SCHED; PG8_LDA(At, 0, 0); PG8_STAGE(PG8_SA(1, 1), a1 + hstepA, voffA);
;             PG8_WAIT_V(8); PG8_WAIT_L(0); PG8_BAR; PG8_MMA(0, 0, At, B0); PG8_MMA(0, 1, At, B1); PG8_BAR; PG8_SCHED;
;             PG8_LDA(At, 0, 1); PG8_STAGE(PG8_SB(0, 0), b2, voffB); PG8_STAGE(PG8_SB(0, 1), b2 + hstepB, voffB); PG8_STAGE(PG8_SA(0, 0), a2, voffA);
.LBB0_215:
	s_add_u32 s20, s0, 0x100
	s_addc_u32 s21, s1, 0
	s_add_i32 s28, 0, 0x10000
	s_cmp_eq_u32 s51, 40
	s_cselect_b32 s25, s5, s21
	s_cselect_b32 s24, s4, s20
	v_add_u32_e32 v138, s28, v141
	s_cselect_b32 s23, s45, s15
	s_cselect_b32 s22, s44, s14
	s_add_i32 s29, 0, 0x14000
	ds_read_b128 v[134:137], v138
	ds_read_b128 v[144:147], v138 offset:1024
	ds_read_b128 v[148:151], v138 offset:2048
	ds_read_b128 v[152:155], v138 offset:3072
	v_add_u32_e32 v138, s29, v141
	ds_read_b128 v[156:159], v138
	ds_read_b128 v[160:163], v138 offset:1024
	ds_read_b128 v[164:167], v138 offset:2048
	ds_read_b128 v[168:171], v138 offset:3072
	v_lshl_add_u64 v[138:139], s[0:1], 0, v[130:131]
	s_add_i32 m0, s26, 0xc000
	ds_read_b128 v[172:175], v143
	ds_read_b128 v[176:179], v143 offset:1024
	ds_read_b128 v[180:183], v143 offset:2048
	ds_read_b128 v[184:187], v143 offset:3072
	ds_read_b128 v[188:191], v143 offset:4096
	ds_read_b128 v[192:195], v143 offset:5120
	ds_read_b128 v[196:199], v143 offset:6144
	ds_read_b128 v[200:203], v143 offset:7168
	global_load_lds_dwordx4 v[138:139], off
	v_lshl_add_u64 v[138:139], s[0:1], 0, v[132:133]
	s_add_i32 m0, s26, 0xe000
	s_nop 0
	global_load_lds_dwordx4 v[138:139], off
	s_waitcnt vmcnt(8)
	s_waitcnt lgkmcnt(0)
	s_barrier
	s_waitcnt lgkmcnt(0)
	v_mfma_f32_16x16x32_bf16 v[124:127], v[134:137], v[172:175], v[124:127]
	v_mfma_f32_16x16x32_bf16 v[120:123], v[148:151], v[172:175], v[120:123]
	v_mfma_f32_16x16x32_bf16 v[116:119], v[134:137], v[180:183], v[116:119]
	v_mfma_f32_16x16x32_bf16 v[112:115], v[148:151], v[180:183], v[112:115]
	v_mfma_f32_16x16x32_bf16 v[108:111], v[134:137], v[188:191], v[108:111]
	v_mfma_f32_16x16x32_bf16 v[100:103], v[148:151], v[188:191], v[100:103]
	v_mfma_f32_16x16x32_bf16 v[92:95], v[134:137], v[196:199], v[92:95]
	v_mfma_f32_16x16x32_bf16 v[80:83], v[148:151], v[196:199], v[80:83]
	v_mfma_f32_16x16x32_bf16 v[124:127], v[144:147], v[176:179], v[124:127]
	v_mfma_f32_16x16x32_bf16 v[120:123], v[152:155], v[176:179], v[120:123]
	v_mfma_f32_16x16x32_bf16 v[116:119], v[144:147], v[184:187], v[116:119]
	v_mfma_f32_16x16x32_bf16 v[112:115], v[152:155], v[184:187], v[112:115]
	v_mfma_f32_16x16x32_bf16 v[108:111], v[144:147], v[192:195], v[108:111]
	v_mfma_f32_16x16x32_bf16 v[100:103], v[152:155], v[192:195], v[100:103]
	v_mfma_f32_16x16x32_bf16 v[92:95], v[144:147], v[200:203], v[92:95]
	v_mfma_f32_16x16x32_bf16 v[80:83], v[152:155], v[200:203], v[80:83]
	v_mfma_f32_16x16x32_bf16 v[104:107], v[156:159], v[172:175], v[104:107]
	v_mfma_f32_16x16x32_bf16 v[96:99], v[164:167], v[172:175], v[96:99]
	v_mfma_f32_16x16x32_bf16 v[88:91], v[156:159], v[180:183], v[88:91]
	v_mfma_f32_16x16x32_bf16 v[84:87], v[164:167], v[180:183], v[84:87]
	v_mfma_f32_16x16x32_bf16 v[76:79], v[156:159], v[188:191], v[76:79]
	v_mfma_f32_16x16x32_bf16 v[72:75], v[164:167], v[188:191], v[72:75]
	v_mfma_f32_16x16x32_bf16 v[68:71], v[156:159], v[196:199], v[68:71]
	v_mfma_f32_16x16x32_bf16 v[64:67], v[164:167], v[196:199], v[64:67]
	v_mfma_f32_16x16x32_bf16 v[104:107], v[160:163], v[176:179], v[104:107]
	v_mfma_f32_16x16x32_bf16 v[96:99], v[168:171], v[176:179], v[96:99]
	v_mfma_f32_16x16x32_bf16 v[88:91], v[160:163], v[184:187], v[88:91]
	v_mfma_f32_16x16x32_bf16 v[84:87], v[168:171], v[184:187], v[84:87]
	v_mfma_f32_16x16x32_bf16 v[76:79], v[160:163], v[192:195], v[76:79]
	v_mfma_f32_16x16x32_bf16 v[72:75], v[168:171], v[192:195], v[72:75]
	v_mfma_f32_16x16x32_bf16 v[68:71], v[160:163], v[200:203], v[68:71]
	v_mfma_f32_16x16x32_bf16 v[64:67], v[168:171], v[200:203], v[64:67]
	s_barrier
	s_add_i32 s0, s28, s19
	v_lshl_add_u64 v[138:139], s[22:23], 0, v[208:209]
	s_mov_b32 m0, s0
	ds_read_b128 v[172:175], v143 offset:16384
	ds_read_b128 v[176:179], v143 offset:17408
	ds_read_b128 v[180:183], v143 offset:18432
	ds_read_b128 v[184:187], v143 offset:19456
	ds_read_b128 v[188:191], v143 offset:20480
	ds_read_b128 v[192:195], v143 offset:21504
	ds_read_b128 v[196:199], v143 offset:22528
	ds_read_b128 v[200:203], v143 offset:23552
	global_load_lds_dwordx4 v208, s[22:23]
	s_add_i32 m0, s0, 0x2000
	s_add_u32 s0, s22, 0xb0000
	v_lshl_add_u64 v[204:205], s[22:23], 0, v[128:129]
	s_addc_u32 s1, s23, 0
	s_add_i32 s28, s29, s19
	global_load_lds_dwordx4 v128, s[22:23]
	s_mov_b32 m0, s28
	v_lshl_add_u64 v[210:211], s[24:25], 0, v[128:129]
	global_load_lds_dwordx4 v208, s[0:1]
	s_add_i32 m0, s28, 0x2000
	s_nop 0
	global_load_lds_dwordx4 v128, s[0:1]
	v_lshl_add_u64 v[206:207], s[24:25], 0, v[208:209]
	s_mov_b32 m0, s26
	s_nop 0
	global_load_lds_dwordx4 v208, s[24:25]
	s_mov_b32 m0, s34
	s_nop 0
	global_load_lds_dwordx4 v128, s[24:25]
	s_waitcnt vmcnt(8)
	s_waitcnt lgkmcnt(0)
	s_barrier
; #define PG8_STAGE(bufoff, gbase, voff) do { _Pragma("unroll") for (int _i = 0; _i < 2; ++_i) \
;         __builtin_amdgcn_global_load_lds((const unsigned*)((const char*)(gbase) + (voff)[_i]), (PG8_LAS unsigned*)(lds + (bufoff) + ldsw + _i * 8192), 16, 0, 0); } while (0)
; #define PG8_LDA(dst, b, h) do { _Pragma("unroll") for (int m = 0; m < 4; ++m) _Pragma("unroll") for (int k = 0; k < 2; ++k) dst[m][k] = *(const PG8_LAS bf16x8*)(lds + PG8_SA(b, h) + aoff + m * 2048 + k * 1024); } while (0)
; #define PG8_LDB(dst, b, h) do { _Pragma("unroll") for (int n = 0; n < 2; ++n) _Pragma("unroll") for (int k = 0; k < 2; ++k) dst[n][k] = *(const PG8_LAS bf16x8*)(lds + PG8_SB(b, h) + boff + n * 2048 + k * 1024); } while (0)
; #define PG8_MMA(ai, bj, At, Bt) do { __builtin_amdgcn_s_setprio(1); _Pragma("unroll") for (int m = 0; m < 4; ++m) _Pragma("unroll") for (int n = 0; n < 2; ++n) _Pragma("unroll") for (int k = 0; k < 2; ++k) \
;         acc[ai][bj][m][n] = __builtin_amdgcn_mfma_f32_16x16x32_bf16(Bt[n][k], At[m][k], acc[ai][bj][m][n], 0, 0, 0); __builtin_amdgcn_s_setprio(0); } while (0)
; #define PG8_WAIT_V(n) asm volatile("s_waitcnt vmcnt(" #n ")" ::: "memory")
; #define PG8_WAIT_L(n) asm volatile("s_waitcnt lgkmcnt(" #n ")" ::: "memory")
; #define PG8_BAR __builtin_amdgcn_s_barrier()
; #define PG8_SCHED __builtin_amdgcn_sched_barrier(0)
; template <class Epi, class Sched, bool ALIGN_EPI = false, bool SP2 = false>
; __device__ __forceinline__ void gemm_phase(PG8_LAS unsigned char* lds, const Gemm g, const Sched& S, const Epi& E) {
;     ...
;             PG8_WAIT_V(8); PG8_WAIT_L(0); PG8_BAR; PG8_MMA(1, 0, At, B0); PG8_MMA(1, 1, At, B1); PG8_BAR; PG8_SCHED;
;             PG8_LDB(B0, 1, 0); PG8_LDB(B1, 1, 1); PG8_SCHED; PG8_LDA(At, 1, 0); PG8_STAGE(PG8_SA(0, 1), a2 + hstepA, voffA);
;             PG8_WAIT_V(8); PG8_WAIT_L(0); PG8_BAR; PG8_MMA(0, 0, At, B0); PG8_MMA(0, 1, At, B1); PG8_BAR; PG8_SCHED;
	s_waitcnt lgkmcnt(0)
	v_mfma_f32_16x16x32_bf16 v[60:63], v[134:137], v[172:175], v[60:63]
	v_mfma_f32_16x16x32_bf16 v[56:59], v[148:151], v[172:175], v[56:59]
	v_mfma_f32_16x16x32_bf16 v[52:55], v[134:137], v[180:183], v[52:55]
	v_mfma_f32_16x16x32_bf16 v[48:51], v[148:151], v[180:183], v[48:51]
	v_mfma_f32_16x16x32_bf16 v[44:47], v[134:137], v[188:191], v[44:47]
	v_mfma_f32_16x16x32_bf16 v[32:35], v[148:151], v[188:191], v[32:35]
	v_mfma_f32_16x16x32_bf16 v[16:19], v[134:137], v[196:199], v[16:19]
	v_mfma_f32_16x16x32_bf16 v[8:11], v[148:151], v[196:199], v[8:11]
	v_mfma_f32_16x16x32_bf16 v[60:63], v[144:147], v[176:179], v[60:63]
	v_mfma_f32_16x16x32_bf16 v[56:59], v[152:155], v[176:179], v[56:59]
	v_mfma_f32_16x16x32_bf16 v[52:55], v[144:147], v[184:187], v[52:55]
	v_mfma_f32_16x16x32_bf16 v[48:51], v[152:155], v[184:187], v[48:51]
	v_mfma_f32_16x16x32_bf16 v[44:47], v[144:147], v[192:195], v[44:47]
	v_mfma_f32_16x16x32_bf16 v[32:35], v[152:155], v[192:195], v[32:35]
	v_mfma_f32_16x16x32_bf16 v[16:19], v[144:147], v[200:203], v[16:19]
	v_mfma_f32_16x16x32_bf16 v[8:11], v[152:155], v[200:203], v[8:11]
	v_mfma_f32_16x16x32_bf16 v[40:43], v[156:159], v[172:175], v[40:43]
	v_mfma_f32_16x16x32_bf16 v[36:39], v[164:167], v[172:175], v[36:39]
	v_mfma_f32_16x16x32_bf16 v[28:31], v[156:159], v[180:183], v[28:31]
	v_mfma_f32_16x16x32_bf16 v[24:27], v[164:167], v[180:183], v[24:27]
	v_mfma_f32_16x16x32_bf16 v[20:23], v[156:159], v[188:191], v[20:23]
	v_mfma_f32_16x16x32_bf16 v[12:15], v[164:167], v[188:191], v[12:15]
	v_mfma_f32_16x16x32_bf16 v[4:7], v[156:159], v[196:199], v[4:7]
	v_mfma_f32_16x16x32_bf16 v[0:3], v[164:167], v[196:199], v[0:3]
	v_mfma_f32_16x16x32_bf16 v[40:43], v[160:163], v[176:179], v[40:43]
	v_mfma_f32_16x16x32_bf16 v[36:39], v[168:171], v[176:179], v[36:39]
	v_mfma_f32_16x16x32_bf16 v[28:31], v[160:163], v[184:187], v[28:31]
	v_mfma_f32_16x16x32_bf16 v[24:27], v[168:171], v[184:187], v[24:27]
	v_mfma_f32_16x16x32_bf16 v[20:23], v[160:163], v[192:195], v[20:23]
	v_mfma_f32_16x16x32_bf16 v[12:15], v[168:171], v[192:195], v[12:15]
	v_mfma_f32_16x16x32_bf16 v[4:7], v[160:163], v[200:203], v[4:7]
	v_mfma_f32_16x16x32_bf16 v[0:3], v[168:171], v[200:203], v[0:3]
	s_barrier
	s_add_i32 s28, 0, 0x18000
	s_add_i32 s29, 0, 0x1c000
	v_add_u32_e32 v152, s28, v141
	v_add_u32_e32 v168, s29, v141
	ds_read_b128 v[134:137], v152
	ds_read_b128 v[144:147], v152 offset:1024
	ds_read_b128 v[148:151], v152 offset:2048
	ds_read_b128 v[152:155], v152 offset:3072
	ds_read_b128 v[156:159], v168
	ds_read_b128 v[160:163], v168 offset:1024
	ds_read_b128 v[164:167], v168 offset:2048
	ds_read_b128 v[168:171], v168 offset:3072
	s_add_u32 s0, s24, 0xb0000
	s_addc_u32 s1, s25, 0
	s_mov_b32 m0, s35
	ds_read_b128 v[172:175], v143 offset:32768
	ds_read_b128 v[176:179], v143 offset:33792
	ds_read_b128 v[180:183], v143 offset:34816
	ds_read_b128 v[184:187], v143 offset:35840
	ds_read_b128 v[188:191], v143 offset:36864
	ds_read_b128 v[192:195], v143 offset:37888
	ds_read_b128 v[196:199], v143 offset:38912
	ds_read_b128 v[200:203], v143 offset:39936
	global_load_lds_dwordx4 v208, s[0:1]
	s_mov_b32 m0, s39
	s_nop 0
	global_load_lds_dwordx4 v128, s[0:1]
	s_waitcnt vmcnt(8)
	s_waitcnt lgkmcnt(0)
	s_barrier
	s_waitcnt lgkmcnt(0)
	v_mfma_f32_16x16x32_bf16 v[124:127], v[134:137], v[172:175], v[124:127]
	v_mfma_f32_16x16x32_bf16 v[120:123], v[148:151], v[172:175], v[120:123]
	v_mfma_f32_16x16x32_bf16 v[116:119], v[134:137], v[180:183], v[116:119]
	v_mfma_f32_16x16x32_bf16 v[112:115], v[148:151], v[180:183], v[112:115]
	v_mfma_f32_16x16x32_bf16 v[108:111], v[134:137], v[188:191], v[108:111]
	v_mfma_f32_16x16x32_bf16 v[100:103], v[148:151], v[188:191], v[100:103]
	v_mfma_f32_16x16x32_bf16 v[92:95], v[134:137], v[196:199], v[92:95]
	v_mfma_f32_16x16x32_bf16 v[80:83], v[148:151], v[196:199], v[80:83]
	v_mfma_f32_16x16x32_bf16 v[124:127], v[144:147], v[176:179], v[124:127]
	v_mfma_f32_16x16x32_bf16 v[120:123], v[152:155], v[176:179], v[120:123]
	v_mfma_f32_16x16x32_bf16 v[116:119], v[144:147], v[184:187], v[116:119]
	v_mfma_f32_16x16x32_bf16 v[112:115], v[152:155], v[184:187], v[112:115]
	v_mfma_f32_16x16x32_bf16 v[108:111], v[144:147], v[192:195], v[108:111]
	v_mfma_f32_16x16x32_bf16 v[100:103], v[152:155], v[192:195], v[100:103]
	v_mfma_f32_16x16x32_bf16 v[92:95], v[144:147], v[200:203], v[92:95]
	v_mfma_f32_16x16x32_bf16 v[80:83], v[152:155], v[200:203], v[80:83]
	v_mfma_f32_16x16x32_bf16 v[104:107], v[156:159], v[172:175], v[104:107]
	v_mfma_f32_16x16x32_bf16 v[96:99], v[164:167], v[172:175], v[96:99]
	v_mfma_f32_16x16x32_bf16 v[88:91], v[156:159], v[180:183], v[88:91]
	v_mfma_f32_16x16x32_bf16 v[84:87], v[164:167], v[180:183], v[84:87]
	v_mfma_f32_16x16x32_bf16 v[76:79], v[156:159], v[188:191], v[76:79]
	v_mfma_f32_16x16x32_bf16 v[72:75], v[164:167], v[188:191], v[72:75]
	v_mfma_f32_16x16x32_bf16 v[68:71], v[156:159], v[196:199], v[68:71]
	v_mfma_f32_16x16x32_bf16 v[64:67], v[164:167], v[196:199], v[64:67]
	v_mfma_f32_16x16x32_bf16 v[104:107], v[160:163], v[176:179], v[104:107]
	v_mfma_f32_16x16x32_bf16 v[96:99], v[168:171], v[176:179], v[96:99]
	v_mfma_f32_16x16x32_bf16 v[88:91], v[160:163], v[184:187], v[88:91]
	v_mfma_f32_16x16x32_bf16 v[84:87], v[168:171], v[184:187], v[84:87]
	v_mfma_f32_16x16x32_bf16 v[76:79], v[160:163], v[192:195], v[76:79]
	v_mfma_f32_16x16x32_bf16 v[72:75], v[168:171], v[192:195], v[72:75]
	v_mfma_f32_16x16x32_bf16 v[68:71], v[160:163], v[200:203], v[68:71]
	v_mfma_f32_16x16x32_bf16 v[64:67], v[168:171], v[200:203], v[64:67]
	s_barrier
; #define PG8_STAGE(bufoff, gbase, voff) do { _Pragma("unroll") for (int _i = 0; _i < 2; ++_i) \
;         __builtin_amdgcn_global_load_lds((const unsigned*)((const char*)(gbase) + (voff)[_i]), (PG8_LAS unsigned*)(lds + (bufoff) + ldsw + _i * 8192), 16, 0, 0); } while (0)
; #define PG8_LDA(dst, b, h) do { _Pragma("unroll") for (int m = 0; m < 4; ++m) _Pragma("unroll") for (int k = 0; k < 2; ++k) dst[m][k] = *(const PG8_LAS bf16x8*)(lds + PG8_SA(b, h) + aoff + m * 2048 + k * 1024); } while (0)
; #define PG8_MMA(ai, bj, At, Bt) do { __builtin_amdgcn_s_setprio(1); _Pragma("unroll") for (int m = 0; m < 4; ++m) _Pragma("unroll") for (int n = 0; n < 2; ++n) _Pragma("unroll") for (int k = 0; k < 2; ++k) \
;         acc[ai][bj][m][n] = __builtin_amdgcn_mfma_f32_16x16x32_bf16(Bt[n][k], At[m][k], acc[ai][bj][m][n], 0, 0, 0); __builtin_amdgcn_s_setprio(0); } while (0)
; #define PG8_WAIT_V(n) asm volatile("s_waitcnt vmcnt(" #n ")" ::: "memory")
; #define PG8_WAIT_L(n) asm volatile("s_waitcnt lgkmcnt(" #n ")" ::: "memory")
; #define PG8_BAR __builtin_amdgcn_s_barrier()
; #define PG8_SCHED __builtin_amdgcn_sched_barrier(0)
; template <class Epi, class Sched, bool ALIGN_EPI = false, bool SP2 = false>
; __device__ __forceinline__ void gemm_phase(PG8_LAS unsigned char* lds, const Gemm g, const Sched& S, const Epi& E) {
;     ...
;             PG8_LDA(At, 1, 1); PG8_STAGE(PG8_SB(1, 0), b3, voffB); PG8_STAGE(PG8_SB(1, 1), b3 + hstepB, voffB); PG8_STAGE(PG8_SA(1, 0), a3, voffA);
;             PG8_WAIT_V(8); PG8_WAIT_L(0); PG8_BAR; PG8_MMA(1, 0, At, B0); PG8_MMA(1, 1, At, B1); PG8_BAR; PG8_SCHED;
;     ...
;         }
;         if constexpr (ALIGN_EPI) { if (wr == 0) PG8_BAR; }
	s_add_i32 s0, s28, s19
	v_lshl_add_u64 v[138:139], v[138:139], 0, s[10:11]
	s_mov_b32 m0, s0
	ds_read_b128 v[172:175], v143 offset:49152
	ds_read_b128 v[176:179], v143 offset:50176
	ds_read_b128 v[180:183], v143 offset:51200
	ds_read_b128 v[184:187], v143 offset:52224
	ds_read_b128 v[188:191], v143 offset:53248
	ds_read_b128 v[192:195], v143 offset:54272
	ds_read_b128 v[196:199], v143 offset:55296
	ds_read_b128 v[200:203], v143 offset:56320
	global_load_lds_dwordx4 v[138:139], off
	s_add_i32 m0, s0, 0x2000
	s_add_u32 s0, s22, 0xb0080
	v_lshl_add_u64 v[138:139], v[204:205], 0, s[10:11]
	s_addc_u32 s1, s23, 0
	s_add_i32 s22, s29, s19
	global_load_lds_dwordx4 v[138:139], off
	s_mov_b32 m0, s22
	s_nop 0
	global_load_lds_dwordx4 v208, s[0:1]
	s_add_i32 m0, s22, 0x2000
	s_nop 0
	global_load_lds_dwordx4 v128, s[0:1]
	v_lshl_add_u64 v[138:139], v[206:207], 0, s[10:11]
	s_mov_b32 m0, s46
	s_nop 0
	global_load_lds_dwordx4 v[138:139], off
	v_lshl_add_u64 v[138:139], v[210:211], 0, s[10:11]
	s_mov_b32 m0, s47
	s_nop 0
	global_load_lds_dwordx4 v[138:139], off
	s_waitcnt vmcnt(8)
	s_waitcnt lgkmcnt(0)
	s_barrier
	s_waitcnt lgkmcnt(0)
	v_mfma_f32_16x16x32_bf16 v[60:63], v[134:137], v[172:175], v[60:63]
	v_mfma_f32_16x16x32_bf16 v[56:59], v[148:151], v[172:175], v[56:59]
	v_mfma_f32_16x16x32_bf16 v[52:55], v[134:137], v[180:183], v[52:55]
	v_mfma_f32_16x16x32_bf16 v[48:51], v[148:151], v[180:183], v[48:51]
	v_mfma_f32_16x16x32_bf16 v[44:47], v[134:137], v[188:191], v[44:47]
	v_mfma_f32_16x16x32_bf16 v[32:35], v[148:151], v[188:191], v[32:35]
	v_mfma_f32_16x16x32_bf16 v[16:19], v[134:137], v[196:199], v[16:19]
	v_mfma_f32_16x16x32_bf16 v[8:11], v[148:151], v[196:199], v[8:11]
	v_mfma_f32_16x16x32_bf16 v[60:63], v[144:147], v[176:179], v[60:63]
	v_mfma_f32_16x16x32_bf16 v[56:59], v[152:155], v[176:179], v[56:59]
	v_mfma_f32_16x16x32_bf16 v[52:55], v[144:147], v[184:187], v[52:55]
	v_mfma_f32_16x16x32_bf16 v[48:51], v[152:155], v[184:187], v[48:51]
	v_mfma_f32_16x16x32_bf16 v[44:47], v[144:147], v[192:195], v[44:47]
	v_mfma_f32_16x16x32_bf16 v[32:35], v[152:155], v[192:195], v[32:35]
	v_mfma_f32_16x16x32_bf16 v[16:19], v[144:147], v[200:203], v[16:19]
	v_mfma_f32_16x16x32_bf16 v[8:11], v[152:155], v[200:203], v[8:11]
	v_mfma_f32_16x16x32_bf16 v[40:43], v[156:159], v[172:175], v[40:43]
	v_mfma_f32_16x16x32_bf16 v[36:39], v[164:167], v[172:175], v[36:39]
	v_mfma_f32_16x16x32_bf16 v[28:31], v[156:159], v[180:183], v[28:31]
	v_mfma_f32_16x16x32_bf16 v[24:27], v[164:167], v[180:183], v[24:27]
	v_mfma_f32_16x16x32_bf16 v[20:23], v[156:159], v[188:191], v[20:23]
	v_mfma_f32_16x16x32_bf16 v[12:15], v[164:167], v[188:191], v[12:15]
	v_mfma_f32_16x16x32_bf16 v[4:7], v[156:159], v[196:199], v[4:7]
	v_mfma_f32_16x16x32_bf16 v[0:3], v[164:167], v[196:199], v[0:3]
	v_mfma_f32_16x16x32_bf16 v[40:43], v[160:163], v[176:179], v[40:43]
	v_mfma_f32_16x16x32_bf16 v[36:39], v[168:171], v[176:179], v[36:39]
	v_mfma_f32_16x16x32_bf16 v[28:31], v[160:163], v[184:187], v[28:31]
	v_mfma_f32_16x16x32_bf16 v[24:27], v[168:171], v[184:187], v[24:27]
	v_mfma_f32_16x16x32_bf16 v[20:23], v[160:163], v[192:195], v[20:23]
	v_mfma_f32_16x16x32_bf16 v[12:15], v[168:171], v[192:195], v[12:15]
	v_mfma_f32_16x16x32_bf16 v[4:7], v[160:163], v[200:203], v[4:7]
	v_mfma_f32_16x16x32_bf16 v[0:3], v[168:171], v[200:203], v[0:3]
	s_barrier
	s_add_i32 s51, s51, 2
	s_add_u32 s14, s14, 0x100
	s_addc_u32 s15, s15, 0
	s_cmp_gt_u32 s51, 41
	s_mov_b64 s[0:1], s[20:21]
	s_cbranch_scc0 .LBB0_215
	s_and_b64 vcc, exec, s[42:43]
	s_cbranch_vccz .LBB0_218
	s_barrier

; #define PG8_STAGE(bufoff, gbase, voff) do { _Pragma("unroll") for (int _i = 0; _i < 2; ++_i) \
;         __builtin_amdgcn_global_load_lds((const unsigned*)((const char*)(gbase) + (voff)[_i]), (PG8_LAS unsigned*)(lds + (bufoff) + ldsw + _i * 8192), 16, 0, 0); } while (0)
; #define PG8_WAIT_V(n) asm volatile("s_waitcnt vmcnt(" #n ")" ::: "memory")
; #define PG8_BAR __builtin_amdgcn_s_barrier()
; template <class Epi, class Sched, bool ALIGN_EPI = false, bool SP2 = false>
; __device__ __forceinline__ void gemm_phase(PG8_LAS unsigned char* lds, const Gemm g, const Sched& S, const Epi& E) {
;     ...
;     for (int i = 0; i < 2; ++i) { int R, C; stage_rc(tid * 16 + i * 8192, R, C); const int Rb = Epi::PERM ? ((R & ~31) + perm32(R & 31)) : R;
;         voffA[i] = (unsigned)(R * g.lda + C) * 2u; voffB[i] = (unsigned)(Rb * g.ldb + C) * 2u; }
;     const size_t kstep = (size_t)(BK * 2);
;     const size_t hstepA = (size_t)HALF * g.lda * 2, hstepB = (size_t)HALF * g.ldb * 2;
;     const size_t tstepA = 2 * hstepA, tstepB = 2 * hstepB;
;     const unsigned ldsw = (unsigned)wid * 1024u;
;     const int aoff = lds_byte(wr * 64 + fr, fq * 8), boff = lds_byte(wc * 32 + fr, fq * 8);
;     ...
;         PG8_STAGE(PG8_SB(0, 0), cB, voffB); PG8_STAGE(PG8_SB(0, 1), cB + hstepB, voffB); PG8_STAGE(PG8_SA(0, 0), cA, voffA); PG8_STAGE(PG8_SA(0, 1), cA + hstepA, voffA);
;         if (wr == 1) PG8_BAR;
;         PG8_WAIT_V(2); PG8_BAR;
;         PG8_STAGE(PG8_SB(1, 0), cB + kstep, voffB); PG8_STAGE(PG8_SA(1, 0), cA + kstep, voffA); PG8_STAGE(PG8_SB(1, 1), cB + hstepB + kstep, voffB);
;         PG8_WAIT_V(6); PG8_BAR;
.LBB0_332:
	v_lshrrev_b32_e32 v16, 1, v14
	v_and_b32_e32 v16, 24, v16
	v_and_b32_e32 v15, 15, v14
	v_lshlrev_b32_e32 v17, 1, v16
	v_lshlrev_b32_e32 v14, 2, v14
	s_sext_i32_i8 s38, s4
	v_lshl_or_b32 v139, s9, 6, v15
	v_lshl_or_b32 v15, v15, 6, v17
	s_lshl_b32 s4, s9, 13
	v_and_b32_e32 v14, 32, v14
	v_bitop3_b32 v17, v15, s4, v14 bitop3:0xde
	s_lshl_b32 s4, s8, 5
	s_and_b32 s4, s4, 0x60
	s_add_i32 m0, s26, 0x18000
	v_lshl_add_u64 v[6:7], v[6:7], 0, s[10:11]
	s_lshl_b32 s8, s4, 7
	s_waitcnt vmcnt(2)
	s_barrier
	global_load_lds_dwordx4 v[6:7], off
	v_lshl_add_u64 v[4:5], v[4:5], 0, s[10:11]
	s_add_i32 m0, s26, 0x1a000
	s_add_i32 s12, s26, 0x8000
	s_add_i32 s43, s26, 0xa000
	v_bitop3_b32 v142, v15, s8, v14 bitop3:0xde
	global_load_lds_dwordx4 v[4:5], off
	v_lshl_add_u64 v[0:1], v[0:1], 0, s[10:11]
	s_mov_b32 m0, s12
	s_add_u32 s8, s24, 0x40080
	global_load_lds_dwordx4 v[0:1], off
	v_lshl_add_u64 v[0:1], v[2:3], 0, s[10:11]
	s_mov_b32 m0, s43
	s_addc_u32 s9, s25, 0
	global_load_lds_dwordx4 v[0:1], off
	s_add_i32 m0, s26, 0x1c000
	v_lshl_add_u64 v[0:1], s[8:9], 0, v[208:209]
	global_load_lds_dwordx4 v208, s[8:9]
	v_lshl_add_u64 v[0:1], s[8:9], 0, v[128:129]
	s_add_i32 m0, s26, 0x1e000
	s_cmpk_lt_u32 s5, 0x100
	global_load_lds_dwordx4 v128, s[8:9]
	v_lshlrev_b32_e32 v0, 14, v12
	v_and_b32_e32 v0, 0xffff8000, v0
	v_lshl_add_u32 v0, v11, 11, v0
	v_and_b32_e32 v1, 1, v12
	v_lshl_or_b32 v0, v1, 6, v0
	v_lshl_add_u32 v134, v13, 1, v0
	v_lshlrev_b32_e32 v0, 14, v8
	v_and_b32_e32 v0, 0xffff8000, v0
	s_waitcnt vmcnt(6)
	v_lshl_add_u32 v0, v9, 11, v0
	v_and_b32_e32 v1, 1, v8
	v_lshl_or_b32 v0, v1, 6, v0
	s_cselect_b64 s[8:9], -1, 0
	v_or_b32_e32 v143, s4, v16
	v_mov_b32_e32 v135, v209
	v_lshl_add_u32 v136, v10, 1, v0
	v_mov_b32_e32 v137, v209
	s_mov_b32 s48, 0
	v_add_u32_e32 v144, 0, v17
	s_barrier
	s_branch .LBB0_335

; #define PG8_STAGE(bufoff, gbase, voff) do { _Pragma("unroll") for (int _i = 0; _i < 2; ++_i) \
;         __builtin_amdgcn_global_load_lds((const unsigned*)((const char*)(gbase) + (voff)[_i]), (PG8_LAS unsigned*)(lds + (bufoff) + ldsw + _i * 8192), 16, 0, 0); } while (0)
; #define PG8_LDA(dst, b, h) do { _Pragma("unroll") for (int m = 0; m < 4; ++m) _Pragma("unroll") for (int k = 0; k < 2; ++k) dst[m][k] = *(const PG8_LAS bf16x8*)(lds + PG8_SA(b, h) + aoff + m * 2048 + k * 1024); } while (0)
; #define PG8_LDB(dst, b, h) do { _Pragma("unroll") for (int n = 0; n < 2; ++n) _Pragma("unroll") for (int k = 0; k < 2; ++k) dst[n][k] = *(const PG8_LAS bf16x8*)(lds + PG8_SB(b, h) + boff + n * 2048 + k * 1024); } while (0)
; #define PG8_MMA(ai, bj, At, Bt) do { __builtin_amdgcn_s_setprio(1); _Pragma("unroll") for (int m = 0; m < 4; ++m) _Pragma("unroll") for (int n = 0; n < 2; ++n) _Pragma("unroll") for (int k = 0; k < 2; ++k) \
;         acc[ai][bj][m][n] = __builtin_amdgcn_mfma_f32_16x16x32_bf16(Bt[n][k], At[m][k], acc[ai][bj][m][n], 0, 0, 0); __builtin_amdgcn_s_setprio(0); } while (0)
; #define PG8_WAIT_V(n) asm volatile("s_waitcnt vmcnt(" #n ")" ::: "memory")
; #define PG8_WAIT_L(n) asm volatile("s_waitcnt lgkmcnt(" #n ")" ::: "memory")
; #define PG8_BAR __builtin_amdgcn_s_barrier()
; #define PG8_SCHED __builtin_amdgcn_sched_barrier(0)
; template <class Epi, class Sched, bool ALIGN_EPI = false, bool SP2 = false>
; __device__ __forceinline__ void gemm_phase(PG8_LAS unsigned char* lds, const Gemm g, const Sched& S, const Epi& E) {
;     ...
;             PG8_LDB(B0, 0, 0); PG8_LDB(B1, 0, 1); PG8_SCHED; PG8_LDA(At, 0, 0); PG8_STAGE(PG8_SA(1, 1), a1 + hstepA, voffA);
;             PG8_WAIT_V(8); PG8_WAIT_L(0); PG8_BAR; PG8_MMA(0, 0, At, B0); PG8_MMA(0, 1, At, B1); PG8_BAR; PG8_SCHED;
;             PG8_LDA(At, 0, 1); PG8_STAGE(PG8_SB(0, 0), b2, voffB); PG8_STAGE(PG8_SB(0, 1), b2 + hstepB, voffB); PG8_STAGE(PG8_SA(0, 0), a2, voffA);
;             PG8_WAIT_V(8); PG8_WAIT_L(0); PG8_BAR; PG8_MMA(1, 0, At, B0); PG8_MMA(1, 1, At, B1); PG8_BAR; PG8_SCHED;
.LBB0_338:
	s_add_u32 s22, s0, 0xfffc0080
	s_addc_u32 s23, s1, -1
	s_add_i32 s28, 0, 0x10000
	s_cmp_eq_u32 s51, 12
	s_cselect_b32 s25, s14, s23
	s_cselect_b32 s24, s15, s22
	v_add_u32_e32 v138, s28, v142
	s_cselect_b32 s23, s21, s50
	s_cselect_b32 s22, s41, s49
	s_add_i32 s29, 0, 0x14000
	ds_read_b128 v[146:149], v138
	ds_read_b128 v[150:153], v138 offset:1024
	ds_read_b128 v[154:157], v138 offset:2048
	ds_read_b128 v[158:161], v138 offset:3072
	v_add_u32_e32 v138, s29, v142
	ds_read_b128 v[162:165], v138
	ds_read_b128 v[166:169], v138 offset:1024
	ds_read_b128 v[170:173], v138 offset:2048
	ds_read_b128 v[174:177], v138 offset:3072
	s_add_i32 m0, s26, 0xc000
	ds_read_b128 v[178:181], v144
	ds_read_b128 v[182:185], v144 offset:1024
	ds_read_b128 v[186:189], v144 offset:2048
	ds_read_b128 v[190:193], v144 offset:3072
	ds_read_b128 v[194:197], v144 offset:4096
	ds_read_b128 v[198:201], v144 offset:5120
	ds_read_b128 v[202:205], v144 offset:6144
	ds_read_b128 v[210:213], v144 offset:7168
	global_load_lds_dwordx4 v134, s[0:1]
	s_add_i32 m0, s26, 0xe000
	s_nop 0
	global_load_lds_dwordx4 v136, s[0:1]
	s_waitcnt vmcnt(8)
	s_waitcnt lgkmcnt(0)
	s_barrier
	s_waitcnt lgkmcnt(0)
	v_mfma_f32_16x16x32_bf16 v[124:127], v[146:149], v[178:181], v[124:127]
	v_mfma_f32_16x16x32_bf16 v[120:123], v[154:157], v[178:181], v[120:123]
	v_mfma_f32_16x16x32_bf16 v[116:119], v[146:149], v[186:189], v[116:119]
	v_mfma_f32_16x16x32_bf16 v[108:111], v[154:157], v[186:189], v[108:111]
	v_mfma_f32_16x16x32_bf16 v[100:103], v[146:149], v[194:197], v[100:103]
	v_mfma_f32_16x16x32_bf16 v[92:95], v[154:157], v[194:197], v[92:95]
	v_mfma_f32_16x16x32_bf16 v[84:87], v[146:149], v[202:205], v[84:87]
	v_mfma_f32_16x16x32_bf16 v[76:79], v[154:157], v[202:205], v[76:79]
	v_mfma_f32_16x16x32_bf16 v[124:127], v[150:153], v[182:185], v[124:127]
	v_mfma_f32_16x16x32_bf16 v[120:123], v[158:161], v[182:185], v[120:123]
	v_mfma_f32_16x16x32_bf16 v[116:119], v[150:153], v[190:193], v[116:119]
	v_mfma_f32_16x16x32_bf16 v[108:111], v[158:161], v[190:193], v[108:111]
	v_mfma_f32_16x16x32_bf16 v[100:103], v[150:153], v[198:201], v[100:103]
	v_mfma_f32_16x16x32_bf16 v[92:95], v[158:161], v[198:201], v[92:95]
	v_mfma_f32_16x16x32_bf16 v[84:87], v[150:153], v[210:213], v[84:87]
	v_mfma_f32_16x16x32_bf16 v[76:79], v[158:161], v[210:213], v[76:79]
	v_mfma_f32_16x16x32_bf16 v[112:115], v[162:165], v[178:181], v[112:115]
	v_mfma_f32_16x16x32_bf16 v[104:107], v[170:173], v[178:181], v[104:107]
	v_mfma_f32_16x16x32_bf16 v[96:99], v[162:165], v[186:189], v[96:99]
	v_mfma_f32_16x16x32_bf16 v[88:91], v[170:173], v[186:189], v[88:91]
	v_mfma_f32_16x16x32_bf16 v[80:83], v[162:165], v[194:197], v[80:83]
	v_mfma_f32_16x16x32_bf16 v[72:75], v[170:173], v[194:197], v[72:75]
	v_mfma_f32_16x16x32_bf16 v[68:71], v[162:165], v[202:205], v[68:71]
	v_mfma_f32_16x16x32_bf16 v[64:67], v[170:173], v[202:205], v[64:67]
	v_mfma_f32_16x16x32_bf16 v[112:115], v[166:169], v[182:185], v[112:115]
	v_mfma_f32_16x16x32_bf16 v[104:107], v[174:177], v[182:185], v[104:107]
	v_mfma_f32_16x16x32_bf16 v[96:99], v[166:169], v[190:193], v[96:99]
	v_mfma_f32_16x16x32_bf16 v[88:91], v[174:177], v[190:193], v[88:91]
	v_mfma_f32_16x16x32_bf16 v[80:83], v[166:169], v[198:201], v[80:83]
	v_mfma_f32_16x16x32_bf16 v[72:75], v[174:177], v[198:201], v[72:75]
	v_mfma_f32_16x16x32_bf16 v[68:71], v[166:169], v[210:213], v[68:71]
	v_mfma_f32_16x16x32_bf16 v[64:67], v[174:177], v[210:213], v[64:67]
	s_barrier
	s_add_i32 s28, s28, s18
	v_lshl_add_u64 v[140:141], s[22:23], 0, v[208:209]
	s_mov_b32 m0, s28
	ds_read_b128 v[178:181], v144 offset:16384
	ds_read_b128 v[182:185], v144 offset:17408
	ds_read_b128 v[186:189], v144 offset:18432
	ds_read_b128 v[190:193], v144 offset:19456
	ds_read_b128 v[194:197], v144 offset:20480
	ds_read_b128 v[198:201], v144 offset:21504
	ds_read_b128 v[202:205], v144 offset:22528
	ds_read_b128 v[210:213], v144 offset:23552
	global_load_lds_dwordx4 v208, s[22:23]
	s_add_i32 m0, s28, 0x2000
	s_add_u32 s52, s22, 0x40000
	v_lshl_add_u64 v[206:207], s[22:23], 0, v[128:129]
	s_addc_u32 s53, s23, 0
	s_add_i32 s28, s29, s18
	global_load_lds_dwordx4 v128, s[22:23]
	s_mov_b32 m0, s28
	v_lshl_add_u64 v[224:225], s[24:25], 0, v[130:131]
	global_load_lds_dwordx4 v208, s[52:53]
	s_add_i32 m0, s28, 0x2000
	s_nop 0
	global_load_lds_dwordx4 v128, s[52:53]
	v_lshl_add_u64 v[222:223], s[24:25], 0, v[132:133]
	s_mov_b32 m0, s26
	s_nop 0
	global_load_lds_dwordx4 v132, s[24:25]
	s_mov_b32 m0, s34
	s_nop 0
	global_load_lds_dwordx4 v130, s[24:25]
	s_waitcnt vmcnt(8)
	s_waitcnt lgkmcnt(0)
	s_barrier
; #define PG8_STAGE(bufoff, gbase, voff) do { _Pragma("unroll") for (int _i = 0; _i < 2; ++_i) \
;         __builtin_amdgcn_global_load_lds((const unsigned*)((const char*)(gbase) + (voff)[_i]), (PG8_LAS unsigned*)(lds + (bufoff) + ldsw + _i * 8192), 16, 0, 0); } while (0)
; #define PG8_LDA(dst, b, h) do { _Pragma("unroll") for (int m = 0; m < 4; ++m) _Pragma("unroll") for (int k = 0; k < 2; ++k) dst[m][k] = *(const PG8_LAS bf16x8*)(lds + PG8_SA(b, h) + aoff + m * 2048 + k * 1024); } while (0)
; #define PG8_LDB(dst, b, h) do { _Pragma("unroll") for (int n = 0; n < 2; ++n) _Pragma("unroll") for (int k = 0; k < 2; ++k) dst[n][k] = *(const PG8_LAS bf16x8*)(lds + PG8_SB(b, h) + boff + n * 2048 + k * 1024); } while (0)
; #define PG8_MMA(ai, bj, At, Bt) do { __builtin_amdgcn_s_setprio(1); _Pragma("unroll") for (int m = 0; m < 4; ++m) _Pragma("unroll") for (int n = 0; n < 2; ++n) _Pragma("unroll") for (int k = 0; k < 2; ++k) \
;         acc[ai][bj][m][n] = __builtin_amdgcn_mfma_f32_16x16x32_bf16(Bt[n][k], At[m][k], acc[ai][bj][m][n], 0, 0, 0); __builtin_amdgcn_s_setprio(0); } while (0)
; #define PG8_WAIT_V(n) asm volatile("s_waitcnt vmcnt(" #n ")" ::: "memory")
; #define PG8_WAIT_L(n) asm volatile("s_waitcnt lgkmcnt(" #n ")" ::: "memory")
; #define PG8_BAR __builtin_amdgcn_s_barrier()
; #define PG8_SCHED __builtin_amdgcn_sched_barrier(0)
; template <class Epi, class Sched, bool ALIGN_EPI = false, bool SP2 = false>
; __device__ __forceinline__ void gemm_phase(PG8_LAS unsigned char* lds, const Gemm g, const Sched& S, const Epi& E) {
;     ...
;             PG8_WAIT_V(8); PG8_WAIT_L(0); PG8_BAR; PG8_MMA(1, 0, At, B0); PG8_MMA(1, 1, At, B1); PG8_BAR; PG8_SCHED;
;             PG8_LDB(B0, 1, 0); PG8_LDB(B1, 1, 1); PG8_SCHED; PG8_LDA(At, 1, 0); PG8_STAGE(PG8_SA(0, 1), a2 + hstepA, voffA);
;             PG8_WAIT_V(8); PG8_WAIT_L(0); PG8_BAR; PG8_MMA(0, 0, At, B0); PG8_MMA(0, 1, At, B1); PG8_BAR; PG8_SCHED;
	s_waitcnt lgkmcnt(0)
	v_mfma_f32_16x16x32_bf16 v[60:63], v[146:149], v[178:181], v[60:63]
	v_mfma_f32_16x16x32_bf16 v[56:59], v[154:157], v[178:181], v[56:59]
	v_mfma_f32_16x16x32_bf16 v[52:55], v[146:149], v[186:189], v[52:55]
	v_mfma_f32_16x16x32_bf16 v[44:47], v[154:157], v[186:189], v[44:47]
	v_mfma_f32_16x16x32_bf16 v[36:39], v[146:149], v[194:197], v[36:39]
	v_mfma_f32_16x16x32_bf16 v[28:31], v[154:157], v[194:197], v[28:31]
	v_mfma_f32_16x16x32_bf16 v[20:23], v[146:149], v[202:205], v[20:23]
	v_mfma_f32_16x16x32_bf16 v[12:15], v[154:157], v[202:205], v[12:15]
	v_mfma_f32_16x16x32_bf16 v[60:63], v[150:153], v[182:185], v[60:63]
	v_mfma_f32_16x16x32_bf16 v[56:59], v[158:161], v[182:185], v[56:59]
	v_mfma_f32_16x16x32_bf16 v[52:55], v[150:153], v[190:193], v[52:55]
	v_mfma_f32_16x16x32_bf16 v[44:47], v[158:161], v[190:193], v[44:47]
	v_mfma_f32_16x16x32_bf16 v[36:39], v[150:153], v[198:201], v[36:39]
	v_mfma_f32_16x16x32_bf16 v[28:31], v[158:161], v[198:201], v[28:31]
	v_mfma_f32_16x16x32_bf16 v[20:23], v[150:153], v[210:213], v[20:23]
	v_mfma_f32_16x16x32_bf16 v[12:15], v[158:161], v[210:213], v[12:15]
	v_mfma_f32_16x16x32_bf16 v[48:51], v[162:165], v[178:181], v[48:51]
	v_mfma_f32_16x16x32_bf16 v[40:43], v[170:173], v[178:181], v[40:43]
	v_mfma_f32_16x16x32_bf16 v[32:35], v[162:165], v[186:189], v[32:35]
	v_mfma_f32_16x16x32_bf16 v[24:27], v[170:173], v[186:189], v[24:27]
	v_mfma_f32_16x16x32_bf16 v[16:19], v[162:165], v[194:197], v[16:19]
	v_mfma_f32_16x16x32_bf16 v[8:11], v[170:173], v[194:197], v[8:11]
	v_mfma_f32_16x16x32_bf16 v[4:7], v[162:165], v[202:205], v[4:7]
	v_mfma_f32_16x16x32_bf16 v[0:3], v[170:173], v[202:205], v[0:3]
	v_mfma_f32_16x16x32_bf16 v[48:51], v[166:169], v[182:185], v[48:51]
	v_mfma_f32_16x16x32_bf16 v[40:43], v[174:177], v[182:185], v[40:43]
	v_mfma_f32_16x16x32_bf16 v[32:35], v[166:169], v[190:193], v[32:35]
	v_mfma_f32_16x16x32_bf16 v[24:27], v[174:177], v[190:193], v[24:27]
	v_mfma_f32_16x16x32_bf16 v[16:19], v[166:169], v[198:201], v[16:19]
	v_mfma_f32_16x16x32_bf16 v[8:11], v[174:177], v[198:201], v[8:11]
	v_mfma_f32_16x16x32_bf16 v[4:7], v[166:169], v[210:213], v[4:7]
	v_mfma_f32_16x16x32_bf16 v[0:3], v[174:177], v[210:213], v[0:3]
	s_barrier
	s_add_i32 s28, 0, 0x18000
	v_add_u32_e32 v138, s28, v142
	s_add_i32 s29, 0, 0x1c000
	ds_read_b128 v[146:149], v138
	ds_read_b128 v[150:153], v138 offset:1024
	ds_read_b128 v[154:157], v138 offset:2048
	ds_read_b128 v[158:161], v138 offset:3072
	v_add_u32_e32 v138, s29, v142
	ds_read_b128 v[162:165], v138
	ds_read_b128 v[166:169], v138 offset:1024
	ds_read_b128 v[170:173], v138 offset:2048
	ds_read_b128 v[174:177], v138 offset:3072
	s_add_u32 s24, s24, 0x40000
	s_addc_u32 s25, s25, 0
	s_mov_b32 m0, s35
	ds_read_b128 v[178:181], v144 offset:32768
	ds_read_b128 v[182:185], v144 offset:33792
	ds_read_b128 v[186:189], v144 offset:34816
	ds_read_b128 v[190:193], v144 offset:35840
	ds_read_b128 v[194:197], v144 offset:36864
	ds_read_b128 v[198:201], v144 offset:37888
	ds_read_b128 v[202:205], v144 offset:38912
	ds_read_b128 v[210:213], v144 offset:39936
	global_load_lds_dwordx4 v132, s[24:25]
	v_lshl_add_u64 v[226:227], s[24:25], 0, v[130:131]
	s_mov_b32 m0, s39
	s_nop 0
	global_load_lds_dwordx4 v130, s[24:25]
	s_waitcnt vmcnt(8)
	s_waitcnt lgkmcnt(0)
	s_barrier
	s_waitcnt lgkmcnt(0)
	v_mfma_f32_16x16x32_bf16 v[124:127], v[146:149], v[178:181], v[124:127]
	v_mfma_f32_16x16x32_bf16 v[120:123], v[154:157], v[178:181], v[120:123]
	v_mfma_f32_16x16x32_bf16 v[116:119], v[146:149], v[186:189], v[116:119]
	v_mfma_f32_16x16x32_bf16 v[108:111], v[154:157], v[186:189], v[108:111]
	v_mfma_f32_16x16x32_bf16 v[100:103], v[146:149], v[194:197], v[100:103]
	v_mfma_f32_16x16x32_bf16 v[92:95], v[154:157], v[194:197], v[92:95]
	v_mfma_f32_16x16x32_bf16 v[84:87], v[146:149], v[202:205], v[84:87]
	v_mfma_f32_16x16x32_bf16 v[76:79], v[154:157], v[202:205], v[76:79]
	v_mfma_f32_16x16x32_bf16 v[124:127], v[150:153], v[182:185], v[124:127]
	v_mfma_f32_16x16x32_bf16 v[120:123], v[158:161], v[182:185], v[120:123]
	v_mfma_f32_16x16x32_bf16 v[116:119], v[150:153], v[190:193], v[116:119]
	v_mfma_f32_16x16x32_bf16 v[108:111], v[158:161], v[190:193], v[108:111]
	v_mfma_f32_16x16x32_bf16 v[100:103], v[150:153], v[198:201], v[100:103]
	v_mfma_f32_16x16x32_bf16 v[92:95], v[158:161], v[198:201], v[92:95]
	v_mfma_f32_16x16x32_bf16 v[84:87], v[150:153], v[210:213], v[84:87]
	v_mfma_f32_16x16x32_bf16 v[76:79], v[158:161], v[210:213], v[76:79]
	v_mfma_f32_16x16x32_bf16 v[112:115], v[162:165], v[178:181], v[112:115]
	v_mfma_f32_16x16x32_bf16 v[104:107], v[170:173], v[178:181], v[104:107]
	v_mfma_f32_16x16x32_bf16 v[96:99], v[162:165], v[186:189], v[96:99]
	v_mfma_f32_16x16x32_bf16 v[88:91], v[170:173], v[186:189], v[88:91]
	v_mfma_f32_16x16x32_bf16 v[80:83], v[162:165], v[194:197], v[80:83]
	v_mfma_f32_16x16x32_bf16 v[72:75], v[170:173], v[194:197], v[72:75]
	v_mfma_f32_16x16x32_bf16 v[68:71], v[162:165], v[202:205], v[68:71]
	v_mfma_f32_16x16x32_bf16 v[64:67], v[170:173], v[202:205], v[64:67]
	v_mfma_f32_16x16x32_bf16 v[112:115], v[166:169], v[182:185], v[112:115]
	v_mfma_f32_16x16x32_bf16 v[104:107], v[174:177], v[182:185], v[104:107]
	v_mfma_f32_16x16x32_bf16 v[96:99], v[166:169], v[190:193], v[96:99]
	v_mfma_f32_16x16x32_bf16 v[88:91], v[174:177], v[190:193], v[88:91]
	v_mfma_f32_16x16x32_bf16 v[80:83], v[166:169], v[198:201], v[80:83]
	v_mfma_f32_16x16x32_bf16 v[72:75], v[174:177], v[198:201], v[72:75]
	v_mfma_f32_16x16x32_bf16 v[68:71], v[166:169], v[210:213], v[68:71]
	v_mfma_f32_16x16x32_bf16 v[64:67], v[174:177], v[210:213], v[64:67]
	s_barrier
; #define PG8_STAGE(bufoff, gbase, voff) do { _Pragma("unroll") for (int _i = 0; _i < 2; ++_i) \
;         __builtin_amdgcn_global_load_lds((const unsigned*)((const char*)(gbase) + (voff)[_i]), (PG8_LAS unsigned*)(lds + (bufoff) + ldsw + _i * 8192), 16, 0, 0); } while (0)
; #define PG8_LDA(dst, b, h) do { _Pragma("unroll") for (int m = 0; m < 4; ++m) _Pragma("unroll") for (int k = 0; k < 2; ++k) dst[m][k] = *(const PG8_LAS bf16x8*)(lds + PG8_SA(b, h) + aoff + m * 2048 + k * 1024); } while (0)
; #define PG8_MMA(ai, bj, At, Bt) do { __builtin_amdgcn_s_setprio(1); _Pragma("unroll") for (int m = 0; m < 4; ++m) _Pragma("unroll") for (int n = 0; n < 2; ++n) _Pragma("unroll") for (int k = 0; k < 2; ++k) \
;         acc[ai][bj][m][n] = __builtin_amdgcn_mfma_f32_16x16x32_bf16(Bt[n][k], At[m][k], acc[ai][bj][m][n], 0, 0, 0); __builtin_amdgcn_s_setprio(0); } while (0)
; #define PG8_WAIT_V(n) asm volatile("s_waitcnt vmcnt(" #n ")" ::: "memory")
; #define PG8_WAIT_L(n) asm volatile("s_waitcnt lgkmcnt(" #n ")" ::: "memory")
; #define PG8_BAR __builtin_amdgcn_s_barrier()
; #define PG8_SCHED __builtin_amdgcn_sched_barrier(0)
; template <class Epi, class Sched, bool ALIGN_EPI = false, bool SP2 = false>
; __device__ __forceinline__ void gemm_phase(PG8_LAS unsigned char* lds, const Gemm g, const Sched& S, const Epi& E) {
;     ...
;             PG8_LDA(At, 1, 1); PG8_STAGE(PG8_SB(1, 0), b3, voffB); PG8_STAGE(PG8_SB(1, 1), b3 + hstepB, voffB); PG8_STAGE(PG8_SA(1, 0), a3, voffA);
;             PG8_WAIT_V(8); PG8_WAIT_L(0); PG8_BAR; PG8_MMA(1, 0, At, B0); PG8_MMA(1, 1, At, B1); PG8_BAR; PG8_SCHED;
	s_add_i32 s24, s28, s18
	v_lshl_add_u64 v[140:141], v[140:141], 0, s[10:11]
	s_mov_b32 m0, s24
	ds_read_b128 v[178:181], v144 offset:49152
	ds_read_b128 v[182:185], v144 offset:50176
	ds_read_b128 v[186:189], v144 offset:51200
	ds_read_b128 v[190:193], v144 offset:52224
	ds_read_b128 v[194:197], v144 offset:53248
	ds_read_b128 v[198:201], v144 offset:54272
	ds_read_b128 v[202:205], v144 offset:55296
	ds_read_b128 v[210:213], v144 offset:56320
	global_load_lds_dwordx4 v[140:141], off
	s_add_i32 m0, s24, 0x2000
	s_add_u32 s22, s22, 0x40080
	v_lshl_add_u64 v[140:141], v[206:207], 0, s[10:11]
	s_addc_u32 s23, s23, 0
	s_add_i32 s24, s29, s18
	global_load_lds_dwordx4 v[140:141], off
	s_mov_b32 m0, s24
	s_nop 0
	global_load_lds_dwordx4 v208, s[22:23]
	s_add_i32 m0, s24, 0x2000
	s_nop 0
	global_load_lds_dwordx4 v128, s[22:23]
	v_lshl_add_u64 v[140:141], v[222:223], 0, s[10:11]
	s_mov_b32 m0, s12
	s_nop 0
	global_load_lds_dwordx4 v[140:141], off
	v_lshl_add_u64 v[140:141], v[224:225], 0, s[10:11]
	s_mov_b32 m0, s43
	s_nop 0
	global_load_lds_dwordx4 v[140:141], off
	s_waitcnt vmcnt(8)
	s_waitcnt lgkmcnt(0)
	s_barrier
	s_waitcnt lgkmcnt(0)
	v_mfma_f32_16x16x32_bf16 v[60:63], v[146:149], v[178:181], v[60:63]
	v_mfma_f32_16x16x32_bf16 v[56:59], v[154:157], v[178:181], v[56:59]
	v_mfma_f32_16x16x32_bf16 v[52:55], v[146:149], v[186:189], v[52:55]
	v_mfma_f32_16x16x32_bf16 v[44:47], v[154:157], v[186:189], v[44:47]
	v_mfma_f32_16x16x32_bf16 v[36:39], v[146:149], v[194:197], v[36:39]
	v_mfma_f32_16x16x32_bf16 v[28:31], v[154:157], v[194:197], v[28:31]
	v_mfma_f32_16x16x32_bf16 v[20:23], v[146:149], v[202:205], v[20:23]
	v_mfma_f32_16x16x32_bf16 v[12:15], v[154:157], v[202:205], v[12:15]
	v_mfma_f32_16x16x32_bf16 v[60:63], v[150:153], v[182:185], v[60:63]
	v_mfma_f32_16x16x32_bf16 v[56:59], v[158:161], v[182:185], v[56:59]
	v_mfma_f32_16x16x32_bf16 v[52:55], v[150:153], v[190:193], v[52:55]
	v_mfma_f32_16x16x32_bf16 v[44:47], v[158:161], v[190:193], v[44:47]
	v_mfma_f32_16x16x32_bf16 v[36:39], v[150:153], v[198:201], v[36:39]
	v_mfma_f32_16x16x32_bf16 v[28:31], v[158:161], v[198:201], v[28:31]
	v_mfma_f32_16x16x32_bf16 v[20:23], v[150:153], v[210:213], v[20:23]
	v_mfma_f32_16x16x32_bf16 v[12:15], v[158:161], v[210:213], v[12:15]
	v_mfma_f32_16x16x32_bf16 v[48:51], v[162:165], v[178:181], v[48:51]
	v_mfma_f32_16x16x32_bf16 v[40:43], v[170:173], v[178:181], v[40:43]
	v_mfma_f32_16x16x32_bf16 v[32:35], v[162:165], v[186:189], v[32:35]
	v_mfma_f32_16x16x32_bf16 v[24:27], v[170:173], v[186:189], v[24:27]
	v_mfma_f32_16x16x32_bf16 v[16:19], v[162:165], v[194:197], v[16:19]
	v_mfma_f32_16x16x32_bf16 v[8:11], v[170:173], v[194:197], v[8:11]
	v_mfma_f32_16x16x32_bf16 v[4:7], v[162:165], v[202:205], v[4:7]
	v_mfma_f32_16x16x32_bf16 v[0:3], v[170:173], v[202:205], v[0:3]
	v_mfma_f32_16x16x32_bf16 v[48:51], v[166:169], v[182:185], v[48:51]
	v_mfma_f32_16x16x32_bf16 v[40:43], v[174:177], v[182:185], v[40:43]
	v_mfma_f32_16x16x32_bf16 v[32:35], v[166:169], v[190:193], v[32:35]
	v_mfma_f32_16x16x32_bf16 v[24:27], v[174:177], v[190:193], v[24:27]
	v_mfma_f32_16x16x32_bf16 v[16:19], v[166:169], v[198:201], v[16:19]
	v_mfma_f32_16x16x32_bf16 v[8:11], v[174:177], v[198:201], v[8:11]
	v_mfma_f32_16x16x32_bf16 v[4:7], v[166:169], v[210:213], v[4:7]
	v_mfma_f32_16x16x32_bf16 v[0:3], v[174:177], v[210:213], v[0:3]
	s_barrier
	s_add_i32 s51, s51, 2
	s_add_u32 s0, s0, 0x100
	s_addc_u32 s1, s1, 0
	s_add_u32 s49, s49, 0x100
	s_addc_u32 s50, s50, 0
	s_cmp_gt_u32 s51, 13
	s_cbranch_scc0 .LBB0_338
	s_and_b64 vcc, exec, s[8:9]
	s_cbranch_vccz .LBB0_341
	s_barrier

; #define PG8_STAGE(bufoff, gbase, voff) do { _Pragma("unroll") for (int _i = 0; _i < 2; ++_i) \
;         __builtin_amdgcn_global_load_lds((const unsigned*)((const char*)(gbase) + (voff)[_i]), (PG8_LAS unsigned*)(lds + (bufoff) + ldsw + _i * 8192), 16, 0, 0); } while (0)
; #define PG8_WAIT_V(n) asm volatile("s_waitcnt vmcnt(" #n ")" ::: "memory")
; #define PG8_BAR __builtin_amdgcn_s_barrier()
; template <class Epi, class Sched, bool ALIGN_EPI = false, bool SP2 = false>
; __device__ __forceinline__ void gemm_phase(PG8_LAS unsigned char* lds, const Gemm g, const Sched& S, const Epi& E) {
;     ...
;     for (int i = 0; i < 2; ++i) { int R, C; stage_rc(tid * 16 + i * 8192, R, C); const int Rb = Epi::PERM ? ((R & ~31) + perm32(R & 31)) : R;
;         voffA[i] = (unsigned)(R * g.lda + C) * 2u; voffB[i] = (unsigned)(Rb * g.ldb + C) * 2u; }
;     const size_t kstep = (size_t)(BK * 2);
;     const size_t hstepA = (size_t)HALF * g.lda * 2, hstepB = (size_t)HALF * g.ldb * 2;
;     const size_t tstepA = 2 * hstepA, tstepB = 2 * hstepB;
;     const unsigned ldsw = (unsigned)wid * 1024u;
;     const int aoff = lds_byte(wr * 64 + fr, fq * 8), boff = lds_byte(wc * 32 + fr, fq * 8);
;     ...
;         PG8_STAGE(PG8_SB(0, 0), cB, voffB); PG8_STAGE(PG8_SB(0, 1), cB + hstepB, voffB); PG8_STAGE(PG8_SA(0, 0), cA, voffA); PG8_STAGE(PG8_SA(0, 1), cA + hstepA, voffA);
;         if (wr == 1) PG8_BAR;
;         PG8_WAIT_V(2); PG8_BAR;
;         PG8_STAGE(PG8_SB(1, 0), cB + kstep, voffB); PG8_STAGE(PG8_SA(1, 0), cA + kstep, voffA); PG8_STAGE(PG8_SB(1, 1), cB + hstepB + kstep, voffB);
;         PG8_WAIT_V(6); PG8_BAR;
.LBB0_348:
	v_lshrrev_b32_e32 v16, 1, v14
	v_and_b32_e32 v16, 24, v16
	v_and_b32_e32 v15, 15, v14
	v_lshlrev_b32_e32 v17, 1, v16
	v_lshlrev_b32_e32 v14, 2, v14
	s_sext_i32_i16 s38, s0
	v_lshl_or_b32 v138, s5, 6, v15
	v_lshl_or_b32 v15, v15, 6, v17
	s_lshl_b32 s0, s5, 13
	v_and_b32_e32 v14, 32, v14
	v_bitop3_b32 v17, v15, s0, v14 bitop3:0xde
	s_lshl_b32 s0, s4, 5
	s_and_b32 s0, s0, 0x60
	s_add_i32 m0, s21, 0x18000
	v_lshl_add_u64 v[6:7], v[6:7], 0, s[10:11]
	s_lshl_b32 s4, s0, 7
	s_waitcnt vmcnt(2)
	s_barrier
	global_load_lds_dwordx4 v[6:7], off
	v_lshl_add_u64 v[4:5], v[4:5], 0, s[10:11]
	s_add_i32 m0, s21, 0x1a000
	s_add_i32 s35, s21, 0x8000
	s_add_i32 s39, s21, 0xa000
	v_bitop3_b32 v139, v15, s4, v14 bitop3:0xde
	global_load_lds_dwordx4 v[4:5], off
	v_lshl_add_u64 v[0:1], v[0:1], 0, s[10:11]
	s_mov_b32 m0, s35
	s_add_u32 s4, s46, 0x40080
	global_load_lds_dwordx4 v[0:1], off
	v_lshl_add_u64 v[0:1], v[2:3], 0, s[10:11]
	s_mov_b32 m0, s39
	s_addc_u32 s5, s47, 0
	global_load_lds_dwordx4 v[0:1], off
	s_add_i32 m0, s21, 0x1c000
	v_lshl_add_u64 v[0:1], s[4:5], 0, v[208:209]
	global_load_lds_dwordx4 v208, s[4:5]
	v_lshl_add_u64 v[0:1], s[4:5], 0, v[128:129]
	s_add_i32 m0, s21, 0x1e000
	s_cmpk_lt_u32 s1, 0x100
	global_load_lds_dwordx4 v128, s[4:5]
	v_lshlrev_b32_e32 v0, 14, v12
	v_and_b32_e32 v0, 0xffff8000, v0
	v_lshl_add_u32 v0, v11, 11, v0
	v_and_b32_e32 v1, 1, v12
	v_lshl_or_b32 v0, v1, 6, v0
	v_lshl_add_u32 v134, v13, 1, v0
	v_lshlrev_b32_e32 v0, 14, v8
	v_and_b32_e32 v0, 0xffff8000, v0
	s_waitcnt vmcnt(6)
	v_lshl_add_u32 v0, v9, 11, v0
	v_and_b32_e32 v1, 1, v8
	v_lshl_or_b32 v0, v1, 6, v0
	v_readlane_b32 s30, v252, 8
	s_cselect_b64 s[8:9], -1, 0
	v_or_b32_e32 v140, s0, v16
	v_mov_b32_e32 v135, v209
	v_lshl_add_u32 v136, v10, 1, v0
	v_mov_b32_e32 v137, v209
	s_mov_b32 s48, 0
	v_add_u32_e32 v141, 0, v17
	v_readlane_b32 s31, v252, 9
	s_barrier
	s_branch .LBB0_351

; #define PG8_STAGE(bufoff, gbase, voff) do { _Pragma("unroll") for (int _i = 0; _i < 2; ++_i) \
;         __builtin_amdgcn_global_load_lds((const unsigned*)((const char*)(gbase) + (voff)[_i]), (PG8_LAS unsigned*)(lds + (bufoff) + ldsw + _i * 8192), 16, 0, 0); } while (0)
; #define PG8_LDA(dst, b, h) do { _Pragma("unroll") for (int m = 0; m < 4; ++m) _Pragma("unroll") for (int k = 0; k < 2; ++k) dst[m][k] = *(const PG8_LAS bf16x8*)(lds + PG8_SA(b, h) + aoff + m * 2048 + k * 1024); } while (0)
; #define PG8_LDB(dst, b, h) do { _Pragma("unroll") for (int n = 0; n < 2; ++n) _Pragma("unroll") for (int k = 0; k < 2; ++k) dst[n][k] = *(const PG8_LAS bf16x8*)(lds + PG8_SB(b, h) + boff + n * 2048 + k * 1024); } while (0)
; #define PG8_MMA(ai, bj, At, Bt) do { __builtin_amdgcn_s_setprio(1); _Pragma("unroll") for (int m = 0; m < 4; ++m) _Pragma("unroll") for (int n = 0; n < 2; ++n) _Pragma("unroll") for (int k = 0; k < 2; ++k) \
;         acc[ai][bj][m][n] = __builtin_amdgcn_mfma_f32_16x16x32_bf16(Bt[n][k], At[m][k], acc[ai][bj][m][n], 0, 0, 0); __builtin_amdgcn_s_setprio(0); } while (0)
; #define PG8_WAIT_V(n) asm volatile("s_waitcnt vmcnt(" #n ")" ::: "memory")
; #define PG8_WAIT_L(n) asm volatile("s_waitcnt lgkmcnt(" #n ")" ::: "memory")
; #define PG8_BAR __builtin_amdgcn_s_barrier()
; #define PG8_SCHED __builtin_amdgcn_sched_barrier(0)
; template <class Epi, class Sched, bool ALIGN_EPI = false, bool SP2 = false>
; __device__ __forceinline__ void gemm_phase(PG8_LAS unsigned char* lds, const Gemm g, const Sched& S, const Epi& E) {
;     ...
;             PG8_LDB(B0, 0, 0); PG8_LDB(B1, 0, 1); PG8_SCHED; PG8_LDA(At, 0, 0); PG8_STAGE(PG8_SA(1, 1), a1 + hstepA, voffA);
;             PG8_WAIT_V(8); PG8_WAIT_L(0); PG8_BAR; PG8_MMA(0, 0, At, B0); PG8_MMA(0, 1, At, B1); PG8_BAR; PG8_SCHED;
;             PG8_LDA(At, 0, 1); PG8_STAGE(PG8_SB(0, 0), b2, voffB); PG8_STAGE(PG8_SB(0, 1), b2 + hstepB, voffB); PG8_STAGE(PG8_SA(0, 0), a2, voffA);
;             PG8_WAIT_V(8); PG8_WAIT_L(0); PG8_BAR; PG8_MMA(1, 0, At, B0); PG8_MMA(1, 1, At, B1); PG8_BAR; PG8_SCHED;
.LBB0_354:
	s_add_u32 s22, s44, 0xfffc0080
	s_addc_u32 s23, s45, -1
	s_add_i32 s28, 0, 0x10000
	s_cmp_eq_u32 s51, 12
	s_cselect_b32 s47, s14, s23
	s_cselect_b32 s46, s15, s22
	s_cselect_b32 s23, s1, s50
	s_cselect_b32 s22, s41, s49
	s_add_i32 s29, 0, 0x14000
	v_add_u32_e32 v154, s28, v139
	v_add_u32_e32 v170, s29, v139
	ds_read_b128 v[142:145], v154
	ds_read_b128 v[146:149], v154 offset:1024
	ds_read_b128 v[150:153], v154 offset:2048
	ds_read_b128 v[154:157], v154 offset:3072
	ds_read_b128 v[158:161], v170
	ds_read_b128 v[162:165], v170 offset:1024
	ds_read_b128 v[166:169], v170 offset:2048
	ds_read_b128 v[170:173], v170 offset:3072
	s_add_i32 m0, s21, 0xc000
	ds_read_b128 v[174:177], v141
	ds_read_b128 v[178:181], v141 offset:1024
	ds_read_b128 v[182:185], v141 offset:2048
	ds_read_b128 v[186:189], v141 offset:3072
	ds_read_b128 v[190:193], v141 offset:4096
	ds_read_b128 v[194:197], v141 offset:5120
	ds_read_b128 v[198:201], v141 offset:6144
	ds_read_b128 v[202:205], v141 offset:7168
	global_load_lds_dwordx4 v134, s[44:45]
	s_add_i32 m0, s21, 0xe000
	s_nop 0
	global_load_lds_dwordx4 v136, s[44:45]
	s_waitcnt vmcnt(8)
	s_waitcnt lgkmcnt(0)
	s_barrier
	s_waitcnt lgkmcnt(0)
	v_mfma_f32_16x16x32_bf16 v[124:127], v[142:145], v[174:177], v[124:127]
	v_mfma_f32_16x16x32_bf16 v[120:123], v[150:153], v[174:177], v[120:123]
	v_mfma_f32_16x16x32_bf16 v[116:119], v[142:145], v[182:185], v[116:119]
	v_mfma_f32_16x16x32_bf16 v[112:115], v[150:153], v[182:185], v[112:115]
	v_mfma_f32_16x16x32_bf16 v[100:103], v[142:145], v[190:193], v[100:103]
	v_mfma_f32_16x16x32_bf16 v[96:99], v[150:153], v[190:193], v[96:99]
	v_mfma_f32_16x16x32_bf16 v[84:87], v[142:145], v[198:201], v[84:87]
	v_mfma_f32_16x16x32_bf16 v[80:83], v[150:153], v[198:201], v[80:83]
	v_mfma_f32_16x16x32_bf16 v[124:127], v[146:149], v[178:181], v[124:127]
	v_mfma_f32_16x16x32_bf16 v[120:123], v[154:157], v[178:181], v[120:123]
	v_mfma_f32_16x16x32_bf16 v[116:119], v[146:149], v[186:189], v[116:119]
	v_mfma_f32_16x16x32_bf16 v[112:115], v[154:157], v[186:189], v[112:115]
	v_mfma_f32_16x16x32_bf16 v[100:103], v[146:149], v[194:197], v[100:103]
	v_mfma_f32_16x16x32_bf16 v[96:99], v[154:157], v[194:197], v[96:99]
	v_mfma_f32_16x16x32_bf16 v[84:87], v[146:149], v[202:205], v[84:87]
	v_mfma_f32_16x16x32_bf16 v[80:83], v[154:157], v[202:205], v[80:83]
	v_mfma_f32_16x16x32_bf16 v[108:111], v[158:161], v[174:177], v[108:111]
	v_mfma_f32_16x16x32_bf16 v[104:107], v[166:169], v[174:177], v[104:107]
	v_mfma_f32_16x16x32_bf16 v[92:95], v[158:161], v[182:185], v[92:95]
	v_mfma_f32_16x16x32_bf16 v[88:91], v[166:169], v[182:185], v[88:91]
	v_mfma_f32_16x16x32_bf16 v[76:79], v[158:161], v[190:193], v[76:79]
	v_mfma_f32_16x16x32_bf16 v[72:75], v[166:169], v[190:193], v[72:75]
	v_mfma_f32_16x16x32_bf16 v[68:71], v[158:161], v[198:201], v[68:71]
	v_mfma_f32_16x16x32_bf16 v[64:67], v[166:169], v[198:201], v[64:67]
	v_mfma_f32_16x16x32_bf16 v[108:111], v[162:165], v[178:181], v[108:111]
	v_mfma_f32_16x16x32_bf16 v[104:107], v[170:173], v[178:181], v[104:107]
	v_mfma_f32_16x16x32_bf16 v[92:95], v[162:165], v[186:189], v[92:95]
	v_mfma_f32_16x16x32_bf16 v[88:91], v[170:173], v[186:189], v[88:91]
	v_mfma_f32_16x16x32_bf16 v[76:79], v[162:165], v[194:197], v[76:79]
	v_mfma_f32_16x16x32_bf16 v[72:75], v[170:173], v[194:197], v[72:75]
	v_mfma_f32_16x16x32_bf16 v[68:71], v[162:165], v[202:205], v[68:71]
	v_mfma_f32_16x16x32_bf16 v[64:67], v[170:173], v[202:205], v[64:67]
	s_barrier
	s_add_i32 s28, s28, s18
	v_lshl_add_u64 v[206:207], s[22:23], 0, v[208:209]
	s_mov_b32 m0, s28
	ds_read_b128 v[174:177], v141 offset:16384
	ds_read_b128 v[178:181], v141 offset:17408
	ds_read_b128 v[182:185], v141 offset:18432
	ds_read_b128 v[186:189], v141 offset:19456
	ds_read_b128 v[190:193], v141 offset:20480
	ds_read_b128 v[194:197], v141 offset:21504
	ds_read_b128 v[198:201], v141 offset:22528
	ds_read_b128 v[202:205], v141 offset:23552
	global_load_lds_dwordx4 v208, s[22:23]
	s_add_i32 m0, s28, 0x2000
	s_add_u32 s52, s22, 0x40000
	v_lshl_add_u64 v[210:211], s[22:23], 0, v[128:129]
	s_addc_u32 s53, s23, 0
	s_add_i32 s28, s29, s18
	global_load_lds_dwordx4 v128, s[22:23]
	s_mov_b32 m0, s28
	v_lshl_add_u64 v[222:223], s[46:47], 0, v[130:131]
	global_load_lds_dwordx4 v208, s[52:53]
	s_add_i32 m0, s28, 0x2000
	s_nop 0
	global_load_lds_dwordx4 v128, s[52:53]
	v_lshl_add_u64 v[212:213], s[46:47], 0, v[132:133]
	s_mov_b32 m0, s21
	s_nop 0
	global_load_lds_dwordx4 v132, s[46:47]
	s_mov_b32 m0, s12
	s_nop 0
	global_load_lds_dwordx4 v130, s[46:47]
	s_waitcnt vmcnt(8)
	s_waitcnt lgkmcnt(0)
	s_barrier
; #define PG8_STAGE(bufoff, gbase, voff) do { _Pragma("unroll") for (int _i = 0; _i < 2; ++_i) \
;         __builtin_amdgcn_global_load_lds((const unsigned*)((const char*)(gbase) + (voff)[_i]), (PG8_LAS unsigned*)(lds + (bufoff) + ldsw + _i * 8192), 16, 0, 0); } while (0)
; #define PG8_LDA(dst, b, h) do { _Pragma("unroll") for (int m = 0; m < 4; ++m) _Pragma("unroll") for (int k = 0; k < 2; ++k) dst[m][k] = *(const PG8_LAS bf16x8*)(lds + PG8_SA(b, h) + aoff + m * 2048 + k * 1024); } while (0)
; #define PG8_LDB(dst, b, h) do { _Pragma("unroll") for (int n = 0; n < 2; ++n) _Pragma("unroll") for (int k = 0; k < 2; ++k) dst[n][k] = *(const PG8_LAS bf16x8*)(lds + PG8_SB(b, h) + boff + n * 2048 + k * 1024); } while (0)
; #define PG8_MMA(ai, bj, At, Bt) do { __builtin_amdgcn_s_setprio(1); _Pragma("unroll") for (int m = 0; m < 4; ++m) _Pragma("unroll") for (int n = 0; n < 2; ++n) _Pragma("unroll") for (int k = 0; k < 2; ++k) \
;         acc[ai][bj][m][n] = __builtin_amdgcn_mfma_f32_16x16x32_bf16(Bt[n][k], At[m][k], acc[ai][bj][m][n], 0, 0, 0); __builtin_amdgcn_s_setprio(0); } while (0)
; #define PG8_WAIT_V(n) asm volatile("s_waitcnt vmcnt(" #n ")" ::: "memory")
; #define PG8_WAIT_L(n) asm volatile("s_waitcnt lgkmcnt(" #n ")" ::: "memory")
; #define PG8_BAR __builtin_amdgcn_s_barrier()
; #define PG8_SCHED __builtin_amdgcn_sched_barrier(0)
; template <class Epi, class Sched, bool ALIGN_EPI = false, bool SP2 = false>
; __device__ __forceinline__ void gemm_phase(PG8_LAS unsigned char* lds, const Gemm g, const Sched& S, const Epi& E) {
;     ...
;             PG8_WAIT_V(8); PG8_WAIT_L(0); PG8_BAR; PG8_MMA(1, 0, At, B0); PG8_MMA(1, 1, At, B1); PG8_BAR; PG8_SCHED;
;             PG8_LDB(B0, 1, 0); PG8_LDB(B1, 1, 1); PG8_SCHED; PG8_LDA(At, 1, 0); PG8_STAGE(PG8_SA(0, 1), a2 + hstepA, voffA);
;             PG8_WAIT_V(8); PG8_WAIT_L(0); PG8_BAR; PG8_MMA(0, 0, At, B0); PG8_MMA(0, 1, At, B1); PG8_BAR; PG8_SCHED;
	s_waitcnt lgkmcnt(0)
	v_mfma_f32_16x16x32_bf16 v[60:63], v[142:145], v[174:177], v[60:63]
	v_mfma_f32_16x16x32_bf16 v[56:59], v[150:153], v[174:177], v[56:59]
	v_mfma_f32_16x16x32_bf16 v[52:55], v[142:145], v[182:185], v[52:55]
	v_mfma_f32_16x16x32_bf16 v[48:51], v[150:153], v[182:185], v[48:51]
	v_mfma_f32_16x16x32_bf16 v[36:39], v[142:145], v[190:193], v[36:39]
	v_mfma_f32_16x16x32_bf16 v[32:35], v[150:153], v[190:193], v[32:35]
	v_mfma_f32_16x16x32_bf16 v[20:23], v[142:145], v[198:201], v[20:23]
	v_mfma_f32_16x16x32_bf16 v[16:19], v[150:153], v[198:201], v[16:19]
	v_mfma_f32_16x16x32_bf16 v[60:63], v[146:149], v[178:181], v[60:63]
	v_mfma_f32_16x16x32_bf16 v[56:59], v[154:157], v[178:181], v[56:59]
	v_mfma_f32_16x16x32_bf16 v[52:55], v[146:149], v[186:189], v[52:55]
	v_mfma_f32_16x16x32_bf16 v[48:51], v[154:157], v[186:189], v[48:51]
	v_mfma_f32_16x16x32_bf16 v[36:39], v[146:149], v[194:197], v[36:39]
	v_mfma_f32_16x16x32_bf16 v[32:35], v[154:157], v[194:197], v[32:35]
	v_mfma_f32_16x16x32_bf16 v[20:23], v[146:149], v[202:205], v[20:23]
	v_mfma_f32_16x16x32_bf16 v[16:19], v[154:157], v[202:205], v[16:19]
	v_mfma_f32_16x16x32_bf16 v[44:47], v[158:161], v[174:177], v[44:47]
	v_mfma_f32_16x16x32_bf16 v[40:43], v[166:169], v[174:177], v[40:43]
	v_mfma_f32_16x16x32_bf16 v[28:31], v[158:161], v[182:185], v[28:31]
	v_mfma_f32_16x16x32_bf16 v[24:27], v[166:169], v[182:185], v[24:27]
	v_mfma_f32_16x16x32_bf16 v[12:15], v[158:161], v[190:193], v[12:15]
	v_mfma_f32_16x16x32_bf16 v[8:11], v[166:169], v[190:193], v[8:11]
	v_mfma_f32_16x16x32_bf16 v[4:7], v[158:161], v[198:201], v[4:7]
	v_mfma_f32_16x16x32_bf16 v[0:3], v[166:169], v[198:201], v[0:3]
	v_mfma_f32_16x16x32_bf16 v[44:47], v[162:165], v[178:181], v[44:47]
	v_mfma_f32_16x16x32_bf16 v[40:43], v[170:173], v[178:181], v[40:43]
	v_mfma_f32_16x16x32_bf16 v[28:31], v[162:165], v[186:189], v[28:31]
	v_mfma_f32_16x16x32_bf16 v[24:27], v[170:173], v[186:189], v[24:27]
	v_mfma_f32_16x16x32_bf16 v[12:15], v[162:165], v[194:197], v[12:15]
	v_mfma_f32_16x16x32_bf16 v[8:11], v[170:173], v[194:197], v[8:11]
	v_mfma_f32_16x16x32_bf16 v[4:7], v[162:165], v[202:205], v[4:7]
	v_mfma_f32_16x16x32_bf16 v[0:3], v[170:173], v[202:205], v[0:3]
	s_barrier
	s_add_i32 s28, 0, 0x18000
	s_add_i32 s29, 0, 0x1c000
	v_add_u32_e32 v154, s28, v139
	v_add_u32_e32 v170, s29, v139
	ds_read_b128 v[142:145], v154
	ds_read_b128 v[146:149], v154 offset:1024
	ds_read_b128 v[150:153], v154 offset:2048
	ds_read_b128 v[154:157], v154 offset:3072
	ds_read_b128 v[158:161], v170
	ds_read_b128 v[162:165], v170 offset:1024
	ds_read_b128 v[166:169], v170 offset:2048
	ds_read_b128 v[170:173], v170 offset:3072
	s_add_u32 s46, s46, 0x40000
	s_addc_u32 s47, s47, 0
	s_mov_b32 m0, s26
	ds_read_b128 v[174:177], v141 offset:32768
	ds_read_b128 v[178:181], v141 offset:33792
	ds_read_b128 v[182:185], v141 offset:34816
	ds_read_b128 v[186:189], v141 offset:35840
	ds_read_b128 v[190:193], v141 offset:36864
	ds_read_b128 v[194:197], v141 offset:37888
	ds_read_b128 v[198:201], v141 offset:38912
	ds_read_b128 v[202:205], v141 offset:39936
	global_load_lds_dwordx4 v132, s[46:47]
	v_lshl_add_u64 v[224:225], s[46:47], 0, v[130:131]
	s_mov_b32 m0, s34
	s_nop 0
	global_load_lds_dwordx4 v130, s[46:47]
	s_waitcnt vmcnt(8)
	s_waitcnt lgkmcnt(0)
	s_barrier
	s_waitcnt lgkmcnt(0)
	v_mfma_f32_16x16x32_bf16 v[124:127], v[142:145], v[174:177], v[124:127]
	v_mfma_f32_16x16x32_bf16 v[120:123], v[150:153], v[174:177], v[120:123]
	v_mfma_f32_16x16x32_bf16 v[116:119], v[142:145], v[182:185], v[116:119]
	v_mfma_f32_16x16x32_bf16 v[112:115], v[150:153], v[182:185], v[112:115]
	v_mfma_f32_16x16x32_bf16 v[100:103], v[142:145], v[190:193], v[100:103]
	v_mfma_f32_16x16x32_bf16 v[96:99], v[150:153], v[190:193], v[96:99]
	v_mfma_f32_16x16x32_bf16 v[84:87], v[142:145], v[198:201], v[84:87]
	v_mfma_f32_16x16x32_bf16 v[80:83], v[150:153], v[198:201], v[80:83]
	v_mfma_f32_16x16x32_bf16 v[124:127], v[146:149], v[178:181], v[124:127]
	v_mfma_f32_16x16x32_bf16 v[120:123], v[154:157], v[178:181], v[120:123]
	v_mfma_f32_16x16x32_bf16 v[116:119], v[146:149], v[186:189], v[116:119]
	v_mfma_f32_16x16x32_bf16 v[112:115], v[154:157], v[186:189], v[112:115]
	v_mfma_f32_16x16x32_bf16 v[100:103], v[146:149], v[194:197], v[100:103]
	v_mfma_f32_16x16x32_bf16 v[96:99], v[154:157], v[194:197], v[96:99]
	v_mfma_f32_16x16x32_bf16 v[84:87], v[146:149], v[202:205], v[84:87]
	v_mfma_f32_16x16x32_bf16 v[80:83], v[154:157], v[202:205], v[80:83]
	v_mfma_f32_16x16x32_bf16 v[108:111], v[158:161], v[174:177], v[108:111]
	v_mfma_f32_16x16x32_bf16 v[104:107], v[166:169], v[174:177], v[104:107]
	v_mfma_f32_16x16x32_bf16 v[92:95], v[158:161], v[182:185], v[92:95]
	v_mfma_f32_16x16x32_bf16 v[88:91], v[166:169], v[182:185], v[88:91]
	v_mfma_f32_16x16x32_bf16 v[76:79], v[158:161], v[190:193], v[76:79]
	v_mfma_f32_16x16x32_bf16 v[72:75], v[166:169], v[190:193], v[72:75]
	v_mfma_f32_16x16x32_bf16 v[68:71], v[158:161], v[198:201], v[68:71]
	v_mfma_f32_16x16x32_bf16 v[64:67], v[166:169], v[198:201], v[64:67]
	v_mfma_f32_16x16x32_bf16 v[108:111], v[162:165], v[178:181], v[108:111]
	v_mfma_f32_16x16x32_bf16 v[104:107], v[170:173], v[178:181], v[104:107]
	v_mfma_f32_16x16x32_bf16 v[92:95], v[162:165], v[186:189], v[92:95]
	v_mfma_f32_16x16x32_bf16 v[88:91], v[170:173], v[186:189], v[88:91]
	v_mfma_f32_16x16x32_bf16 v[76:79], v[162:165], v[194:197], v[76:79]
	v_mfma_f32_16x16x32_bf16 v[72:75], v[170:173], v[194:197], v[72:75]
	v_mfma_f32_16x16x32_bf16 v[68:71], v[162:165], v[202:205], v[68:71]
	v_mfma_f32_16x16x32_bf16 v[64:67], v[170:173], v[202:205], v[64:67]
	s_barrier
; #define PG8_STAGE(bufoff, gbase, voff) do { _Pragma("unroll") for (int _i = 0; _i < 2; ++_i) \
;         __builtin_amdgcn_global_load_lds((const unsigned*)((const char*)(gbase) + (voff)[_i]), (PG8_LAS unsigned*)(lds + (bufoff) + ldsw + _i * 8192), 16, 0, 0); } while (0)
; #define PG8_LDA(dst, b, h) do { _Pragma("unroll") for (int m = 0; m < 4; ++m) _Pragma("unroll") for (int k = 0; k < 2; ++k) dst[m][k] = *(const PG8_LAS bf16x8*)(lds + PG8_SA(b, h) + aoff + m * 2048 + k * 1024); } while (0)
; #define PG8_MMA(ai, bj, At, Bt) do { __builtin_amdgcn_s_setprio(1); _Pragma("unroll") for (int m = 0; m < 4; ++m) _Pragma("unroll") for (int n = 0; n < 2; ++n) _Pragma("unroll") for (int k = 0; k < 2; ++k) \
;         acc[ai][bj][m][n] = __builtin_amdgcn_mfma_f32_16x16x32_bf16(Bt[n][k], At[m][k], acc[ai][bj][m][n], 0, 0, 0); __builtin_amdgcn_s_setprio(0); } while (0)
; #define PG8_WAIT_V(n) asm volatile("s_waitcnt vmcnt(" #n ")" ::: "memory")
; #define PG8_WAIT_L(n) asm volatile("s_waitcnt lgkmcnt(" #n ")" ::: "memory")
; #define PG8_BAR __builtin_amdgcn_s_barrier()
; #define PG8_SCHED __builtin_amdgcn_sched_barrier(0)
; template <class Epi, class Sched, bool ALIGN_EPI = false, bool SP2 = false>
; __device__ __forceinline__ void gemm_phase(PG8_LAS unsigned char* lds, const Gemm g, const Sched& S, const Epi& E) {
;     ...
;             PG8_LDA(At, 1, 1); PG8_STAGE(PG8_SB(1, 0), b3, voffB); PG8_STAGE(PG8_SB(1, 1), b3 + hstepB, voffB); PG8_STAGE(PG8_SA(1, 0), a3, voffA);
;             PG8_WAIT_V(8); PG8_WAIT_L(0); PG8_BAR; PG8_MMA(1, 0, At, B0); PG8_MMA(1, 1, At, B1); PG8_BAR; PG8_SCHED;
	s_add_i32 s28, s28, s18
	v_lshl_add_u64 v[206:207], v[206:207], 0, s[10:11]
	s_mov_b32 m0, s28
	ds_read_b128 v[174:177], v141 offset:49152
	ds_read_b128 v[178:181], v141 offset:50176
	ds_read_b128 v[182:185], v141 offset:51200
	ds_read_b128 v[186:189], v141 offset:52224
	ds_read_b128 v[190:193], v141 offset:53248
	ds_read_b128 v[194:197], v141 offset:54272
	ds_read_b128 v[198:201], v141 offset:55296
	ds_read_b128 v[202:205], v141 offset:56320
	global_load_lds_dwordx4 v[206:207], off
	s_add_i32 m0, s28, 0x2000
	s_add_u32 s22, s22, 0x40080
	v_lshl_add_u64 v[206:207], v[210:211], 0, s[10:11]
	s_addc_u32 s23, s23, 0
	s_add_i32 s28, s29, s18
	global_load_lds_dwordx4 v[206:207], off
	s_mov_b32 m0, s28
	s_nop 0
	global_load_lds_dwordx4 v208, s[22:23]
	s_add_i32 m0, s28, 0x2000
	s_nop 0
	global_load_lds_dwordx4 v128, s[22:23]
	v_lshl_add_u64 v[206:207], v[212:213], 0, s[10:11]
	s_mov_b32 m0, s35
	s_nop 0
	global_load_lds_dwordx4 v[206:207], off
	v_lshl_add_u64 v[206:207], v[222:223], 0, s[10:11]
	s_mov_b32 m0, s39
	s_nop 0
	global_load_lds_dwordx4 v[206:207], off
	s_waitcnt vmcnt(8)
	s_waitcnt lgkmcnt(0)
	s_barrier
	s_waitcnt lgkmcnt(0)
	v_mfma_f32_16x16x32_bf16 v[60:63], v[142:145], v[174:177], v[60:63]
	v_mfma_f32_16x16x32_bf16 v[56:59], v[150:153], v[174:177], v[56:59]
	v_mfma_f32_16x16x32_bf16 v[52:55], v[142:145], v[182:185], v[52:55]
	v_mfma_f32_16x16x32_bf16 v[48:51], v[150:153], v[182:185], v[48:51]
	v_mfma_f32_16x16x32_bf16 v[36:39], v[142:145], v[190:193], v[36:39]
	v_mfma_f32_16x16x32_bf16 v[32:35], v[150:153], v[190:193], v[32:35]
	v_mfma_f32_16x16x32_bf16 v[20:23], v[142:145], v[198:201], v[20:23]
	v_mfma_f32_16x16x32_bf16 v[16:19], v[150:153], v[198:201], v[16:19]
	v_mfma_f32_16x16x32_bf16 v[60:63], v[146:149], v[178:181], v[60:63]
	v_mfma_f32_16x16x32_bf16 v[56:59], v[154:157], v[178:181], v[56:59]
	v_mfma_f32_16x16x32_bf16 v[52:55], v[146:149], v[186:189], v[52:55]
	v_mfma_f32_16x16x32_bf16 v[48:51], v[154:157], v[186:189], v[48:51]
	v_mfma_f32_16x16x32_bf16 v[36:39], v[146:149], v[194:197], v[36:39]
	v_mfma_f32_16x16x32_bf16 v[32:35], v[154:157], v[194:197], v[32:35]
	v_mfma_f32_16x16x32_bf16 v[20:23], v[146:149], v[202:205], v[20:23]
	v_mfma_f32_16x16x32_bf16 v[16:19], v[154:157], v[202:205], v[16:19]
	v_mfma_f32_16x16x32_bf16 v[44:47], v[158:161], v[174:177], v[44:47]
	v_mfma_f32_16x16x32_bf16 v[40:43], v[166:169], v[174:177], v[40:43]
	v_mfma_f32_16x16x32_bf16 v[28:31], v[158:161], v[182:185], v[28:31]
	v_mfma_f32_16x16x32_bf16 v[24:27], v[166:169], v[182:185], v[24:27]
	v_mfma_f32_16x16x32_bf16 v[12:15], v[158:161], v[190:193], v[12:15]
	v_mfma_f32_16x16x32_bf16 v[8:11], v[166:169], v[190:193], v[8:11]
	v_mfma_f32_16x16x32_bf16 v[4:7], v[158:161], v[198:201], v[4:7]
	v_mfma_f32_16x16x32_bf16 v[0:3], v[166:169], v[198:201], v[0:3]
	v_mfma_f32_16x16x32_bf16 v[44:47], v[162:165], v[178:181], v[44:47]
	v_mfma_f32_16x16x32_bf16 v[40:43], v[170:173], v[178:181], v[40:43]
	v_mfma_f32_16x16x32_bf16 v[28:31], v[162:165], v[186:189], v[28:31]
	v_mfma_f32_16x16x32_bf16 v[24:27], v[170:173], v[186:189], v[24:27]
	v_mfma_f32_16x16x32_bf16 v[12:15], v[162:165], v[194:197], v[12:15]
	v_mfma_f32_16x16x32_bf16 v[8:11], v[170:173], v[194:197], v[8:11]
	v_mfma_f32_16x16x32_bf16 v[4:7], v[162:165], v[202:205], v[4:7]
	v_mfma_f32_16x16x32_bf16 v[0:3], v[170:173], v[202:205], v[0:3]
	s_barrier
	s_add_i32 s51, s51, 2
	s_add_u32 s44, s44, 0x100
	s_addc_u32 s45, s45, 0
	s_add_u32 s49, s49, 0x100
	s_addc_u32 s50, s50, 0
	s_cmp_gt_u32 s51, 13
	s_cbranch_scc0 .LBB0_354
	s_and_b64 vcc, exec, s[8:9]
	s_cbranch_vccz .LBB0_357
	s_barrier

; #define PG8_STAGE(bufoff, gbase, voff) do { _Pragma("unroll") for (int _i = 0; _i < 2; ++_i) \
;         __builtin_amdgcn_global_load_lds((const unsigned*)((const char*)(gbase) + (voff)[_i]), (PG8_LAS unsigned*)(lds + (bufoff) + ldsw + _i * 8192), 16, 0, 0); } while (0)
; #define PG8_WAIT_V(n) asm volatile("s_waitcnt vmcnt(" #n ")" ::: "memory")
; #define PG8_BAR __builtin_amdgcn_s_barrier()
; template <class Epi, class Sched, bool ALIGN_EPI = false, bool SP2 = false>
; __device__ __forceinline__ void gemm_phase(PG8_LAS unsigned char* lds, const Gemm g, const Sched& S, const Epi& E) {
;     ...
;     for (int i = 0; i < 2; ++i) { int R, C; stage_rc(tid * 16 + i * 8192, R, C); const int Rb = Epi::PERM ? ((R & ~31) + perm32(R & 31)) : R;
;         voffA[i] = (unsigned)(R * g.lda + C) * 2u; voffB[i] = (unsigned)(Rb * g.ldb + C) * 2u; }
;     const size_t kstep = (size_t)(BK * 2);
;     const size_t hstepA = (size_t)HALF * g.lda * 2, hstepB = (size_t)HALF * g.ldb * 2;
;     const size_t tstepA = 2 * hstepA, tstepB = 2 * hstepB;
;     const unsigned ldsw = (unsigned)wid * 1024u;
;     const int aoff = lds_byte(wr * 64 + fr, fq * 8), boff = lds_byte(wc * 32 + fr, fq * 8);
;     ...
;         PG8_STAGE(PG8_SB(0, 0), cB, voffB); PG8_STAGE(PG8_SB(0, 1), cB + hstepB, voffB); PG8_STAGE(PG8_SA(0, 0), cA, voffA); PG8_STAGE(PG8_SA(0, 1), cA + hstepA, voffA);
;         if (wr == 1) PG8_BAR;
;         PG8_WAIT_V(2); PG8_BAR;
;         PG8_STAGE(PG8_SB(1, 0), cB + kstep, voffB); PG8_STAGE(PG8_SA(1, 0), cA + kstep, voffA); PG8_STAGE(PG8_SB(1, 1), cB + hstepB + kstep, voffB);
;         PG8_WAIT_V(6); PG8_BAR;
.LBB0_601:
	v_lshrrev_b32_e32 v16, 1, v14
	v_and_b32_e32 v16, 24, v16
	v_and_b32_e32 v15, 15, v14
	v_lshlrev_b32_e32 v17, 1, v16
	v_lshlrev_b32_e32 v14, 2, v14
	s_sext_i32_i8 s12, s6
	v_lshl_or_b32 v142, s9, 6, v15
	v_lshl_or_b32 v15, v15, 6, v17
	s_lshl_b32 s6, s9, 13
	v_and_b32_e32 v14, 32, v14
	v_bitop3_b32 v17, v15, s6, v14 bitop3:0xde
	s_lshl_b32 s6, s8, 5
	s_and_b32 s14, s6, 0x60
	s_add_i32 m0, s21, 0x18000
	v_lshl_add_u64 v[6:7], v[6:7], 0, s[10:11]
	s_lshl_b32 s6, s14, 7
	s_waitcnt vmcnt(2)
	s_barrier
	global_load_lds_dwordx4 v[6:7], off
	v_lshl_add_u64 v[4:5], v[4:5], 0, s[10:11]
	s_add_i32 m0, s21, 0x1a000
	s_add_i32 s35, s21, 0x8000
	s_add_i32 s39, s21, 0xa000
	global_load_lds_dwordx4 v[4:5], off
	v_lshl_add_u64 v[0:1], v[0:1], 0, s[10:11]
	s_mov_b32 m0, s35
	s_add_u32 s8, s24, 0x40080
	global_load_lds_dwordx4 v[0:1], off
	v_lshl_add_u64 v[0:1], v[2:3], 0, s[10:11]
	s_mov_b32 m0, s39
	s_addc_u32 s9, s25, 0
	global_load_lds_dwordx4 v[0:1], off
	s_add_i32 m0, s21, 0x1c000
	v_lshl_add_u64 v[0:1], s[8:9], 0, v[208:209]
	global_load_lds_dwordx4 v208, s[8:9]
	v_lshl_add_u64 v[0:1], s[8:9], 0, v[128:129]
	s_add_i32 m0, s21, 0x1e000
	s_cmpk_lt_u32 s7, 0x100
	global_load_lds_dwordx4 v128, s[8:9]
	v_lshlrev_b32_e32 v0, 14, v12
	v_and_b32_e32 v0, 0xffff8000, v0
	v_lshl_add_u32 v0, v11, 11, v0
	v_and_b32_e32 v1, 1, v12
	v_lshl_or_b32 v0, v1, 6, v0
	v_lshl_add_u32 v134, v13, 1, v0
	v_lshlrev_b32_e32 v0, 14, v8
	v_and_b32_e32 v0, 0xffff8000, v0
	s_waitcnt vmcnt(6)
	v_lshl_add_u32 v0, v9, 11, v0
	v_and_b32_e32 v1, 1, v8
	v_lshl_or_b32 v0, v1, 6, v0
	v_bitop3_b32 v143, v15, s6, v14 bitop3:0xde
	s_cselect_b64 s[6:7], -1, 0
	v_or_b32_e32 v144, s14, v16
	v_mov_b32_e32 v135, v209
	v_lshl_add_u32 v136, v10, 1, v0
	v_mov_b32_e32 v137, v209
	s_mov_b32 s49, 0
	v_add_u32_e32 v145, 0, v17
	v_readlane_b32 s31, v252, 6
	s_barrier
	s_waitcnt vmcnt(0)
	s_branch .LBB0_604

; #define PG8_STAGE(bufoff, gbase, voff) do { _Pragma("unroll") for (int _i = 0; _i < 2; ++_i) \
;         __builtin_amdgcn_global_load_lds((const unsigned*)((const char*)(gbase) + (voff)[_i]), (PG8_LAS unsigned*)(lds + (bufoff) + ldsw + _i * 8192), 16, 0, 0); } while (0)
; #define PG8_LDA(dst, b, h) do { _Pragma("unroll") for (int m = 0; m < 4; ++m) _Pragma("unroll") for (int k = 0; k < 2; ++k) dst[m][k] = *(const PG8_LAS bf16x8*)(lds + PG8_SA(b, h) + aoff + m * 2048 + k * 1024); } while (0)
; #define PG8_LDB(dst, b, h) do { _Pragma("unroll") for (int n = 0; n < 2; ++n) _Pragma("unroll") for (int k = 0; k < 2; ++k) dst[n][k] = *(const PG8_LAS bf16x8*)(lds + PG8_SB(b, h) + boff + n * 2048 + k * 1024); } while (0)
; #define PG8_MMA(ai, bj, At, Bt) do { __builtin_amdgcn_s_setprio(1); _Pragma("unroll") for (int m = 0; m < 4; ++m) _Pragma("unroll") for (int n = 0; n < 2; ++n) _Pragma("unroll") for (int k = 0; k < 2; ++k) \
;         acc[ai][bj][m][n] = __builtin_amdgcn_mfma_f32_16x16x32_bf16(Bt[n][k], At[m][k], acc[ai][bj][m][n], 0, 0, 0); __builtin_amdgcn_s_setprio(0); } while (0)
; #define PG8_WAIT_V(n) asm volatile("s_waitcnt vmcnt(" #n ")" ::: "memory")
; #define PG8_WAIT_L(n) asm volatile("s_waitcnt lgkmcnt(" #n ")" ::: "memory")
; #define PG8_BAR __builtin_amdgcn_s_barrier()
; #define PG8_SCHED __builtin_amdgcn_sched_barrier(0)
; template <class Epi, class Sched, bool ALIGN_EPI = false, bool SP2 = false>
; __device__ __forceinline__ void gemm_phase(PG8_LAS unsigned char* lds, const Gemm g, const Sched& S, const Epi& E) {
;     ...
;             PG8_LDB(B0, 0, 0); PG8_LDB(B1, 0, 1); PG8_SCHED; PG8_LDA(At, 0, 0); PG8_STAGE(PG8_SA(1, 1), a1 + hstepA, voffA);
;             PG8_WAIT_V(8); PG8_WAIT_L(0); PG8_BAR; PG8_MMA(0, 0, At, B0); PG8_MMA(0, 1, At, B1); PG8_BAR; PG8_SCHED;
;             PG8_LDA(At, 0, 1); PG8_STAGE(PG8_SB(0, 0), b2, voffB); PG8_STAGE(PG8_SB(0, 1), b2 + hstepB, voffB); PG8_STAGE(PG8_SA(0, 0), a2, voffA);
;             PG8_WAIT_V(8); PG8_WAIT_L(0); PG8_BAR; PG8_MMA(1, 0, At, B0); PG8_MMA(1, 1, At, B1); PG8_BAR; PG8_SCHED;
.LBB0_607:
	s_add_u32 s22, s0, 0xfffc0080
	s_addc_u32 s23, s1, -1
	s_add_i32 s28, 0, 0x10000
	s_cmp_eq_u32 s51, 12
	s_cselect_b32 s25, s14, s23
	s_cselect_b32 s24, s15, s22
	s_cselect_b32 s23, s9, s50
	s_cselect_b32 s22, s38, s43
	s_add_i32 s29, 0, 0x14000
	v_add_u32_e32 v154, s28, v143
	v_add_u32_e32 v170, s29, v143
	ds_read_b128 v[138:141], v154
	ds_read_b128 v[146:149], v154 offset:1024
	ds_read_b128 v[150:153], v154 offset:2048
	ds_read_b128 v[154:157], v154 offset:3072
	ds_read_b128 v[158:161], v170
	ds_read_b128 v[162:165], v170 offset:1024
	ds_read_b128 v[166:169], v170 offset:2048
	ds_read_b128 v[170:173], v170 offset:3072
	s_add_i32 m0, s21, 0xc000
	ds_read_b128 v[174:177], v145
	ds_read_b128 v[178:181], v145 offset:1024
	ds_read_b128 v[182:185], v145 offset:2048
	ds_read_b128 v[186:189], v145 offset:3072
	ds_read_b128 v[190:193], v145 offset:4096
	ds_read_b128 v[194:197], v145 offset:5120
	ds_read_b128 v[198:201], v145 offset:6144
	ds_read_b128 v[202:205], v145 offset:7168
	global_load_lds_dwordx4 v134, s[0:1]
	s_add_i32 m0, s21, 0xe000
	s_nop 0
	global_load_lds_dwordx4 v136, s[0:1]
	s_waitcnt vmcnt(8)
	s_waitcnt lgkmcnt(0)
	s_barrier
	s_waitcnt lgkmcnt(0)
	v_mfma_f32_16x16x32_bf16 v[124:127], v[138:141], v[174:177], v[124:127]
	v_mfma_f32_16x16x32_bf16 v[120:123], v[150:153], v[174:177], v[120:123]
	v_mfma_f32_16x16x32_bf16 v[108:111], v[138:141], v[182:185], v[108:111]
	v_mfma_f32_16x16x32_bf16 v[104:107], v[150:153], v[182:185], v[104:107]
	v_mfma_f32_16x16x32_bf16 v[92:95], v[138:141], v[190:193], v[92:95]
	v_mfma_f32_16x16x32_bf16 v[88:91], v[150:153], v[190:193], v[88:91]
	v_mfma_f32_16x16x32_bf16 v[76:79], v[138:141], v[198:201], v[76:79]
	v_mfma_f32_16x16x32_bf16 v[72:75], v[150:153], v[198:201], v[72:75]
	v_mfma_f32_16x16x32_bf16 v[124:127], v[146:149], v[178:181], v[124:127]
	v_mfma_f32_16x16x32_bf16 v[120:123], v[154:157], v[178:181], v[120:123]
	v_mfma_f32_16x16x32_bf16 v[108:111], v[146:149], v[186:189], v[108:111]
	v_mfma_f32_16x16x32_bf16 v[104:107], v[154:157], v[186:189], v[104:107]
	v_mfma_f32_16x16x32_bf16 v[92:95], v[146:149], v[194:197], v[92:95]
	v_mfma_f32_16x16x32_bf16 v[88:91], v[154:157], v[194:197], v[88:91]
	v_mfma_f32_16x16x32_bf16 v[76:79], v[146:149], v[202:205], v[76:79]
	v_mfma_f32_16x16x32_bf16 v[72:75], v[154:157], v[202:205], v[72:75]
	v_mfma_f32_16x16x32_bf16 v[116:119], v[158:161], v[174:177], v[116:119]
	v_mfma_f32_16x16x32_bf16 v[112:115], v[166:169], v[174:177], v[112:115]
	v_mfma_f32_16x16x32_bf16 v[100:103], v[158:161], v[182:185], v[100:103]
	v_mfma_f32_16x16x32_bf16 v[96:99], v[166:169], v[182:185], v[96:99]
	v_mfma_f32_16x16x32_bf16 v[84:87], v[158:161], v[190:193], v[84:87]
	v_mfma_f32_16x16x32_bf16 v[80:83], v[166:169], v[190:193], v[80:83]
	v_mfma_f32_16x16x32_bf16 v[68:71], v[158:161], v[198:201], v[68:71]
	v_mfma_f32_16x16x32_bf16 v[64:67], v[166:169], v[198:201], v[64:67]
	v_mfma_f32_16x16x32_bf16 v[116:119], v[162:165], v[178:181], v[116:119]
	v_mfma_f32_16x16x32_bf16 v[112:115], v[170:173], v[178:181], v[112:115]
	v_mfma_f32_16x16x32_bf16 v[100:103], v[162:165], v[186:189], v[100:103]
	v_mfma_f32_16x16x32_bf16 v[96:99], v[170:173], v[186:189], v[96:99]
	v_mfma_f32_16x16x32_bf16 v[84:87], v[162:165], v[194:197], v[84:87]
	v_mfma_f32_16x16x32_bf16 v[80:83], v[170:173], v[194:197], v[80:83]
	v_mfma_f32_16x16x32_bf16 v[68:71], v[162:165], v[202:205], v[68:71]
	v_mfma_f32_16x16x32_bf16 v[64:67], v[170:173], v[202:205], v[64:67]
	s_barrier
	s_add_i32 s28, s28, s26
	v_lshl_add_u64 v[206:207], s[22:23], 0, v[208:209]
	s_mov_b32 m0, s28
	ds_read_b128 v[174:177], v145 offset:16384
	ds_read_b128 v[178:181], v145 offset:17408
	ds_read_b128 v[182:185], v145 offset:18432
	ds_read_b128 v[186:189], v145 offset:19456
	ds_read_b128 v[190:193], v145 offset:20480
	ds_read_b128 v[194:197], v145 offset:21504
	ds_read_b128 v[198:201], v145 offset:22528
	ds_read_b128 v[202:205], v145 offset:23552
	global_load_lds_dwordx4 v208, s[22:23]
	s_add_i32 m0, s28, 0x2000
	s_add_u32 s52, s22, 0x40000
	v_lshl_add_u64 v[210:211], s[22:23], 0, v[128:129]
	s_addc_u32 s53, s23, 0
	s_add_i32 s28, s29, s26
	global_load_lds_dwordx4 v128, s[22:23]
	s_mov_b32 m0, s28
	v_lshl_add_u64 v[222:223], s[24:25], 0, v[130:131]
	global_load_lds_dwordx4 v208, s[52:53]
	s_add_i32 m0, s28, 0x2000
	s_nop 0
	global_load_lds_dwordx4 v128, s[52:53]
	v_lshl_add_u64 v[212:213], s[24:25], 0, v[132:133]
	s_mov_b32 m0, s21
	s_nop 0
	global_load_lds_dwordx4 v132, s[24:25]
	s_mov_b32 m0, s18
	s_nop 0
	global_load_lds_dwordx4 v130, s[24:25]
	s_waitcnt vmcnt(8)
	s_waitcnt lgkmcnt(0)
	s_barrier
; #define PG8_STAGE(bufoff, gbase, voff) do { _Pragma("unroll") for (int _i = 0; _i < 2; ++_i) \
;         __builtin_amdgcn_global_load_lds((const unsigned*)((const char*)(gbase) + (voff)[_i]), (PG8_LAS unsigned*)(lds + (bufoff) + ldsw + _i * 8192), 16, 0, 0); } while (0)
; #define PG8_LDA(dst, b, h) do { _Pragma("unroll") for (int m = 0; m < 4; ++m) _Pragma("unroll") for (int k = 0; k < 2; ++k) dst[m][k] = *(const PG8_LAS bf16x8*)(lds + PG8_SA(b, h) + aoff + m * 2048 + k * 1024); } while (0)
; #define PG8_LDB(dst, b, h) do { _Pragma("unroll") for (int n = 0; n < 2; ++n) _Pragma("unroll") for (int k = 0; k < 2; ++k) dst[n][k] = *(const PG8_LAS bf16x8*)(lds + PG8_SB(b, h) + boff + n * 2048 + k * 1024); } while (0)
; #define PG8_MMA(ai, bj, At, Bt) do { __builtin_amdgcn_s_setprio(1); _Pragma("unroll") for (int m = 0; m < 4; ++m) _Pragma("unroll") for (int n = 0; n < 2; ++n) _Pragma("unroll") for (int k = 0; k < 2; ++k) \
;         acc[ai][bj][m][n] = __builtin_amdgcn_mfma_f32_16x16x32_bf16(Bt[n][k], At[m][k], acc[ai][bj][m][n], 0, 0, 0); __builtin_amdgcn_s_setprio(0); } while (0)
; #define PG8_WAIT_V(n) asm volatile("s_waitcnt vmcnt(" #n ")" ::: "memory")
; #define PG8_WAIT_L(n) asm volatile("s_waitcnt lgkmcnt(" #n ")" ::: "memory")
; #define PG8_BAR __builtin_amdgcn_s_barrier()
; #define PG8_SCHED __builtin_amdgcn_sched_barrier(0)
; template <class Epi, class Sched, bool ALIGN_EPI = false, bool SP2 = false>
; __device__ __forceinline__ void gemm_phase(PG8_LAS unsigned char* lds, const Gemm g, const Sched& S, const Epi& E) {
;     ...
;             PG8_WAIT_V(8); PG8_WAIT_L(0); PG8_BAR; PG8_MMA(1, 0, At, B0); PG8_MMA(1, 1, At, B1); PG8_BAR; PG8_SCHED;
;             PG8_LDB(B0, 1, 0); PG8_LDB(B1, 1, 1); PG8_SCHED; PG8_LDA(At, 1, 0); PG8_STAGE(PG8_SA(0, 1), a2 + hstepA, voffA);
;             PG8_WAIT_V(8); PG8_WAIT_L(0); PG8_BAR; PG8_MMA(0, 0, At, B0); PG8_MMA(0, 1, At, B1); PG8_BAR; PG8_SCHED;
	s_waitcnt lgkmcnt(0)
	v_mfma_f32_16x16x32_bf16 v[60:63], v[138:141], v[174:177], v[60:63]
	v_mfma_f32_16x16x32_bf16 v[56:59], v[150:153], v[174:177], v[56:59]
	v_mfma_f32_16x16x32_bf16 v[44:47], v[138:141], v[182:185], v[44:47]
	v_mfma_f32_16x16x32_bf16 v[40:43], v[150:153], v[182:185], v[40:43]
	v_mfma_f32_16x16x32_bf16 v[28:31], v[138:141], v[190:193], v[28:31]
	v_mfma_f32_16x16x32_bf16 v[24:27], v[150:153], v[190:193], v[24:27]
	v_mfma_f32_16x16x32_bf16 v[12:15], v[138:141], v[198:201], v[12:15]
	v_mfma_f32_16x16x32_bf16 v[8:11], v[150:153], v[198:201], v[8:11]
	v_mfma_f32_16x16x32_bf16 v[60:63], v[146:149], v[178:181], v[60:63]
	v_mfma_f32_16x16x32_bf16 v[56:59], v[154:157], v[178:181], v[56:59]
	v_mfma_f32_16x16x32_bf16 v[44:47], v[146:149], v[186:189], v[44:47]
	v_mfma_f32_16x16x32_bf16 v[40:43], v[154:157], v[186:189], v[40:43]
	v_mfma_f32_16x16x32_bf16 v[28:31], v[146:149], v[194:197], v[28:31]
	v_mfma_f32_16x16x32_bf16 v[24:27], v[154:157], v[194:197], v[24:27]
	v_mfma_f32_16x16x32_bf16 v[12:15], v[146:149], v[202:205], v[12:15]
	v_mfma_f32_16x16x32_bf16 v[8:11], v[154:157], v[202:205], v[8:11]
	v_mfma_f32_16x16x32_bf16 v[52:55], v[158:161], v[174:177], v[52:55]
	v_mfma_f32_16x16x32_bf16 v[48:51], v[166:169], v[174:177], v[48:51]
	v_mfma_f32_16x16x32_bf16 v[36:39], v[158:161], v[182:185], v[36:39]
	v_mfma_f32_16x16x32_bf16 v[32:35], v[166:169], v[182:185], v[32:35]
	v_mfma_f32_16x16x32_bf16 v[20:23], v[158:161], v[190:193], v[20:23]
	v_mfma_f32_16x16x32_bf16 v[16:19], v[166:169], v[190:193], v[16:19]
	v_mfma_f32_16x16x32_bf16 v[4:7], v[158:161], v[198:201], v[4:7]
	v_mfma_f32_16x16x32_bf16 v[0:3], v[166:169], v[198:201], v[0:3]
	v_mfma_f32_16x16x32_bf16 v[52:55], v[162:165], v[178:181], v[52:55]
	v_mfma_f32_16x16x32_bf16 v[48:51], v[170:173], v[178:181], v[48:51]
	v_mfma_f32_16x16x32_bf16 v[36:39], v[162:165], v[186:189], v[36:39]
	v_mfma_f32_16x16x32_bf16 v[32:35], v[170:173], v[186:189], v[32:35]
	v_mfma_f32_16x16x32_bf16 v[20:23], v[162:165], v[194:197], v[20:23]
	v_mfma_f32_16x16x32_bf16 v[16:19], v[170:173], v[194:197], v[16:19]
	v_mfma_f32_16x16x32_bf16 v[4:7], v[162:165], v[202:205], v[4:7]
	v_mfma_f32_16x16x32_bf16 v[0:3], v[170:173], v[202:205], v[0:3]
	s_barrier
	s_add_i32 s28, 0, 0x18000
	s_add_i32 s29, 0, 0x1c000
	v_add_u32_e32 v154, s28, v143
	v_add_u32_e32 v170, s29, v143
	ds_read_b128 v[138:141], v154
	ds_read_b128 v[146:149], v154 offset:1024
	ds_read_b128 v[150:153], v154 offset:2048
	ds_read_b128 v[154:157], v154 offset:3072
	ds_read_b128 v[158:161], v170
	ds_read_b128 v[162:165], v170 offset:1024
	ds_read_b128 v[166:169], v170 offset:2048
	ds_read_b128 v[170:173], v170 offset:3072
	s_add_u32 s24, s24, 0x40000
	s_addc_u32 s25, s25, 0
	s_mov_b32 m0, s19
	ds_read_b128 v[174:177], v145 offset:32768
	ds_read_b128 v[178:181], v145 offset:33792
	ds_read_b128 v[182:185], v145 offset:34816
	ds_read_b128 v[186:189], v145 offset:35840
	ds_read_b128 v[190:193], v145 offset:36864
	ds_read_b128 v[194:197], v145 offset:37888
	ds_read_b128 v[198:201], v145 offset:38912
	ds_read_b128 v[202:205], v145 offset:39936
	global_load_lds_dwordx4 v132, s[24:25]
	v_lshl_add_u64 v[224:225], s[24:25], 0, v[130:131]
	s_mov_b32 m0, s34
	s_nop 0
	global_load_lds_dwordx4 v130, s[24:25]
	s_waitcnt vmcnt(8)
	s_waitcnt lgkmcnt(0)
	s_barrier
	s_waitcnt lgkmcnt(0)
	v_mfma_f32_16x16x32_bf16 v[124:127], v[138:141], v[174:177], v[124:127]
	v_mfma_f32_16x16x32_bf16 v[120:123], v[150:153], v[174:177], v[120:123]
	v_mfma_f32_16x16x32_bf16 v[108:111], v[138:141], v[182:185], v[108:111]
	v_mfma_f32_16x16x32_bf16 v[104:107], v[150:153], v[182:185], v[104:107]
	v_mfma_f32_16x16x32_bf16 v[92:95], v[138:141], v[190:193], v[92:95]
	v_mfma_f32_16x16x32_bf16 v[88:91], v[150:153], v[190:193], v[88:91]
	v_mfma_f32_16x16x32_bf16 v[76:79], v[138:141], v[198:201], v[76:79]
	v_mfma_f32_16x16x32_bf16 v[72:75], v[150:153], v[198:201], v[72:75]
	v_mfma_f32_16x16x32_bf16 v[124:127], v[146:149], v[178:181], v[124:127]
	v_mfma_f32_16x16x32_bf16 v[120:123], v[154:157], v[178:181], v[120:123]
	v_mfma_f32_16x16x32_bf16 v[108:111], v[146:149], v[186:189], v[108:111]
	v_mfma_f32_16x16x32_bf16 v[104:107], v[154:157], v[186:189], v[104:107]
	v_mfma_f32_16x16x32_bf16 v[92:95], v[146:149], v[194:197], v[92:95]
	v_mfma_f32_16x16x32_bf16 v[88:91], v[154:157], v[194:197], v[88:91]
	v_mfma_f32_16x16x32_bf16 v[76:79], v[146:149], v[202:205], v[76:79]
	v_mfma_f32_16x16x32_bf16 v[72:75], v[154:157], v[202:205], v[72:75]
	v_mfma_f32_16x16x32_bf16 v[116:119], v[158:161], v[174:177], v[116:119]
	v_mfma_f32_16x16x32_bf16 v[112:115], v[166:169], v[174:177], v[112:115]
	v_mfma_f32_16x16x32_bf16 v[100:103], v[158:161], v[182:185], v[100:103]
	v_mfma_f32_16x16x32_bf16 v[96:99], v[166:169], v[182:185], v[96:99]
	v_mfma_f32_16x16x32_bf16 v[84:87], v[158:161], v[190:193], v[84:87]
	v_mfma_f32_16x16x32_bf16 v[80:83], v[166:169], v[190:193], v[80:83]
	v_mfma_f32_16x16x32_bf16 v[68:71], v[158:161], v[198:201], v[68:71]
	v_mfma_f32_16x16x32_bf16 v[64:67], v[166:169], v[198:201], v[64:67]
	v_mfma_f32_16x16x32_bf16 v[116:119], v[162:165], v[178:181], v[116:119]
	v_mfma_f32_16x16x32_bf16 v[112:115], v[170:173], v[178:181], v[112:115]
	v_mfma_f32_16x16x32_bf16 v[100:103], v[162:165], v[186:189], v[100:103]
	v_mfma_f32_16x16x32_bf16 v[96:99], v[170:173], v[186:189], v[96:99]
	v_mfma_f32_16x16x32_bf16 v[84:87], v[162:165], v[194:197], v[84:87]
	v_mfma_f32_16x16x32_bf16 v[80:83], v[170:173], v[194:197], v[80:83]
	v_mfma_f32_16x16x32_bf16 v[68:71], v[162:165], v[202:205], v[68:71]
	v_mfma_f32_16x16x32_bf16 v[64:67], v[170:173], v[202:205], v[64:67]
	s_barrier
; #define PG8_STAGE(bufoff, gbase, voff) do { _Pragma("unroll") for (int _i = 0; _i < 2; ++_i) \
;         __builtin_amdgcn_global_load_lds((const unsigned*)((const char*)(gbase) + (voff)[_i]), (PG8_LAS unsigned*)(lds + (bufoff) + ldsw + _i * 8192), 16, 0, 0); } while (0)
; #define PG8_LDA(dst, b, h) do { _Pragma("unroll") for (int m = 0; m < 4; ++m) _Pragma("unroll") for (int k = 0; k < 2; ++k) dst[m][k] = *(const PG8_LAS bf16x8*)(lds + PG8_SA(b, h) + aoff + m * 2048 + k * 1024); } while (0)
; #define PG8_MMA(ai, bj, At, Bt) do { __builtin_amdgcn_s_setprio(1); _Pragma("unroll") for (int m = 0; m < 4; ++m) _Pragma("unroll") for (int n = 0; n < 2; ++n) _Pragma("unroll") for (int k = 0; k < 2; ++k) \
;         acc[ai][bj][m][n] = __builtin_amdgcn_mfma_f32_16x16x32_bf16(Bt[n][k], At[m][k], acc[ai][bj][m][n], 0, 0, 0); __builtin_amdgcn_s_setprio(0); } while (0)
; #define PG8_WAIT_V(n) asm volatile("s_waitcnt vmcnt(" #n ")" ::: "memory")
; #define PG8_WAIT_L(n) asm volatile("s_waitcnt lgkmcnt(" #n ")" ::: "memory")
; #define PG8_BAR __builtin_amdgcn_s_barrier()
; #define PG8_SCHED __builtin_amdgcn_sched_barrier(0)
; template <class Epi, class Sched, bool ALIGN_EPI = false, bool SP2 = false>
; __device__ __forceinline__ void gemm_phase(PG8_LAS unsigned char* lds, const Gemm g, const Sched& S, const Epi& E) {
;     ...
;             PG8_LDA(At, 1, 1); PG8_STAGE(PG8_SB(1, 0), b3, voffB); PG8_STAGE(PG8_SB(1, 1), b3 + hstepB, voffB); PG8_STAGE(PG8_SA(1, 0), a3, voffA);
;             PG8_WAIT_V(8); PG8_WAIT_L(0); PG8_BAR; PG8_MMA(1, 0, At, B0); PG8_MMA(1, 1, At, B1); PG8_BAR; PG8_SCHED;
	s_add_i32 s24, s28, s26
	v_lshl_add_u64 v[206:207], v[206:207], 0, s[10:11]
	s_mov_b32 m0, s24
	ds_read_b128 v[174:177], v145 offset:49152
	ds_read_b128 v[178:181], v145 offset:50176
	ds_read_b128 v[182:185], v145 offset:51200
	ds_read_b128 v[186:189], v145 offset:52224
	ds_read_b128 v[190:193], v145 offset:53248
	ds_read_b128 v[194:197], v145 offset:54272
	ds_read_b128 v[198:201], v145 offset:55296
	ds_read_b128 v[202:205], v145 offset:56320
	global_load_lds_dwordx4 v[206:207], off
	s_add_i32 m0, s24, 0x2000
	s_add_u32 s22, s22, 0x40080
	v_lshl_add_u64 v[206:207], v[210:211], 0, s[10:11]
	s_addc_u32 s23, s23, 0
	s_add_i32 s24, s29, s26
	global_load_lds_dwordx4 v[206:207], off
	s_mov_b32 m0, s24
	s_nop 0
	global_load_lds_dwordx4 v208, s[22:23]
	s_add_i32 m0, s24, 0x2000
	s_nop 0
	global_load_lds_dwordx4 v128, s[22:23]
	v_lshl_add_u64 v[206:207], v[212:213], 0, s[10:11]
	s_mov_b32 m0, s35
	s_nop 0
	global_load_lds_dwordx4 v[206:207], off
	v_lshl_add_u64 v[206:207], v[222:223], 0, s[10:11]
	s_mov_b32 m0, s39
	s_nop 0
	global_load_lds_dwordx4 v[206:207], off
	s_waitcnt vmcnt(8)
	s_waitcnt lgkmcnt(0)
	s_barrier
	s_waitcnt lgkmcnt(0)
	v_mfma_f32_16x16x32_bf16 v[60:63], v[138:141], v[174:177], v[60:63]
	v_mfma_f32_16x16x32_bf16 v[56:59], v[150:153], v[174:177], v[56:59]
	v_mfma_f32_16x16x32_bf16 v[44:47], v[138:141], v[182:185], v[44:47]
	v_mfma_f32_16x16x32_bf16 v[40:43], v[150:153], v[182:185], v[40:43]
	v_mfma_f32_16x16x32_bf16 v[28:31], v[138:141], v[190:193], v[28:31]
	v_mfma_f32_16x16x32_bf16 v[24:27], v[150:153], v[190:193], v[24:27]
	v_mfma_f32_16x16x32_bf16 v[12:15], v[138:141], v[198:201], v[12:15]
	v_mfma_f32_16x16x32_bf16 v[8:11], v[150:153], v[198:201], v[8:11]
	v_mfma_f32_16x16x32_bf16 v[60:63], v[146:149], v[178:181], v[60:63]
	v_mfma_f32_16x16x32_bf16 v[56:59], v[154:157], v[178:181], v[56:59]
	v_mfma_f32_16x16x32_bf16 v[44:47], v[146:149], v[186:189], v[44:47]
	v_mfma_f32_16x16x32_bf16 v[40:43], v[154:157], v[186:189], v[40:43]
	v_mfma_f32_16x16x32_bf16 v[28:31], v[146:149], v[194:197], v[28:31]
	v_mfma_f32_16x16x32_bf16 v[24:27], v[154:157], v[194:197], v[24:27]
	v_mfma_f32_16x16x32_bf16 v[12:15], v[146:149], v[202:205], v[12:15]
	v_mfma_f32_16x16x32_bf16 v[8:11], v[154:157], v[202:205], v[8:11]
	v_mfma_f32_16x16x32_bf16 v[52:55], v[158:161], v[174:177], v[52:55]
	v_mfma_f32_16x16x32_bf16 v[48:51], v[166:169], v[174:177], v[48:51]
	v_mfma_f32_16x16x32_bf16 v[36:39], v[158:161], v[182:185], v[36:39]
	v_mfma_f32_16x16x32_bf16 v[32:35], v[166:169], v[182:185], v[32:35]
	v_mfma_f32_16x16x32_bf16 v[20:23], v[158:161], v[190:193], v[20:23]
	v_mfma_f32_16x16x32_bf16 v[16:19], v[166:169], v[190:193], v[16:19]
	v_mfma_f32_16x16x32_bf16 v[4:7], v[158:161], v[198:201], v[4:7]
	v_mfma_f32_16x16x32_bf16 v[0:3], v[166:169], v[198:201], v[0:3]
	v_mfma_f32_16x16x32_bf16 v[52:55], v[162:165], v[178:181], v[52:55]
	v_mfma_f32_16x16x32_bf16 v[48:51], v[170:173], v[178:181], v[48:51]
	v_mfma_f32_16x16x32_bf16 v[36:39], v[162:165], v[186:189], v[36:39]
	v_mfma_f32_16x16x32_bf16 v[32:35], v[170:173], v[186:189], v[32:35]
	v_mfma_f32_16x16x32_bf16 v[20:23], v[162:165], v[194:197], v[20:23]
	v_mfma_f32_16x16x32_bf16 v[16:19], v[170:173], v[194:197], v[16:19]
	v_mfma_f32_16x16x32_bf16 v[4:7], v[162:165], v[202:205], v[4:7]
	v_mfma_f32_16x16x32_bf16 v[0:3], v[170:173], v[202:205], v[0:3]
	s_barrier
	s_add_i32 s51, s51, 2
	s_add_u32 s0, s0, 0x100
	s_addc_u32 s1, s1, 0
	s_add_u32 s43, s43, 0x100
	s_addc_u32 s50, s50, 0
	s_cmp_gt_u32 s51, 13
	s_cbranch_scc0 .LBB0_607
	s_and_b64 vcc, exec, s[6:7]
	s_cbranch_vccz .LBB0_610
	s_barrier

; #define PG8_STAGE(bufoff, gbase, voff) do { _Pragma("unroll") for (int _i = 0; _i < 2; ++_i) \
;         __builtin_amdgcn_global_load_lds((const unsigned*)((const char*)(gbase) + (voff)[_i]), (PG8_LAS unsigned*)(lds + (bufoff) + ldsw + _i * 8192), 16, 0, 0); } while (0)
; #define PG8_WAIT_V(n) asm volatile("s_waitcnt vmcnt(" #n ")" ::: "memory")
; #define PG8_BAR __builtin_amdgcn_s_barrier()
; template <class Epi, class Sched, bool ALIGN_EPI = false, bool SP2 = false>
; __device__ __forceinline__ void gemm_phase(PG8_LAS unsigned char* lds, const Gemm g, const Sched& S, const Epi& E) {
;     ...
;     for (int i = 0; i < 2; ++i) { int R, C; stage_rc(tid * 16 + i * 8192, R, C); const int Rb = Epi::PERM ? ((R & ~31) + perm32(R & 31)) : R;
;         voffA[i] = (unsigned)(R * g.lda + C) * 2u; voffB[i] = (unsigned)(Rb * g.ldb + C) * 2u; }
;     const size_t kstep = (size_t)(BK * 2);
;     const size_t hstepA = (size_t)HALF * g.lda * 2, hstepB = (size_t)HALF * g.ldb * 2;
;     const size_t tstepA = 2 * hstepA, tstepB = 2 * hstepB;
;     const unsigned ldsw = (unsigned)wid * 1024u;
;     const int aoff = lds_byte(wr * 64 + fr, fq * 8), boff = lds_byte(wc * 32 + fr, fq * 8);
;     ...
;         PG8_STAGE(PG8_SB(0, 0), cB, voffB); PG8_STAGE(PG8_SB(0, 1), cB + hstepB, voffB); PG8_STAGE(PG8_SA(0, 0), cA, voffA); PG8_STAGE(PG8_SA(0, 1), cA + hstepA, voffA);
;         if (wr == 1) PG8_BAR;
;         PG8_WAIT_V(2); PG8_BAR;
;         PG8_STAGE(PG8_SB(1, 0), cB + kstep, voffB); PG8_STAGE(PG8_SA(1, 0), cA + kstep, voffA); PG8_STAGE(PG8_SB(1, 1), cB + hstepB + kstep, voffB);
;         PG8_WAIT_V(6); PG8_BAR;
.LBB0_678:
	s_lshl_b64 s[8:9], s[26:27], 26
	v_readlane_b32 s15, v252, 6
	s_add_u32 s8, s15, s8
	v_readlane_b32 s15, v252, 7
	v_lshrrev_b32_e32 v18, 1, v9
	s_addc_u32 s9, s15, s9
	v_and_b32_e32 v18, 24, v18
	s_cmp_lg_u32 s26, 0
	v_and_b32_e32 v17, 15, v9
	v_lshlrev_b32_e32 v19, 1, v18
	v_lshlrev_b32_e32 v9, 2, v9
	s_cselect_b64 s[42:43], -1, 0
	v_lshl_or_b32 v210, s4, 6, v17
	v_lshl_or_b32 v17, v17, 6, v19
	s_lshl_b32 s4, s4, 13
	v_and_b32_e32 v9, 32, v9
	v_bitop3_b32 v19, v17, s4, v9 bitop3:0xde
	s_lshl_b32 s4, s5, 5
	s_and_b32 s15, s4, 0x60
	s_add_i32 m0, s53, 0x18000
	v_lshl_add_u64 v[6:7], v[6:7], 0, s[10:11]
	s_lshl_b32 s4, s15, 7
	s_waitcnt vmcnt(2)
	s_barrier
	global_load_lds_dwordx4 v[6:7], off
	v_lshl_add_u64 v[4:5], v[4:5], 0, s[10:11]
	s_add_i32 m0, s53, 0x1a000
	s_add_i32 s61, s53, 0x8000
	s_add_i32 s62, s53, 0xa000
	v_bitop3_b32 v211, v17, s4, v9 bitop3:0xde
	global_load_lds_dwordx4 v[4:5], off
	v_lshl_add_u64 v[0:1], v[0:1], 0, s[10:11]
	s_mov_b32 m0, s61
	s_add_u32 s4, s20, 0x20080
	global_load_lds_dwordx4 v[0:1], off
	v_lshl_add_u64 v[0:1], v[2:3], 0, s[10:11]
	s_mov_b32 m0, s62
	s_addc_u32 s5, s21, 0
	global_load_lds_dwordx4 v[0:1], off
	s_add_i32 m0, s53, 0x1c000
	v_lshl_add_u64 v[0:1], s[4:5], 0, v[208:209]
	global_load_lds_dwordx4 v208, s[4:5]
	v_lshl_add_u64 v[0:1], s[4:5], 0, v[196:197]
	s_add_i32 m0, s53, 0x1e000
	v_or_b32_e32 v230, s15, v18
	global_load_lds_dwordx4 v196, s[4:5]
	s_movk_i32 s15, 0x600
	s_cmpk_lt_u32 s14, 0x100
	v_lshrrev_b32_e32 v1, 1, v8
	v_mul_lo_u32 v0, v11, s15
	s_movk_i32 s14, 0x6000
	v_mad_u64_u32 v[0:1], s[4:5], v1, s14, v[0:1]
	v_or_b32_e32 v0, v0, v10
	v_add_lshl_u32 v0, v0, v12, 1
	v_mov_b32_e32 v1, v209
	s_mov_b64 s[18:19], 0x60080
	v_lshl_add_u64 v[198:199], v[0:1], 0, s[18:19]
	v_lshrrev_b32_e32 v1, 1, v13
	v_mul_lo_u32 v0, v15, s15
	v_mad_u64_u32 v[0:1], s[4:5], v1, s14, v[0:1]
	s_waitcnt vmcnt(6)
	v_or_b32_e32 v0, v0, v14
	v_add_lshl_u32 v0, v0, v16, 1
	v_mov_b32_e32 v1, v209
	s_mov_b32 s60, 0
	s_cselect_b64 s[44:45], -1, 0
	s_ashr_i32 s63, s2, 31
	v_lshl_add_u64 v[200:201], v[0:1], 0, s[18:19]
	v_add_u32_e32 v231, 0, v19
	s_barrier
	s_branch .LBB0_681

; #define PG8_STAGE(bufoff, gbase, voff) do { _Pragma("unroll") for (int _i = 0; _i < 2; ++_i) \
;         __builtin_amdgcn_global_load_lds((const unsigned*)((const char*)(gbase) + (voff)[_i]), (PG8_LAS unsigned*)(lds + (bufoff) + ldsw + _i * 8192), 16, 0, 0); } while (0)
; #define PG8_LDA(dst, b, h) do { _Pragma("unroll") for (int m = 0; m < 4; ++m) _Pragma("unroll") for (int k = 0; k < 2; ++k) dst[m][k] = *(const PG8_LAS bf16x8*)(lds + PG8_SA(b, h) + aoff + m * 2048 + k * 1024); } while (0)
; #define PG8_LDB(dst, b, h) do { _Pragma("unroll") for (int n = 0; n < 2; ++n) _Pragma("unroll") for (int k = 0; k < 2; ++k) dst[n][k] = *(const PG8_LAS bf16x8*)(lds + PG8_SB(b, h) + boff + n * 2048 + k * 1024); } while (0)
; #define PG8_MMA(ai, bj, At, Bt) do { __builtin_amdgcn_s_setprio(1); _Pragma("unroll") for (int m = 0; m < 4; ++m) _Pragma("unroll") for (int n = 0; n < 2; ++n) _Pragma("unroll") for (int k = 0; k < 2; ++k) \
;         acc[ai][bj][m][n] = __builtin_amdgcn_mfma_f32_16x16x32_bf16(Bt[n][k], At[m][k], acc[ai][bj][m][n], 0, 0, 0); __builtin_amdgcn_s_setprio(0); } while (0)
; #define PG8_WAIT_V(n) asm volatile("s_waitcnt vmcnt(" #n ")" ::: "memory")
; #define PG8_WAIT_L(n) asm volatile("s_waitcnt lgkmcnt(" #n ")" ::: "memory")
; #define PG8_BAR __builtin_amdgcn_s_barrier()
; #define PG8_SCHED __builtin_amdgcn_sched_barrier(0)
; template <class Epi, class Sched, bool ALIGN_EPI = false, bool SP2 = false>
; __device__ __forceinline__ void gemm_phase(PG8_LAS unsigned char* lds, const Gemm g, const Sched& S, const Epi& E) {
;     ...
;             PG8_LDB(B0, 0, 0); PG8_LDB(B1, 0, 1); PG8_SCHED; PG8_LDA(At, 0, 0); PG8_STAGE(PG8_SA(1, 1), a1 + hstepA, voffA);
;             PG8_WAIT_V(8); PG8_WAIT_L(0); PG8_BAR; PG8_MMA(0, 0, At, B0); PG8_MMA(0, 1, At, B1); PG8_BAR; PG8_SCHED;
;             PG8_LDA(At, 0, 1); PG8_STAGE(PG8_SB(0, 0), b2, voffB); PG8_STAGE(PG8_SB(0, 1), b2 + hstepB, voffB); PG8_STAGE(PG8_SA(0, 0), a2, voffA);
;             PG8_WAIT_V(8); PG8_WAIT_L(0); PG8_BAR; PG8_MMA(1, 0, At, B0); PG8_MMA(1, 1, At, B1); PG8_BAR; PG8_SCHED;
.LBB0_690:
	s_add_u32 s4, s0, 0x100
	s_addc_u32 s5, s1, 0
	s_add_i32 s28, 0, 0x10000
	s_cmp_eq_u32 s34, 4
	s_cselect_b32 s23, s49, s5
	s_cselect_b32 s22, s48, s4
	s_cselect_b32 s21, s14, s19
	s_cselect_b32 s20, s15, s18
	s_add_i32 s29, 0, 0x14000
	v_add_u32_e32 v140, s28, v211
	v_add_u32_e32 v156, s29, v211
	ds_read_b128 v[128:131], v140
	ds_read_b128 v[132:135], v140 offset:1024
	ds_read_b128 v[136:139], v140 offset:2048
	ds_read_b128 v[140:143], v140 offset:3072
	ds_read_b128 v[144:147], v156
	ds_read_b128 v[148:151], v156 offset:1024
	ds_read_b128 v[152:155], v156 offset:2048
	ds_read_b128 v[156:159], v156 offset:3072
	v_lshl_add_u64 v[202:203], s[0:1], 0, v[198:199]
	s_add_i32 m0, s53, 0xc000
	ds_read_b128 v[160:163], v231
	ds_read_b128 v[164:167], v231 offset:1024
	ds_read_b128 v[168:171], v231 offset:2048
	ds_read_b128 v[172:175], v231 offset:3072
	ds_read_b128 v[176:179], v231 offset:4096
	ds_read_b128 v[180:183], v231 offset:5120
	ds_read_b128 v[184:187], v231 offset:6144
	ds_read_b128 v[188:191], v231 offset:7168
	global_load_lds_dwordx4 v[202:203], off
	v_lshl_add_u64 v[202:203], s[0:1], 0, v[200:201]
	s_add_i32 m0, s53, 0xe000
	s_nop 0
	global_load_lds_dwordx4 v[202:203], off
	s_waitcnt vmcnt(8)
	s_waitcnt lgkmcnt(0)
	s_barrier
	s_waitcnt lgkmcnt(0)
	v_mfma_f32_16x16x32_bf16 v[124:127], v[128:131], v[160:163], v[124:127]
	v_mfma_f32_16x16x32_bf16 v[120:123], v[136:139], v[160:163], v[120:123]
	v_mfma_f32_16x16x32_bf16 v[112:115], v[128:131], v[168:171], v[112:115]
	v_mfma_f32_16x16x32_bf16 v[104:107], v[136:139], v[168:171], v[104:107]
	v_mfma_f32_16x16x32_bf16 v[96:99], v[128:131], v[176:179], v[96:99]
	v_mfma_f32_16x16x32_bf16 v[88:91], v[136:139], v[176:179], v[88:91]
	v_mfma_f32_16x16x32_bf16 v[80:83], v[128:131], v[184:187], v[80:83]
	v_mfma_f32_16x16x32_bf16 v[72:75], v[136:139], v[184:187], v[72:75]
	v_mfma_f32_16x16x32_bf16 v[124:127], v[132:135], v[164:167], v[124:127]
	v_mfma_f32_16x16x32_bf16 v[120:123], v[140:143], v[164:167], v[120:123]
	v_mfma_f32_16x16x32_bf16 v[112:115], v[132:135], v[172:175], v[112:115]
	v_mfma_f32_16x16x32_bf16 v[104:107], v[140:143], v[172:175], v[104:107]
	v_mfma_f32_16x16x32_bf16 v[96:99], v[132:135], v[180:183], v[96:99]
	v_mfma_f32_16x16x32_bf16 v[88:91], v[140:143], v[180:183], v[88:91]
	v_mfma_f32_16x16x32_bf16 v[80:83], v[132:135], v[188:191], v[80:83]
	v_mfma_f32_16x16x32_bf16 v[72:75], v[140:143], v[188:191], v[72:75]
	v_mfma_f32_16x16x32_bf16 v[116:119], v[144:147], v[160:163], v[116:119]
	v_mfma_f32_16x16x32_bf16 v[108:111], v[152:155], v[160:163], v[108:111]
	v_mfma_f32_16x16x32_bf16 v[100:103], v[144:147], v[168:171], v[100:103]
	v_mfma_f32_16x16x32_bf16 v[92:95], v[152:155], v[168:171], v[92:95]
	v_mfma_f32_16x16x32_bf16 v[84:87], v[144:147], v[176:179], v[84:87]
	v_mfma_f32_16x16x32_bf16 v[76:79], v[152:155], v[176:179], v[76:79]
	v_mfma_f32_16x16x32_bf16 v[68:71], v[144:147], v[184:187], v[68:71]
	v_mfma_f32_16x16x32_bf16 v[64:67], v[152:155], v[184:187], v[64:67]
	v_mfma_f32_16x16x32_bf16 v[116:119], v[148:151], v[164:167], v[116:119]
	v_mfma_f32_16x16x32_bf16 v[108:111], v[156:159], v[164:167], v[108:111]
	v_mfma_f32_16x16x32_bf16 v[100:103], v[148:151], v[172:175], v[100:103]
	v_mfma_f32_16x16x32_bf16 v[92:95], v[156:159], v[172:175], v[92:95]
	v_mfma_f32_16x16x32_bf16 v[84:87], v[148:151], v[180:183], v[84:87]
	v_mfma_f32_16x16x32_bf16 v[76:79], v[156:159], v[180:183], v[76:79]
	v_mfma_f32_16x16x32_bf16 v[68:71], v[148:151], v[188:191], v[68:71]
	v_mfma_f32_16x16x32_bf16 v[64:67], v[156:159], v[188:191], v[64:67]
	s_barrier
	s_add_i32 s0, s28, s56
	v_lshl_add_u64 v[202:203], s[20:21], 0, v[208:209]
	s_mov_b32 m0, s0
	ds_read_b128 v[160:163], v231 offset:16384
	ds_read_b128 v[164:167], v231 offset:17408
	ds_read_b128 v[168:171], v231 offset:18432
	ds_read_b128 v[172:175], v231 offset:19456
	ds_read_b128 v[176:179], v231 offset:20480
	ds_read_b128 v[180:183], v231 offset:21504
	ds_read_b128 v[184:187], v231 offset:22528
	ds_read_b128 v[188:191], v231 offset:23552
	global_load_lds_dwordx4 v208, s[20:21]
	s_add_i32 m0, s0, 0x2000
	s_add_u32 s0, s20, 0x20000
	v_lshl_add_u64 v[204:205], s[20:21], 0, v[196:197]
	s_addc_u32 s1, s21, 0
	s_add_i32 s28, s29, s56
	global_load_lds_dwordx4 v196, s[20:21]
	s_mov_b32 m0, s28
	v_lshl_add_u64 v[212:213], s[22:23], 0, v[194:195]
	global_load_lds_dwordx4 v208, s[0:1]
	s_add_i32 m0, s28, 0x2000
	s_nop 0
	global_load_lds_dwordx4 v196, s[0:1]
	v_lshl_add_u64 v[206:207], s[22:23], 0, v[192:193]
	s_mov_b32 m0, s53
	s_nop 0
	global_load_lds_dwordx4 v192, s[22:23]
	s_mov_b32 m0, s57
	s_nop 0
	global_load_lds_dwordx4 v194, s[22:23]
	s_waitcnt vmcnt(8)
	s_waitcnt lgkmcnt(0)
	s_barrier
; #define PG8_STAGE(bufoff, gbase, voff) do { _Pragma("unroll") for (int _i = 0; _i < 2; ++_i) \
;         __builtin_amdgcn_global_load_lds((const unsigned*)((const char*)(gbase) + (voff)[_i]), (PG8_LAS unsigned*)(lds + (bufoff) + ldsw + _i * 8192), 16, 0, 0); } while (0)
; #define PG8_LDA(dst, b, h) do { _Pragma("unroll") for (int m = 0; m < 4; ++m) _Pragma("unroll") for (int k = 0; k < 2; ++k) dst[m][k] = *(const PG8_LAS bf16x8*)(lds + PG8_SA(b, h) + aoff + m * 2048 + k * 1024); } while (0)
; #define PG8_LDB(dst, b, h) do { _Pragma("unroll") for (int n = 0; n < 2; ++n) _Pragma("unroll") for (int k = 0; k < 2; ++k) dst[n][k] = *(const PG8_LAS bf16x8*)(lds + PG8_SB(b, h) + boff + n * 2048 + k * 1024); } while (0)
; #define PG8_MMA(ai, bj, At, Bt) do { __builtin_amdgcn_s_setprio(1); _Pragma("unroll") for (int m = 0; m < 4; ++m) _Pragma("unroll") for (int n = 0; n < 2; ++n) _Pragma("unroll") for (int k = 0; k < 2; ++k) \
;         acc[ai][bj][m][n] = __builtin_amdgcn_mfma_f32_16x16x32_bf16(Bt[n][k], At[m][k], acc[ai][bj][m][n], 0, 0, 0); __builtin_amdgcn_s_setprio(0); } while (0)
; #define PG8_WAIT_V(n) asm volatile("s_waitcnt vmcnt(" #n ")" ::: "memory")
; #define PG8_WAIT_L(n) asm volatile("s_waitcnt lgkmcnt(" #n ")" ::: "memory")
; #define PG8_BAR __builtin_amdgcn_s_barrier()
; #define PG8_SCHED __builtin_amdgcn_sched_barrier(0)
; template <class Epi, class Sched, bool ALIGN_EPI = false, bool SP2 = false>
; __device__ __forceinline__ void gemm_phase(PG8_LAS unsigned char* lds, const Gemm g, const Sched& S, const Epi& E) {
;     ...
;             PG8_WAIT_V(8); PG8_WAIT_L(0); PG8_BAR; PG8_MMA(1, 0, At, B0); PG8_MMA(1, 1, At, B1); PG8_BAR; PG8_SCHED;
;             PG8_LDB(B0, 1, 0); PG8_LDB(B1, 1, 1); PG8_SCHED; PG8_LDA(At, 1, 0); PG8_STAGE(PG8_SA(0, 1), a2 + hstepA, voffA);
;             PG8_WAIT_V(8); PG8_WAIT_L(0); PG8_BAR; PG8_MMA(0, 0, At, B0); PG8_MMA(0, 1, At, B1); PG8_BAR; PG8_SCHED;
	s_waitcnt lgkmcnt(0)
	v_mfma_f32_16x16x32_bf16 v[60:63], v[128:131], v[160:163], v[60:63]
	v_mfma_f32_16x16x32_bf16 v[56:59], v[136:139], v[160:163], v[56:59]
	v_mfma_f32_16x16x32_bf16 v[48:51], v[128:131], v[168:171], v[48:51]
	v_mfma_f32_16x16x32_bf16 v[40:43], v[136:139], v[168:171], v[40:43]
	v_mfma_f32_16x16x32_bf16 v[32:35], v[128:131], v[176:179], v[32:35]
	v_mfma_f32_16x16x32_bf16 v[24:27], v[136:139], v[176:179], v[24:27]
	v_mfma_f32_16x16x32_bf16 v[16:19], v[128:131], v[184:187], v[16:19]
	v_mfma_f32_16x16x32_bf16 v[8:11], v[136:139], v[184:187], v[8:11]
	v_mfma_f32_16x16x32_bf16 v[60:63], v[132:135], v[164:167], v[60:63]
	v_mfma_f32_16x16x32_bf16 v[56:59], v[140:143], v[164:167], v[56:59]
	v_mfma_f32_16x16x32_bf16 v[48:51], v[132:135], v[172:175], v[48:51]
	v_mfma_f32_16x16x32_bf16 v[40:43], v[140:143], v[172:175], v[40:43]
	v_mfma_f32_16x16x32_bf16 v[32:35], v[132:135], v[180:183], v[32:35]
	v_mfma_f32_16x16x32_bf16 v[24:27], v[140:143], v[180:183], v[24:27]
	v_mfma_f32_16x16x32_bf16 v[16:19], v[132:135], v[188:191], v[16:19]
	v_mfma_f32_16x16x32_bf16 v[8:11], v[140:143], v[188:191], v[8:11]
	v_mfma_f32_16x16x32_bf16 v[52:55], v[144:147], v[160:163], v[52:55]
	v_mfma_f32_16x16x32_bf16 v[44:47], v[152:155], v[160:163], v[44:47]
	v_mfma_f32_16x16x32_bf16 v[36:39], v[144:147], v[168:171], v[36:39]
	v_mfma_f32_16x16x32_bf16 v[28:31], v[152:155], v[168:171], v[28:31]
	v_mfma_f32_16x16x32_bf16 v[20:23], v[144:147], v[176:179], v[20:23]
	v_mfma_f32_16x16x32_bf16 v[12:15], v[152:155], v[176:179], v[12:15]
	v_mfma_f32_16x16x32_bf16 v[4:7], v[144:147], v[184:187], v[4:7]
	v_mfma_f32_16x16x32_bf16 v[0:3], v[152:155], v[184:187], v[0:3]
	v_mfma_f32_16x16x32_bf16 v[52:55], v[148:151], v[164:167], v[52:55]
	v_mfma_f32_16x16x32_bf16 v[44:47], v[156:159], v[164:167], v[44:47]
	v_mfma_f32_16x16x32_bf16 v[36:39], v[148:151], v[172:175], v[36:39]
	v_mfma_f32_16x16x32_bf16 v[28:31], v[156:159], v[172:175], v[28:31]
	v_mfma_f32_16x16x32_bf16 v[20:23], v[148:151], v[180:183], v[20:23]
	v_mfma_f32_16x16x32_bf16 v[12:15], v[156:159], v[180:183], v[12:15]
	v_mfma_f32_16x16x32_bf16 v[4:7], v[148:151], v[188:191], v[4:7]
	v_mfma_f32_16x16x32_bf16 v[0:3], v[156:159], v[188:191], v[0:3]
	s_barrier
	s_add_i32 s28, 0, 0x18000
	s_add_i32 s29, 0, 0x1c000
	v_add_u32_e32 v140, s28, v211
	v_add_u32_e32 v156, s29, v211
	ds_read_b128 v[128:131], v140
	ds_read_b128 v[132:135], v140 offset:1024
	ds_read_b128 v[136:139], v140 offset:2048
	ds_read_b128 v[140:143], v140 offset:3072
	ds_read_b128 v[144:147], v156
	ds_read_b128 v[148:151], v156 offset:1024
	ds_read_b128 v[152:155], v156 offset:2048
	ds_read_b128 v[156:159], v156 offset:3072
	s_add_u32 s0, s22, 0x60000
	s_addc_u32 s1, s23, 0
	s_mov_b32 m0, s58
	ds_read_b128 v[160:163], v231 offset:32768
	ds_read_b128 v[164:167], v231 offset:33792
	ds_read_b128 v[168:171], v231 offset:34816
	ds_read_b128 v[172:175], v231 offset:35840
	ds_read_b128 v[176:179], v231 offset:36864
	ds_read_b128 v[180:183], v231 offset:37888
	ds_read_b128 v[184:187], v231 offset:38912
	ds_read_b128 v[188:191], v231 offset:39936
	global_load_lds_dwordx4 v192, s[0:1]
	s_mov_b32 m0, s59
	s_nop 0
	global_load_lds_dwordx4 v194, s[0:1]
	s_waitcnt vmcnt(8)
	s_waitcnt lgkmcnt(0)
	s_barrier
	s_waitcnt lgkmcnt(0)
	v_mfma_f32_16x16x32_bf16 v[124:127], v[128:131], v[160:163], v[124:127]
	v_mfma_f32_16x16x32_bf16 v[120:123], v[136:139], v[160:163], v[120:123]
	v_mfma_f32_16x16x32_bf16 v[112:115], v[128:131], v[168:171], v[112:115]
	v_mfma_f32_16x16x32_bf16 v[104:107], v[136:139], v[168:171], v[104:107]
	v_mfma_f32_16x16x32_bf16 v[96:99], v[128:131], v[176:179], v[96:99]
	v_mfma_f32_16x16x32_bf16 v[88:91], v[136:139], v[176:179], v[88:91]
	v_mfma_f32_16x16x32_bf16 v[80:83], v[128:131], v[184:187], v[80:83]
	v_mfma_f32_16x16x32_bf16 v[72:75], v[136:139], v[184:187], v[72:75]
	v_mfma_f32_16x16x32_bf16 v[124:127], v[132:135], v[164:167], v[124:127]
	v_mfma_f32_16x16x32_bf16 v[120:123], v[140:143], v[164:167], v[120:123]
	v_mfma_f32_16x16x32_bf16 v[112:115], v[132:135], v[172:175], v[112:115]
	v_mfma_f32_16x16x32_bf16 v[104:107], v[140:143], v[172:175], v[104:107]
	v_mfma_f32_16x16x32_bf16 v[96:99], v[132:135], v[180:183], v[96:99]
	v_mfma_f32_16x16x32_bf16 v[88:91], v[140:143], v[180:183], v[88:91]
	v_mfma_f32_16x16x32_bf16 v[80:83], v[132:135], v[188:191], v[80:83]
	v_mfma_f32_16x16x32_bf16 v[72:75], v[140:143], v[188:191], v[72:75]
	v_mfma_f32_16x16x32_bf16 v[116:119], v[144:147], v[160:163], v[116:119]
	v_mfma_f32_16x16x32_bf16 v[108:111], v[152:155], v[160:163], v[108:111]
	v_mfma_f32_16x16x32_bf16 v[100:103], v[144:147], v[168:171], v[100:103]
	v_mfma_f32_16x16x32_bf16 v[92:95], v[152:155], v[168:171], v[92:95]
	v_mfma_f32_16x16x32_bf16 v[84:87], v[144:147], v[176:179], v[84:87]
	v_mfma_f32_16x16x32_bf16 v[76:79], v[152:155], v[176:179], v[76:79]
	v_mfma_f32_16x16x32_bf16 v[68:71], v[144:147], v[184:187], v[68:71]
	v_mfma_f32_16x16x32_bf16 v[64:67], v[152:155], v[184:187], v[64:67]
	v_mfma_f32_16x16x32_bf16 v[116:119], v[148:151], v[164:167], v[116:119]
	v_mfma_f32_16x16x32_bf16 v[108:111], v[156:159], v[164:167], v[108:111]
	v_mfma_f32_16x16x32_bf16 v[100:103], v[148:151], v[172:175], v[100:103]
	v_mfma_f32_16x16x32_bf16 v[92:95], v[156:159], v[172:175], v[92:95]
	v_mfma_f32_16x16x32_bf16 v[84:87], v[148:151], v[180:183], v[84:87]
	v_mfma_f32_16x16x32_bf16 v[76:79], v[156:159], v[180:183], v[76:79]
	v_mfma_f32_16x16x32_bf16 v[68:71], v[148:151], v[188:191], v[68:71]
	v_mfma_f32_16x16x32_bf16 v[64:67], v[156:159], v[188:191], v[64:67]
	s_barrier
; #define PG8_STAGE(bufoff, gbase, voff) do { _Pragma("unroll") for (int _i = 0; _i < 2; ++_i) \
;         __builtin_amdgcn_global_load_lds((const unsigned*)((const char*)(gbase) + (voff)[_i]), (PG8_LAS unsigned*)(lds + (bufoff) + ldsw + _i * 8192), 16, 0, 0); } while (0)
; #define PG8_LDA(dst, b, h) do { _Pragma("unroll") for (int m = 0; m < 4; ++m) _Pragma("unroll") for (int k = 0; k < 2; ++k) dst[m][k] = *(const PG8_LAS bf16x8*)(lds + PG8_SA(b, h) + aoff + m * 2048 + k * 1024); } while (0)
; #define PG8_MMA(ai, bj, At, Bt) do { __builtin_amdgcn_s_setprio(1); _Pragma("unroll") for (int m = 0; m < 4; ++m) _Pragma("unroll") for (int n = 0; n < 2; ++n) _Pragma("unroll") for (int k = 0; k < 2; ++k) \
;         acc[ai][bj][m][n] = __builtin_amdgcn_mfma_f32_16x16x32_bf16(Bt[n][k], At[m][k], acc[ai][bj][m][n], 0, 0, 0); __builtin_amdgcn_s_setprio(0); } while (0)
; #define PG8_WAIT_V(n) asm volatile("s_waitcnt vmcnt(" #n ")" ::: "memory")
; #define PG8_WAIT_L(n) asm volatile("s_waitcnt lgkmcnt(" #n ")" ::: "memory")
; #define PG8_BAR __builtin_amdgcn_s_barrier()
; #define PG8_SCHED __builtin_amdgcn_sched_barrier(0)
; template <class Epi, class Sched, bool ALIGN_EPI = false, bool SP2 = false>
; __device__ __forceinline__ void gemm_phase(PG8_LAS unsigned char* lds, const Gemm g, const Sched& S, const Epi& E) {
;     ...
;             PG8_LDA(At, 1, 1); PG8_STAGE(PG8_SB(1, 0), b3, voffB); PG8_STAGE(PG8_SB(1, 1), b3 + hstepB, voffB); PG8_STAGE(PG8_SA(1, 0), a3, voffA);
;             PG8_WAIT_V(8); PG8_WAIT_L(0); PG8_BAR; PG8_MMA(1, 0, At, B0); PG8_MMA(1, 1, At, B1); PG8_BAR; PG8_SCHED;
	s_add_i32 s0, s28, s56
	v_lshl_add_u64 v[202:203], v[202:203], 0, s[10:11]
	s_mov_b32 m0, s0
	ds_read_b128 v[160:163], v231 offset:49152
	ds_read_b128 v[164:167], v231 offset:50176
	ds_read_b128 v[168:171], v231 offset:51200
	ds_read_b128 v[172:175], v231 offset:52224
	ds_read_b128 v[176:179], v231 offset:53248
	ds_read_b128 v[180:183], v231 offset:54272
	ds_read_b128 v[184:187], v231 offset:55296
	ds_read_b128 v[188:191], v231 offset:56320
	global_load_lds_dwordx4 v[202:203], off
	s_add_i32 m0, s0, 0x2000
	s_add_u32 s0, s20, 0x20080
	v_lshl_add_u64 v[202:203], v[204:205], 0, s[10:11]
	s_addc_u32 s1, s21, 0
	s_add_i32 s20, s29, s56
	global_load_lds_dwordx4 v[202:203], off
	s_mov_b32 m0, s20
	s_nop 0
	global_load_lds_dwordx4 v208, s[0:1]
	s_add_i32 m0, s20, 0x2000
	s_nop 0
	global_load_lds_dwordx4 v196, s[0:1]
	v_lshl_add_u64 v[202:203], v[206:207], 0, s[10:11]
	s_mov_b32 m0, s61
	s_nop 0
	global_load_lds_dwordx4 v[202:203], off
	v_lshl_add_u64 v[202:203], v[212:213], 0, s[10:11]
	s_mov_b32 m0, s62
	s_nop 0
	global_load_lds_dwordx4 v[202:203], off
	s_waitcnt vmcnt(8)
	s_waitcnt lgkmcnt(0)
	s_barrier
	s_waitcnt lgkmcnt(0)
	v_mfma_f32_16x16x32_bf16 v[60:63], v[128:131], v[160:163], v[60:63]
	v_mfma_f32_16x16x32_bf16 v[56:59], v[136:139], v[160:163], v[56:59]
	v_mfma_f32_16x16x32_bf16 v[48:51], v[128:131], v[168:171], v[48:51]
	v_mfma_f32_16x16x32_bf16 v[40:43], v[136:139], v[168:171], v[40:43]
	v_mfma_f32_16x16x32_bf16 v[32:35], v[128:131], v[176:179], v[32:35]
	v_mfma_f32_16x16x32_bf16 v[24:27], v[136:139], v[176:179], v[24:27]
	v_mfma_f32_16x16x32_bf16 v[16:19], v[128:131], v[184:187], v[16:19]
	v_mfma_f32_16x16x32_bf16 v[8:11], v[136:139], v[184:187], v[8:11]
	v_mfma_f32_16x16x32_bf16 v[60:63], v[132:135], v[164:167], v[60:63]
	v_mfma_f32_16x16x32_bf16 v[56:59], v[140:143], v[164:167], v[56:59]
	v_mfma_f32_16x16x32_bf16 v[48:51], v[132:135], v[172:175], v[48:51]
	v_mfma_f32_16x16x32_bf16 v[40:43], v[140:143], v[172:175], v[40:43]
	v_mfma_f32_16x16x32_bf16 v[32:35], v[132:135], v[180:183], v[32:35]
	v_mfma_f32_16x16x32_bf16 v[24:27], v[140:143], v[180:183], v[24:27]
	v_mfma_f32_16x16x32_bf16 v[16:19], v[132:135], v[188:191], v[16:19]
	v_mfma_f32_16x16x32_bf16 v[8:11], v[140:143], v[188:191], v[8:11]
	v_mfma_f32_16x16x32_bf16 v[52:55], v[144:147], v[160:163], v[52:55]
	v_mfma_f32_16x16x32_bf16 v[44:47], v[152:155], v[160:163], v[44:47]
	v_mfma_f32_16x16x32_bf16 v[36:39], v[144:147], v[168:171], v[36:39]
	v_mfma_f32_16x16x32_bf16 v[28:31], v[152:155], v[168:171], v[28:31]
	v_mfma_f32_16x16x32_bf16 v[20:23], v[144:147], v[176:179], v[20:23]
	v_mfma_f32_16x16x32_bf16 v[12:15], v[152:155], v[176:179], v[12:15]
	v_mfma_f32_16x16x32_bf16 v[4:7], v[144:147], v[184:187], v[4:7]
	v_mfma_f32_16x16x32_bf16 v[0:3], v[152:155], v[184:187], v[0:3]
	v_mfma_f32_16x16x32_bf16 v[52:55], v[148:151], v[164:167], v[52:55]
	v_mfma_f32_16x16x32_bf16 v[44:47], v[156:159], v[164:167], v[44:47]
	v_mfma_f32_16x16x32_bf16 v[36:39], v[148:151], v[172:175], v[36:39]
	v_mfma_f32_16x16x32_bf16 v[28:31], v[156:159], v[172:175], v[28:31]
	v_mfma_f32_16x16x32_bf16 v[20:23], v[148:151], v[180:183], v[20:23]
	v_mfma_f32_16x16x32_bf16 v[12:15], v[156:159], v[180:183], v[12:15]
	v_mfma_f32_16x16x32_bf16 v[4:7], v[148:151], v[188:191], v[4:7]
	v_mfma_f32_16x16x32_bf16 v[0:3], v[156:159], v[188:191], v[0:3]
	s_barrier
	s_add_i32 s34, s34, 2
	s_add_u32 s18, s18, 0x100
	s_addc_u32 s19, s19, 0
	s_cmp_gt_u32 s34, 5
	s_mov_b64 s[0:1], s[4:5]
	s_cbranch_scc0 .LBB0_690
	s_and_b64 vcc, exec, s[44:45]
	s_cbranch_vccz .LBB0_693
	s_barrier

; #define PG8_STAGE(bufoff, gbase, voff) do { _Pragma("unroll") for (int _i = 0; _i < 2; ++_i) \
;         __builtin_amdgcn_global_load_lds((const unsigned*)((const char*)(gbase) + (voff)[_i]), (PG8_LAS unsigned*)(lds + (bufoff) + ldsw + _i * 8192), 16, 0, 0); } while (0)
; #define PG8_WAIT_V(n) asm volatile("s_waitcnt vmcnt(" #n ")" ::: "memory")
; #define PG8_BAR __builtin_amdgcn_s_barrier()
; template <class Epi, class Sched, bool ALIGN_EPI = false, bool SP2 = false>
; __device__ __forceinline__ void gemm_phase(PG8_LAS unsigned char* lds, const Gemm g, const Sched& S, const Epi& E) {
;     ...
;     for (int i = 0; i < 2; ++i) { int R, C; stage_rc(tid * 16 + i * 8192, R, C); const int Rb = Epi::PERM ? ((R & ~31) + perm32(R & 31)) : R;
;         voffA[i] = (unsigned)(R * g.lda + C) * 2u; voffB[i] = (unsigned)(Rb * g.ldb + C) * 2u; }
;     const size_t kstep = (size_t)(BK * 2);
;     const size_t hstepA = (size_t)HALF * g.lda * 2, hstepB = (size_t)HALF * g.ldb * 2;
;     const size_t tstepA = 2 * hstepA, tstepB = 2 * hstepB;
;     const unsigned ldsw = (unsigned)wid * 1024u;
;     const int aoff = lds_byte(wr * 64 + fr, fq * 8), boff = lds_byte(wc * 32 + fr, fq * 8);
;     ...
;         PG8_STAGE(PG8_SB(0, 0), cB, voffB); PG8_STAGE(PG8_SB(0, 1), cB + hstepB, voffB); PG8_STAGE(PG8_SA(0, 0), cA, voffA); PG8_STAGE(PG8_SA(0, 1), cA + hstepA, voffA);
;         if (wr == 1) PG8_BAR;
;         PG8_WAIT_V(2); PG8_BAR;
;         PG8_STAGE(PG8_SB(1, 0), cB + kstep, voffB); PG8_STAGE(PG8_SA(1, 0), cA + kstep, voffA); PG8_STAGE(PG8_SB(1, 1), cB + hstepB + kstep, voffB);
;         PG8_WAIT_V(6); PG8_BAR;
.LBB0_787:
	v_bfe_u32 v15, v14, 4, 2
	v_and_b32_e32 v16, 15, v14
	v_lshlrev_b32_e32 v17, 4, v15
	v_lshlrev_b32_e32 v14, 2, v14
	s_sext_i32_i8 s12, s6
	v_lshl_or_b32 v140, s8, 6, v16
	v_lshl_or_b32 v16, v16, 6, v17
	s_lshl_b32 s6, s8, 13
	v_and_b32_e32 v14, 32, v14
	v_bitop3_b32 v17, v16, s6, v14 bitop3:0xde
	s_lshl_b32 s6, s9, 5
	s_and_b32 s14, s6, 0x60
	s_add_i32 m0, s21, 0x18000
	v_lshl_add_u64 v[6:7], v[6:7], 0, s[10:11]
	s_lshl_b32 s6, s14, 7
	s_waitcnt vmcnt(2)
	s_barrier
	global_load_lds_dwordx4 v[6:7], off
	v_lshl_add_u64 v[4:5], v[4:5], 0, s[10:11]
	s_add_i32 m0, s21, 0x1a000
	s_add_i32 s39, s21, 0x8000
	s_add_i32 s48, s21, 0xa000
	global_load_lds_dwordx4 v[4:5], off
	v_lshl_add_u64 v[0:1], v[0:1], 0, s[10:11]
	s_mov_b32 m0, s39
	s_add_u32 s8, s24, 0x40080
	global_load_lds_dwordx4 v[0:1], off
	v_lshl_add_u64 v[0:1], v[2:3], 0, s[10:11]
	s_mov_b32 m0, s48
	s_addc_u32 s9, s25, 0
	global_load_lds_dwordx4 v[0:1], off
	s_add_i32 m0, s21, 0x1c000
	v_lshl_add_u64 v[0:1], s[8:9], 0, v[208:209]
	global_load_lds_dwordx4 v208, s[8:9]
	v_lshl_add_u64 v[0:1], s[8:9], 0, v[128:129]
	s_add_i32 m0, s21, 0x1e000
	s_cmpk_lt_u32 s7, 0x100
	global_load_lds_dwordx4 v128, s[8:9]
	v_lshlrev_b32_e32 v0, 14, v8
	v_and_b32_e32 v0, 0xffff8000, v0
	v_lshl_add_u32 v0, v9, 11, v0
	v_and_b32_e32 v1, 1, v8
	v_lshl_or_b32 v0, v1, 6, v0
	v_lshl_add_u32 v130, v10, 1, v0
	v_lshlrev_b32_e32 v0, 14, v11
	v_and_b32_e32 v0, 0xffff8000, v0
	s_waitcnt vmcnt(6)
	v_lshl_add_u32 v0, v12, 11, v0
	v_and_b32_e32 v1, 1, v11
	v_lshl_or_b32 v0, v1, 6, v0
	v_bitop3_b32 v141, v16, s6, v14 bitop3:0xde
	s_cselect_b64 s[6:7], -1, 0
	v_lshl_or_b32 v142, v15, 2, s14
	v_mov_b32_e32 v131, v209
	v_lshl_add_u32 v132, v13, 1, v0
	v_mov_b32_e32 v133, v209
	s_mov_b32 s49, 0
	v_add_u32_e32 v143, 0, v17
	s_barrier
	s_branch .LBB0_790

; #define PG8_STAGE(bufoff, gbase, voff) do { _Pragma("unroll") for (int _i = 0; _i < 2; ++_i) \
;         __builtin_amdgcn_global_load_lds((const unsigned*)((const char*)(gbase) + (voff)[_i]), (PG8_LAS unsigned*)(lds + (bufoff) + ldsw + _i * 8192), 16, 0, 0); } while (0)
; #define PG8_LDA(dst, b, h) do { _Pragma("unroll") for (int m = 0; m < 4; ++m) _Pragma("unroll") for (int k = 0; k < 2; ++k) dst[m][k] = *(const PG8_LAS bf16x8*)(lds + PG8_SA(b, h) + aoff + m * 2048 + k * 1024); } while (0)
; #define PG8_LDB(dst, b, h) do { _Pragma("unroll") for (int n = 0; n < 2; ++n) _Pragma("unroll") for (int k = 0; k < 2; ++k) dst[n][k] = *(const PG8_LAS bf16x8*)(lds + PG8_SB(b, h) + boff + n * 2048 + k * 1024); } while (0)
; #define PG8_MMA(ai, bj, At, Bt) do { __builtin_amdgcn_s_setprio(1); _Pragma("unroll") for (int m = 0; m < 4; ++m) _Pragma("unroll") for (int n = 0; n < 2; ++n) _Pragma("unroll") for (int k = 0; k < 2; ++k) \
;         acc[ai][bj][m][n] = __builtin_amdgcn_mfma_f32_16x16x32_bf16(Bt[n][k], At[m][k], acc[ai][bj][m][n], 0, 0, 0); __builtin_amdgcn_s_setprio(0); } while (0)
; #define PG8_WAIT_V(n) asm volatile("s_waitcnt vmcnt(" #n ")" ::: "memory")
; #define PG8_WAIT_L(n) asm volatile("s_waitcnt lgkmcnt(" #n ")" ::: "memory")
; #define PG8_BAR __builtin_amdgcn_s_barrier()
; #define PG8_SCHED __builtin_amdgcn_sched_barrier(0)
; template <class Epi, class Sched, bool ALIGN_EPI = false, bool SP2 = false>
; __device__ __forceinline__ void gemm_phase(PG8_LAS unsigned char* lds, const Gemm g, const Sched& S, const Epi& E) {
;     ...
;             PG8_LDB(B0, 0, 0); PG8_LDB(B1, 0, 1); PG8_SCHED; PG8_LDA(At, 0, 0); PG8_STAGE(PG8_SA(1, 1), a1 + hstepA, voffA);
;             PG8_WAIT_V(8); PG8_WAIT_L(0); PG8_BAR; PG8_MMA(0, 0, At, B0); PG8_MMA(0, 1, At, B1); PG8_BAR; PG8_SCHED;
;             PG8_LDA(At, 0, 1); PG8_STAGE(PG8_SB(0, 0), b2, voffB); PG8_STAGE(PG8_SB(0, 1), b2 + hstepB, voffB); PG8_STAGE(PG8_SA(0, 0), a2, voffA);
;             PG8_WAIT_V(8); PG8_WAIT_L(0); PG8_BAR; PG8_MMA(1, 0, At, B0); PG8_MMA(1, 1, At, B1); PG8_BAR; PG8_SCHED;
.LBB0_797:
	s_add_u32 s22, s0, 0xfffc0080
	s_addc_u32 s23, s1, -1
	s_add_i32 s28, 0, 0x10000
	s_cmp_eq_u32 s51, 12
	s_cselect_b32 s25, s14, s23
	s_cselect_b32 s24, s15, s22
	v_add_u32_e32 v138, s28, v141
	s_cselect_b32 s23, s9, s50
	s_cselect_b32 s22, s38, s43
	s_add_i32 s30, 0, 0x14000
	ds_read_b128 v[134:137], v138
	ds_read_b128 v[144:147], v138 offset:1024
	ds_read_b128 v[148:151], v138 offset:2048
	ds_read_b128 v[152:155], v138 offset:3072
	v_add_u32_e32 v138, s30, v141
	ds_read_b128 v[156:159], v138
	ds_read_b128 v[160:163], v138 offset:1024
	ds_read_b128 v[164:167], v138 offset:2048
	ds_read_b128 v[168:171], v138 offset:3072
	s_add_i32 m0, s21, 0xc000
	ds_read_b128 v[172:175], v143
	ds_read_b128 v[176:179], v143 offset:1024
	ds_read_b128 v[180:183], v143 offset:2048
	ds_read_b128 v[184:187], v143 offset:3072
	ds_read_b128 v[188:191], v143 offset:4096
	ds_read_b128 v[192:195], v143 offset:5120
	ds_read_b128 v[196:199], v143 offset:6144
	ds_read_b128 v[200:203], v143 offset:7168
	global_load_lds_dwordx4 v130, s[0:1]
	s_add_i32 m0, s21, 0xe000
	s_nop 0
	global_load_lds_dwordx4 v132, s[0:1]
	s_waitcnt vmcnt(8)
	s_waitcnt lgkmcnt(0)
	s_barrier
	s_waitcnt lgkmcnt(0)
	v_mfma_f32_16x16x32_bf16 v[124:127], v[134:137], v[172:175], v[124:127]
	v_mfma_f32_16x16x32_bf16 v[120:123], v[148:151], v[172:175], v[120:123]
	v_mfma_f32_16x16x32_bf16 v[116:119], v[134:137], v[180:183], v[116:119]
	v_mfma_f32_16x16x32_bf16 v[112:115], v[148:151], v[180:183], v[112:115]
	v_mfma_f32_16x16x32_bf16 v[108:111], v[134:137], v[188:191], v[108:111]
	v_mfma_f32_16x16x32_bf16 v[100:103], v[148:151], v[188:191], v[100:103]
	v_mfma_f32_16x16x32_bf16 v[92:95], v[134:137], v[196:199], v[92:95]
	v_mfma_f32_16x16x32_bf16 v[80:83], v[148:151], v[196:199], v[80:83]
	v_mfma_f32_16x16x32_bf16 v[124:127], v[144:147], v[176:179], v[124:127]
	v_mfma_f32_16x16x32_bf16 v[120:123], v[152:155], v[176:179], v[120:123]
	v_mfma_f32_16x16x32_bf16 v[116:119], v[144:147], v[184:187], v[116:119]
	v_mfma_f32_16x16x32_bf16 v[112:115], v[152:155], v[184:187], v[112:115]
	v_mfma_f32_16x16x32_bf16 v[108:111], v[144:147], v[192:195], v[108:111]
	v_mfma_f32_16x16x32_bf16 v[100:103], v[152:155], v[192:195], v[100:103]
	v_mfma_f32_16x16x32_bf16 v[92:95], v[144:147], v[200:203], v[92:95]
	v_mfma_f32_16x16x32_bf16 v[80:83], v[152:155], v[200:203], v[80:83]
	v_mfma_f32_16x16x32_bf16 v[104:107], v[156:159], v[172:175], v[104:107]
	v_mfma_f32_16x16x32_bf16 v[96:99], v[164:167], v[172:175], v[96:99]
	v_mfma_f32_16x16x32_bf16 v[88:91], v[156:159], v[180:183], v[88:91]
	v_mfma_f32_16x16x32_bf16 v[84:87], v[164:167], v[180:183], v[84:87]
	v_mfma_f32_16x16x32_bf16 v[76:79], v[156:159], v[188:191], v[76:79]
	v_mfma_f32_16x16x32_bf16 v[72:75], v[164:167], v[188:191], v[72:75]
	v_mfma_f32_16x16x32_bf16 v[68:71], v[156:159], v[196:199], v[68:71]
	v_mfma_f32_16x16x32_bf16 v[64:67], v[164:167], v[196:199], v[64:67]
	v_mfma_f32_16x16x32_bf16 v[104:107], v[160:163], v[176:179], v[104:107]
	v_mfma_f32_16x16x32_bf16 v[96:99], v[168:171], v[176:179], v[96:99]
	v_mfma_f32_16x16x32_bf16 v[88:91], v[160:163], v[184:187], v[88:91]
	v_mfma_f32_16x16x32_bf16 v[84:87], v[168:171], v[184:187], v[84:87]
	v_mfma_f32_16x16x32_bf16 v[76:79], v[160:163], v[192:195], v[76:79]
	v_mfma_f32_16x16x32_bf16 v[72:75], v[168:171], v[192:195], v[72:75]
	v_mfma_f32_16x16x32_bf16 v[68:71], v[160:163], v[200:203], v[68:71]
	v_mfma_f32_16x16x32_bf16 v[64:67], v[168:171], v[200:203], v[64:67]
	s_barrier
	s_add_i32 s28, s28, s19
	v_lshl_add_u64 v[138:139], s[22:23], 0, v[208:209]
	s_mov_b32 m0, s28
	ds_read_b128 v[172:175], v143 offset:16384
	ds_read_b128 v[176:179], v143 offset:17408
	ds_read_b128 v[180:183], v143 offset:18432
	ds_read_b128 v[184:187], v143 offset:19456
	ds_read_b128 v[188:191], v143 offset:20480
	ds_read_b128 v[192:195], v143 offset:21504
	ds_read_b128 v[196:199], v143 offset:22528
	ds_read_b128 v[200:203], v143 offset:23552
	global_load_lds_dwordx4 v208, s[22:23]
	s_add_i32 m0, s28, 0x2000
	s_add_u32 s28, s22, 0x40000
	v_lshl_add_u64 v[204:205], s[22:23], 0, v[128:129]
	s_addc_u32 s29, s23, 0
	s_add_i32 s30, s30, s19
	global_load_lds_dwordx4 v128, s[22:23]
	s_mov_b32 m0, s30
	v_lshl_add_u64 v[210:211], s[24:25], 0, v[128:129]
	global_load_lds_dwordx4 v208, s[28:29]
	s_add_i32 m0, s30, 0x2000
	s_nop 0
	global_load_lds_dwordx4 v128, s[28:29]
	v_lshl_add_u64 v[206:207], s[24:25], 0, v[208:209]
	s_mov_b32 m0, s21
	s_nop 0
	global_load_lds_dwordx4 v208, s[24:25]
	s_mov_b32 m0, s26
	s_nop 0
	global_load_lds_dwordx4 v128, s[24:25]
	s_waitcnt vmcnt(8)
	s_waitcnt lgkmcnt(0)
	s_barrier
; #define PG8_STAGE(bufoff, gbase, voff) do { _Pragma("unroll") for (int _i = 0; _i < 2; ++_i) \
;         __builtin_amdgcn_global_load_lds((const unsigned*)((const char*)(gbase) + (voff)[_i]), (PG8_LAS unsigned*)(lds + (bufoff) + ldsw + _i * 8192), 16, 0, 0); } while (0)
; #define PG8_LDA(dst, b, h) do { _Pragma("unroll") for (int m = 0; m < 4; ++m) _Pragma("unroll") for (int k = 0; k < 2; ++k) dst[m][k] = *(const PG8_LAS bf16x8*)(lds + PG8_SA(b, h) + aoff + m * 2048 + k * 1024); } while (0)
; #define PG8_LDB(dst, b, h) do { _Pragma("unroll") for (int n = 0; n < 2; ++n) _Pragma("unroll") for (int k = 0; k < 2; ++k) dst[n][k] = *(const PG8_LAS bf16x8*)(lds + PG8_SB(b, h) + boff + n * 2048 + k * 1024); } while (0)
; #define PG8_MMA(ai, bj, At, Bt) do { __builtin_amdgcn_s_setprio(1); _Pragma("unroll") for (int m = 0; m < 4; ++m) _Pragma("unroll") for (int n = 0; n < 2; ++n) _Pragma("unroll") for (int k = 0; k < 2; ++k) \
;         acc[ai][bj][m][n] = __builtin_amdgcn_mfma_f32_16x16x32_bf16(Bt[n][k], At[m][k], acc[ai][bj][m][n], 0, 0, 0); __builtin_amdgcn_s_setprio(0); } while (0)
; #define PG8_WAIT_V(n) asm volatile("s_waitcnt vmcnt(" #n ")" ::: "memory")
; #define PG8_WAIT_L(n) asm volatile("s_waitcnt lgkmcnt(" #n ")" ::: "memory")
; #define PG8_BAR __builtin_amdgcn_s_barrier()
; #define PG8_SCHED __builtin_amdgcn_sched_barrier(0)
; template <class Epi, class Sched, bool ALIGN_EPI = false, bool SP2 = false>
; __device__ __forceinline__ void gemm_phase(PG8_LAS unsigned char* lds, const Gemm g, const Sched& S, const Epi& E) {
;     ...
;             PG8_WAIT_V(8); PG8_WAIT_L(0); PG8_BAR; PG8_MMA(1, 0, At, B0); PG8_MMA(1, 1, At, B1); PG8_BAR; PG8_SCHED;
;             PG8_LDB(B0, 1, 0); PG8_LDB(B1, 1, 1); PG8_SCHED; PG8_LDA(At, 1, 0); PG8_STAGE(PG8_SA(0, 1), a2 + hstepA, voffA);
;             PG8_WAIT_V(8); PG8_WAIT_L(0); PG8_BAR; PG8_MMA(0, 0, At, B0); PG8_MMA(0, 1, At, B1); PG8_BAR; PG8_SCHED;
	s_waitcnt lgkmcnt(0)
	v_mfma_f32_16x16x32_bf16 v[60:63], v[134:137], v[172:175], v[60:63]
	v_mfma_f32_16x16x32_bf16 v[56:59], v[148:151], v[172:175], v[56:59]
	v_mfma_f32_16x16x32_bf16 v[52:55], v[134:137], v[180:183], v[52:55]
	v_mfma_f32_16x16x32_bf16 v[48:51], v[148:151], v[180:183], v[48:51]
	v_mfma_f32_16x16x32_bf16 v[44:47], v[134:137], v[188:191], v[44:47]
	v_mfma_f32_16x16x32_bf16 v[32:35], v[148:151], v[188:191], v[32:35]
	v_mfma_f32_16x16x32_bf16 v[16:19], v[134:137], v[196:199], v[16:19]
	v_mfma_f32_16x16x32_bf16 v[8:11], v[148:151], v[196:199], v[8:11]
	v_mfma_f32_16x16x32_bf16 v[60:63], v[144:147], v[176:179], v[60:63]
	v_mfma_f32_16x16x32_bf16 v[56:59], v[152:155], v[176:179], v[56:59]
	v_mfma_f32_16x16x32_bf16 v[52:55], v[144:147], v[184:187], v[52:55]
	v_mfma_f32_16x16x32_bf16 v[48:51], v[152:155], v[184:187], v[48:51]
	v_mfma_f32_16x16x32_bf16 v[44:47], v[144:147], v[192:195], v[44:47]
	v_mfma_f32_16x16x32_bf16 v[32:35], v[152:155], v[192:195], v[32:35]
	v_mfma_f32_16x16x32_bf16 v[16:19], v[144:147], v[200:203], v[16:19]
	v_mfma_f32_16x16x32_bf16 v[8:11], v[152:155], v[200:203], v[8:11]
	v_mfma_f32_16x16x32_bf16 v[40:43], v[156:159], v[172:175], v[40:43]
	v_mfma_f32_16x16x32_bf16 v[36:39], v[164:167], v[172:175], v[36:39]
	v_mfma_f32_16x16x32_bf16 v[28:31], v[156:159], v[180:183], v[28:31]
	v_mfma_f32_16x16x32_bf16 v[24:27], v[164:167], v[180:183], v[24:27]
	v_mfma_f32_16x16x32_bf16 v[20:23], v[156:159], v[188:191], v[20:23]
	v_mfma_f32_16x16x32_bf16 v[12:15], v[164:167], v[188:191], v[12:15]
	v_mfma_f32_16x16x32_bf16 v[4:7], v[156:159], v[196:199], v[4:7]
	v_mfma_f32_16x16x32_bf16 v[0:3], v[164:167], v[196:199], v[0:3]
	v_mfma_f32_16x16x32_bf16 v[40:43], v[160:163], v[176:179], v[40:43]
	v_mfma_f32_16x16x32_bf16 v[36:39], v[168:171], v[176:179], v[36:39]
	v_mfma_f32_16x16x32_bf16 v[28:31], v[160:163], v[184:187], v[28:31]
	v_mfma_f32_16x16x32_bf16 v[24:27], v[168:171], v[184:187], v[24:27]
	v_mfma_f32_16x16x32_bf16 v[20:23], v[160:163], v[192:195], v[20:23]
	v_mfma_f32_16x16x32_bf16 v[12:15], v[168:171], v[192:195], v[12:15]
	v_mfma_f32_16x16x32_bf16 v[4:7], v[160:163], v[200:203], v[4:7]
	v_mfma_f32_16x16x32_bf16 v[0:3], v[168:171], v[200:203], v[0:3]
	s_barrier
	s_add_i32 s28, 0, 0x18000
	s_add_i32 s29, 0, 0x1c000
	v_add_u32_e32 v152, s28, v141
	v_add_u32_e32 v168, s29, v141
	ds_read_b128 v[134:137], v152
	ds_read_b128 v[144:147], v152 offset:1024
	ds_read_b128 v[148:151], v152 offset:2048
	ds_read_b128 v[152:155], v152 offset:3072
	ds_read_b128 v[156:159], v168
	ds_read_b128 v[160:163], v168 offset:1024
	ds_read_b128 v[164:167], v168 offset:2048
	ds_read_b128 v[168:171], v168 offset:3072
	s_add_u32 s24, s24, 0x40000
	s_addc_u32 s25, s25, 0
	s_mov_b32 m0, s34
	ds_read_b128 v[172:175], v143 offset:32768
	ds_read_b128 v[176:179], v143 offset:33792
	ds_read_b128 v[180:183], v143 offset:34816
	ds_read_b128 v[184:187], v143 offset:35840
	ds_read_b128 v[188:191], v143 offset:36864
	ds_read_b128 v[192:195], v143 offset:37888
	ds_read_b128 v[196:199], v143 offset:38912
	ds_read_b128 v[200:203], v143 offset:39936
	global_load_lds_dwordx4 v208, s[24:25]
	s_mov_b32 m0, s35
	s_nop 0
	global_load_lds_dwordx4 v128, s[24:25]
	s_waitcnt vmcnt(8)
	s_waitcnt lgkmcnt(0)
	s_barrier
	s_waitcnt lgkmcnt(0)
	v_mfma_f32_16x16x32_bf16 v[124:127], v[134:137], v[172:175], v[124:127]
	v_mfma_f32_16x16x32_bf16 v[120:123], v[148:151], v[172:175], v[120:123]
	v_mfma_f32_16x16x32_bf16 v[116:119], v[134:137], v[180:183], v[116:119]
	v_mfma_f32_16x16x32_bf16 v[112:115], v[148:151], v[180:183], v[112:115]
	v_mfma_f32_16x16x32_bf16 v[108:111], v[134:137], v[188:191], v[108:111]
	v_mfma_f32_16x16x32_bf16 v[100:103], v[148:151], v[188:191], v[100:103]
	v_mfma_f32_16x16x32_bf16 v[92:95], v[134:137], v[196:199], v[92:95]
	v_mfma_f32_16x16x32_bf16 v[80:83], v[148:151], v[196:199], v[80:83]
	v_mfma_f32_16x16x32_bf16 v[124:127], v[144:147], v[176:179], v[124:127]
	v_mfma_f32_16x16x32_bf16 v[120:123], v[152:155], v[176:179], v[120:123]
	v_mfma_f32_16x16x32_bf16 v[116:119], v[144:147], v[184:187], v[116:119]
	v_mfma_f32_16x16x32_bf16 v[112:115], v[152:155], v[184:187], v[112:115]
	v_mfma_f32_16x16x32_bf16 v[108:111], v[144:147], v[192:195], v[108:111]
	v_mfma_f32_16x16x32_bf16 v[100:103], v[152:155], v[192:195], v[100:103]
	v_mfma_f32_16x16x32_bf16 v[92:95], v[144:147], v[200:203], v[92:95]
	v_mfma_f32_16x16x32_bf16 v[80:83], v[152:155], v[200:203], v[80:83]
	v_mfma_f32_16x16x32_bf16 v[104:107], v[156:159], v[172:175], v[104:107]
	v_mfma_f32_16x16x32_bf16 v[96:99], v[164:167], v[172:175], v[96:99]
	v_mfma_f32_16x16x32_bf16 v[88:91], v[156:159], v[180:183], v[88:91]
	v_mfma_f32_16x16x32_bf16 v[84:87], v[164:167], v[180:183], v[84:87]
	v_mfma_f32_16x16x32_bf16 v[76:79], v[156:159], v[188:191], v[76:79]
	v_mfma_f32_16x16x32_bf16 v[72:75], v[164:167], v[188:191], v[72:75]
	v_mfma_f32_16x16x32_bf16 v[68:71], v[156:159], v[196:199], v[68:71]
	v_mfma_f32_16x16x32_bf16 v[64:67], v[164:167], v[196:199], v[64:67]
	v_mfma_f32_16x16x32_bf16 v[104:107], v[160:163], v[176:179], v[104:107]
	v_mfma_f32_16x16x32_bf16 v[96:99], v[168:171], v[176:179], v[96:99]
	v_mfma_f32_16x16x32_bf16 v[88:91], v[160:163], v[184:187], v[88:91]
	v_mfma_f32_16x16x32_bf16 v[84:87], v[168:171], v[184:187], v[84:87]
	v_mfma_f32_16x16x32_bf16 v[76:79], v[160:163], v[192:195], v[76:79]
	v_mfma_f32_16x16x32_bf16 v[72:75], v[168:171], v[192:195], v[72:75]
	v_mfma_f32_16x16x32_bf16 v[68:71], v[160:163], v[200:203], v[68:71]
	v_mfma_f32_16x16x32_bf16 v[64:67], v[168:171], v[200:203], v[64:67]
	s_barrier
; #define PG8_STAGE(bufoff, gbase, voff) do { _Pragma("unroll") for (int _i = 0; _i < 2; ++_i) \
;         __builtin_amdgcn_global_load_lds((const unsigned*)((const char*)(gbase) + (voff)[_i]), (PG8_LAS unsigned*)(lds + (bufoff) + ldsw + _i * 8192), 16, 0, 0); } while (0)
; #define PG8_LDA(dst, b, h) do { _Pragma("unroll") for (int m = 0; m < 4; ++m) _Pragma("unroll") for (int k = 0; k < 2; ++k) dst[m][k] = *(const PG8_LAS bf16x8*)(lds + PG8_SA(b, h) + aoff + m * 2048 + k * 1024); } while (0)
; #define PG8_MMA(ai, bj, At, Bt) do { __builtin_amdgcn_s_setprio(1); _Pragma("unroll") for (int m = 0; m < 4; ++m) _Pragma("unroll") for (int n = 0; n < 2; ++n) _Pragma("unroll") for (int k = 0; k < 2; ++k) \
;         acc[ai][bj][m][n] = __builtin_amdgcn_mfma_f32_16x16x32_bf16(Bt[n][k], At[m][k], acc[ai][bj][m][n], 0, 0, 0); __builtin_amdgcn_s_setprio(0); } while (0)
; #define PG8_WAIT_V(n) asm volatile("s_waitcnt vmcnt(" #n ")" ::: "memory")
; #define PG8_WAIT_L(n) asm volatile("s_waitcnt lgkmcnt(" #n ")" ::: "memory")
; #define PG8_BAR __builtin_amdgcn_s_barrier()
; #define PG8_SCHED __builtin_amdgcn_sched_barrier(0)
; template <class Epi, class Sched, bool ALIGN_EPI = false, bool SP2 = false>
; __device__ __forceinline__ void gemm_phase(PG8_LAS unsigned char* lds, const Gemm g, const Sched& S, const Epi& E) {
;     ...
;             PG8_LDA(At, 1, 1); PG8_STAGE(PG8_SB(1, 0), b3, voffB); PG8_STAGE(PG8_SB(1, 1), b3 + hstepB, voffB); PG8_STAGE(PG8_SA(1, 0), a3, voffA);
;             PG8_WAIT_V(8); PG8_WAIT_L(0); PG8_BAR; PG8_MMA(1, 0, At, B0); PG8_MMA(1, 1, At, B1); PG8_BAR; PG8_SCHED;
	s_add_i32 s24, s28, s19
	v_lshl_add_u64 v[138:139], v[138:139], 0, s[10:11]
	s_mov_b32 m0, s24
	ds_read_b128 v[172:175], v143 offset:49152
	ds_read_b128 v[176:179], v143 offset:50176
	ds_read_b128 v[180:183], v143 offset:51200
	ds_read_b128 v[184:187], v143 offset:52224
	ds_read_b128 v[188:191], v143 offset:53248
	ds_read_b128 v[192:195], v143 offset:54272
	ds_read_b128 v[196:199], v143 offset:55296
	ds_read_b128 v[200:203], v143 offset:56320
	global_load_lds_dwordx4 v[138:139], off
	s_add_i32 m0, s24, 0x2000
	s_add_u32 s22, s22, 0x40080
	v_lshl_add_u64 v[138:139], v[204:205], 0, s[10:11]
	s_addc_u32 s23, s23, 0
	s_add_i32 s24, s29, s19
	global_load_lds_dwordx4 v[138:139], off
	s_mov_b32 m0, s24
	s_nop 0
	global_load_lds_dwordx4 v208, s[22:23]
	s_add_i32 m0, s24, 0x2000
	s_nop 0
	global_load_lds_dwordx4 v128, s[22:23]
	v_lshl_add_u64 v[138:139], v[206:207], 0, s[10:11]
	s_mov_b32 m0, s39
	s_nop 0
	global_load_lds_dwordx4 v[138:139], off
	v_lshl_add_u64 v[138:139], v[210:211], 0, s[10:11]
	s_mov_b32 m0, s48
	s_nop 0
	global_load_lds_dwordx4 v[138:139], off
	s_waitcnt vmcnt(8)
	s_waitcnt lgkmcnt(0)
	s_barrier
	s_waitcnt lgkmcnt(0)
	v_mfma_f32_16x16x32_bf16 v[60:63], v[134:137], v[172:175], v[60:63]
	v_mfma_f32_16x16x32_bf16 v[56:59], v[148:151], v[172:175], v[56:59]
	v_mfma_f32_16x16x32_bf16 v[52:55], v[134:137], v[180:183], v[52:55]
	v_mfma_f32_16x16x32_bf16 v[48:51], v[148:151], v[180:183], v[48:51]
	v_mfma_f32_16x16x32_bf16 v[44:47], v[134:137], v[188:191], v[44:47]
	v_mfma_f32_16x16x32_bf16 v[32:35], v[148:151], v[188:191], v[32:35]
	v_mfma_f32_16x16x32_bf16 v[16:19], v[134:137], v[196:199], v[16:19]
	v_mfma_f32_16x16x32_bf16 v[8:11], v[148:151], v[196:199], v[8:11]
	v_mfma_f32_16x16x32_bf16 v[60:63], v[144:147], v[176:179], v[60:63]
	v_mfma_f32_16x16x32_bf16 v[56:59], v[152:155], v[176:179], v[56:59]
	v_mfma_f32_16x16x32_bf16 v[52:55], v[144:147], v[184:187], v[52:55]
	v_mfma_f32_16x16x32_bf16 v[48:51], v[152:155], v[184:187], v[48:51]
	v_mfma_f32_16x16x32_bf16 v[44:47], v[144:147], v[192:195], v[44:47]
	v_mfma_f32_16x16x32_bf16 v[32:35], v[152:155], v[192:195], v[32:35]
	v_mfma_f32_16x16x32_bf16 v[16:19], v[144:147], v[200:203], v[16:19]
	v_mfma_f32_16x16x32_bf16 v[8:11], v[152:155], v[200:203], v[8:11]
	v_mfma_f32_16x16x32_bf16 v[40:43], v[156:159], v[172:175], v[40:43]
	v_mfma_f32_16x16x32_bf16 v[36:39], v[164:167], v[172:175], v[36:39]
	v_mfma_f32_16x16x32_bf16 v[28:31], v[156:159], v[180:183], v[28:31]
	v_mfma_f32_16x16x32_bf16 v[24:27], v[164:167], v[180:183], v[24:27]
	v_mfma_f32_16x16x32_bf16 v[20:23], v[156:159], v[188:191], v[20:23]
	v_mfma_f32_16x16x32_bf16 v[12:15], v[164:167], v[188:191], v[12:15]
	v_mfma_f32_16x16x32_bf16 v[4:7], v[156:159], v[196:199], v[4:7]
	v_mfma_f32_16x16x32_bf16 v[0:3], v[164:167], v[196:199], v[0:3]
	v_mfma_f32_16x16x32_bf16 v[40:43], v[160:163], v[176:179], v[40:43]
	v_mfma_f32_16x16x32_bf16 v[36:39], v[168:171], v[176:179], v[36:39]
	v_mfma_f32_16x16x32_bf16 v[28:31], v[160:163], v[184:187], v[28:31]
	v_mfma_f32_16x16x32_bf16 v[24:27], v[168:171], v[184:187], v[24:27]
	v_mfma_f32_16x16x32_bf16 v[20:23], v[160:163], v[192:195], v[20:23]
	v_mfma_f32_16x16x32_bf16 v[12:15], v[168:171], v[192:195], v[12:15]
	v_mfma_f32_16x16x32_bf16 v[4:7], v[160:163], v[200:203], v[4:7]
	v_mfma_f32_16x16x32_bf16 v[0:3], v[168:171], v[200:203], v[0:3]
	s_barrier
	s_add_i32 s51, s51, 2
	s_add_u32 s0, s0, 0x100
	s_addc_u32 s1, s1, 0
	s_add_u32 s43, s43, 0x100
	s_addc_u32 s50, s50, 0
	s_cmp_gt_u32 s51, 13
	s_cbranch_scc0 .LBB0_797
	s_and_b64 vcc, exec, s[6:7]
	s_cbranch_vccz .LBB0_800
	s_barrier

; #define PG8_STAGE(bufoff, gbase, voff) do { _Pragma("unroll") for (int _i = 0; _i < 2; ++_i) \
;         __builtin_amdgcn_global_load_lds((const unsigned*)((const char*)(gbase) + (voff)[_i]), (PG8_LAS unsigned*)(lds + (bufoff) + ldsw + _i * 8192), 16, 0, 0); } while (0)
; #define PG8_WAIT_V(n) asm volatile("s_waitcnt vmcnt(" #n ")" ::: "memory")
; #define PG8_BAR __builtin_amdgcn_s_barrier()
; template <class Epi, class Sched, bool ALIGN_EPI = false, bool SP2 = false>
; __device__ __forceinline__ void gemm_phase(PG8_LAS unsigned char* lds, const Gemm g, const Sched& S, const Epi& E) {
;     ...
;     for (int i = 0; i < 2; ++i) { int R, C; stage_rc(tid * 16 + i * 8192, R, C); const int Rb = Epi::PERM ? ((R & ~31) + perm32(R & 31)) : R;
;         voffA[i] = (unsigned)(R * g.lda + C) * 2u; voffB[i] = (unsigned)(Rb * g.ldb + C) * 2u; }
;     const size_t kstep = (size_t)(BK * 2);
;     const size_t hstepA = (size_t)HALF * g.lda * 2, hstepB = (size_t)HALF * g.ldb * 2;
;     const size_t tstepA = 2 * hstepA, tstepB = 2 * hstepB;
;     const unsigned ldsw = (unsigned)wid * 1024u;
;     const int aoff = lds_byte(wr * 64 + fr, fq * 8), boff = lds_byte(wc * 32 + fr, fq * 8);
;     ...
;         PG8_STAGE(PG8_SB(0, 0), cB, voffB); PG8_STAGE(PG8_SB(0, 1), cB + hstepB, voffB); PG8_STAGE(PG8_SA(0, 0), cA, voffA); PG8_STAGE(PG8_SA(0, 1), cA + hstepA, voffA);
;         if (wr == 1) PG8_BAR;
;         PG8_WAIT_V(2); PG8_BAR;
;         PG8_STAGE(PG8_SB(1, 0), cB + kstep, voffB); PG8_STAGE(PG8_SA(1, 0), cA + kstep, voffA); PG8_STAGE(PG8_SB(1, 1), cB + hstepB + kstep, voffB);
;         PG8_WAIT_V(6); PG8_BAR;
.LBB0_914:
	v_lshrrev_b32_e32 v16, 1, v14
	v_and_b32_e32 v16, 24, v16
	v_and_b32_e32 v15, 15, v14
	v_lshlrev_b32_e32 v17, 1, v16
	v_lshlrev_b32_e32 v14, 2, v14
	s_sext_i32_i16 s12, s6
	v_lshl_or_b32 v140, s9, 6, v15
	v_lshl_or_b32 v15, v15, 6, v17
	s_lshl_b32 s6, s9, 13
	v_and_b32_e32 v14, 32, v14
	v_bitop3_b32 v17, v15, s6, v14 bitop3:0xde
	s_lshl_b32 s6, s8, 5
	s_and_b32 s14, s6, 0x60
	s_add_i32 m0, s21, 0x18000
	v_lshl_add_u64 v[6:7], v[6:7], 0, s[10:11]
	s_lshl_b32 s6, s14, 7
	s_waitcnt vmcnt(2)
	s_barrier
	global_load_lds_dwordx4 v[6:7], off
	v_lshl_add_u64 v[4:5], v[4:5], 0, s[10:11]
	s_add_i32 m0, s21, 0x1a000
	s_add_i32 s39, s21, 0x8000
	s_add_i32 s48, s21, 0xa000
	global_load_lds_dwordx4 v[4:5], off
	v_lshl_add_u64 v[0:1], v[0:1], 0, s[10:11]
	s_mov_b32 m0, s39
	s_add_u32 s8, s24, 0x40080
	global_load_lds_dwordx4 v[0:1], off
	v_lshl_add_u64 v[0:1], v[2:3], 0, s[10:11]
	s_mov_b32 m0, s48
	s_addc_u32 s9, s25, 0
	global_load_lds_dwordx4 v[0:1], off
	s_add_i32 m0, s21, 0x1c000
	v_lshl_add_u64 v[0:1], s[8:9], 0, v[208:209]
	global_load_lds_dwordx4 v208, s[8:9]
	v_lshl_add_u64 v[0:1], s[8:9], 0, v[128:129]
	s_add_i32 m0, s21, 0x1e000
	s_cmpk_lt_u32 s7, 0x100
	global_load_lds_dwordx4 v128, s[8:9]
	v_lshlrev_b32_e32 v0, 14, v12
	v_and_b32_e32 v0, 0xffff8000, v0
	v_lshl_add_u32 v0, v11, 11, v0
	v_and_b32_e32 v1, 1, v12
	v_lshl_or_b32 v0, v1, 6, v0
	v_lshl_add_u32 v134, v13, 1, v0
	v_lshlrev_b32_e32 v0, 14, v8
	v_and_b32_e32 v0, 0xffff8000, v0
	s_waitcnt vmcnt(6)
	v_lshl_add_u32 v0, v9, 11, v0
	v_and_b32_e32 v1, 1, v8
	v_lshl_or_b32 v0, v1, 6, v0
	v_bitop3_b32 v141, v15, s6, v14 bitop3:0xde
	s_cselect_b64 s[6:7], -1, 0
	v_or_b32_e32 v142, s14, v16
	v_mov_b32_e32 v135, v209
	v_lshl_add_u32 v136, v10, 1, v0
	v_mov_b32_e32 v137, v209
	s_mov_b32 s49, 0
	v_add_u32_e32 v143, 0, v17
	s_barrier
	s_branch .LBB0_917

; #define PG8_STAGE(bufoff, gbase, voff) do { _Pragma("unroll") for (int _i = 0; _i < 2; ++_i) \
;         __builtin_amdgcn_global_load_lds((const unsigned*)((const char*)(gbase) + (voff)[_i]), (PG8_LAS unsigned*)(lds + (bufoff) + ldsw + _i * 8192), 16, 0, 0); } while (0)
; #define PG8_LDA(dst, b, h) do { _Pragma("unroll") for (int m = 0; m < 4; ++m) _Pragma("unroll") for (int k = 0; k < 2; ++k) dst[m][k] = *(const PG8_LAS bf16x8*)(lds + PG8_SA(b, h) + aoff + m * 2048 + k * 1024); } while (0)
; #define PG8_LDB(dst, b, h) do { _Pragma("unroll") for (int n = 0; n < 2; ++n) _Pragma("unroll") for (int k = 0; k < 2; ++k) dst[n][k] = *(const PG8_LAS bf16x8*)(lds + PG8_SB(b, h) + boff + n * 2048 + k * 1024); } while (0)
; #define PG8_MMA(ai, bj, At, Bt) do { __builtin_amdgcn_s_setprio(1); _Pragma("unroll") for (int m = 0; m < 4; ++m) _Pragma("unroll") for (int n = 0; n < 2; ++n) _Pragma("unroll") for (int k = 0; k < 2; ++k) \
;         acc[ai][bj][m][n] = __builtin_amdgcn_mfma_f32_16x16x32_bf16(Bt[n][k], At[m][k], acc[ai][bj][m][n], 0, 0, 0); __builtin_amdgcn_s_setprio(0); } while (0)
; #define PG8_WAIT_V(n) asm volatile("s_waitcnt vmcnt(" #n ")" ::: "memory")
; #define PG8_WAIT_L(n) asm volatile("s_waitcnt lgkmcnt(" #n ")" ::: "memory")
; #define PG8_BAR __builtin_amdgcn_s_barrier()
; #define PG8_SCHED __builtin_amdgcn_sched_barrier(0)
; template <class Epi, class Sched, bool ALIGN_EPI = false, bool SP2 = false>
; __device__ __forceinline__ void gemm_phase(PG8_LAS unsigned char* lds, const Gemm g, const Sched& S, const Epi& E) {
;     ...
;             PG8_LDB(B0, 0, 0); PG8_LDB(B1, 0, 1); PG8_SCHED; PG8_LDA(At, 0, 0); PG8_STAGE(PG8_SA(1, 1), a1 + hstepA, voffA);
;             PG8_WAIT_V(8); PG8_WAIT_L(0); PG8_BAR; PG8_MMA(0, 0, At, B0); PG8_MMA(0, 1, At, B1); PG8_BAR; PG8_SCHED;
;             PG8_LDA(At, 0, 1); PG8_STAGE(PG8_SB(0, 0), b2, voffB); PG8_STAGE(PG8_SB(0, 1), b2 + hstepB, voffB); PG8_STAGE(PG8_SA(0, 0), a2, voffA);
;             PG8_WAIT_V(8); PG8_WAIT_L(0); PG8_BAR; PG8_MMA(1, 0, At, B0); PG8_MMA(1, 1, At, B1); PG8_BAR; PG8_SCHED;
.LBB0_920:
	s_add_u32 s22, s0, 0xfffc0080
	s_addc_u32 s23, s1, -1
	s_add_i32 s28, 0, 0x10000
	s_cmp_eq_u32 s51, 12
	s_cselect_b32 s25, s14, s23
	s_cselect_b32 s24, s15, s22
	v_add_u32_e32 v138, s28, v141
	s_cselect_b32 s23, s9, s50
	s_cselect_b32 s22, s38, s43
	s_add_i32 s30, 0, 0x14000
	ds_read_b128 v[144:147], v138
	ds_read_b128 v[148:151], v138 offset:1024
	ds_read_b128 v[152:155], v138 offset:2048
	ds_read_b128 v[156:159], v138 offset:3072
	v_add_u32_e32 v138, s30, v141
	ds_read_b128 v[160:163], v138
	ds_read_b128 v[164:167], v138 offset:1024
	ds_read_b128 v[168:171], v138 offset:2048
	ds_read_b128 v[172:175], v138 offset:3072
	s_add_i32 m0, s21, 0xc000
	ds_read_b128 v[176:179], v143
	ds_read_b128 v[180:183], v143 offset:1024
	ds_read_b128 v[184:187], v143 offset:2048
	ds_read_b128 v[188:191], v143 offset:3072
	ds_read_b128 v[192:195], v143 offset:4096
	ds_read_b128 v[196:199], v143 offset:5120
	ds_read_b128 v[200:203], v143 offset:6144
	ds_read_b128 v[204:207], v143 offset:7168
	global_load_lds_dwordx4 v134, s[0:1]
	s_add_i32 m0, s21, 0xe000
	s_nop 0
	global_load_lds_dwordx4 v136, s[0:1]
	s_waitcnt vmcnt(8)
	s_waitcnt lgkmcnt(0)
	s_barrier
	s_waitcnt lgkmcnt(0)
	v_mfma_f32_16x16x32_bf16 v[124:127], v[144:147], v[176:179], v[124:127]
	v_mfma_f32_16x16x32_bf16 v[120:123], v[152:155], v[176:179], v[120:123]
	v_mfma_f32_16x16x32_bf16 v[108:111], v[144:147], v[184:187], v[108:111]
	v_mfma_f32_16x16x32_bf16 v[104:107], v[152:155], v[184:187], v[104:107]
	v_mfma_f32_16x16x32_bf16 v[92:95], v[144:147], v[192:195], v[92:95]
	v_mfma_f32_16x16x32_bf16 v[88:91], v[152:155], v[192:195], v[88:91]
	v_mfma_f32_16x16x32_bf16 v[76:79], v[144:147], v[200:203], v[76:79]
	v_mfma_f32_16x16x32_bf16 v[72:75], v[152:155], v[200:203], v[72:75]
	v_mfma_f32_16x16x32_bf16 v[124:127], v[148:151], v[180:183], v[124:127]
	v_mfma_f32_16x16x32_bf16 v[120:123], v[156:159], v[180:183], v[120:123]
	v_mfma_f32_16x16x32_bf16 v[108:111], v[148:151], v[188:191], v[108:111]
	v_mfma_f32_16x16x32_bf16 v[104:107], v[156:159], v[188:191], v[104:107]
	v_mfma_f32_16x16x32_bf16 v[92:95], v[148:151], v[196:199], v[92:95]
	v_mfma_f32_16x16x32_bf16 v[88:91], v[156:159], v[196:199], v[88:91]
	v_mfma_f32_16x16x32_bf16 v[76:79], v[148:151], v[204:207], v[76:79]
	v_mfma_f32_16x16x32_bf16 v[72:75], v[156:159], v[204:207], v[72:75]
	v_mfma_f32_16x16x32_bf16 v[116:119], v[160:163], v[176:179], v[116:119]
	v_mfma_f32_16x16x32_bf16 v[112:115], v[168:171], v[176:179], v[112:115]
	v_mfma_f32_16x16x32_bf16 v[100:103], v[160:163], v[184:187], v[100:103]
	v_mfma_f32_16x16x32_bf16 v[96:99], v[168:171], v[184:187], v[96:99]
	v_mfma_f32_16x16x32_bf16 v[84:87], v[160:163], v[192:195], v[84:87]
	v_mfma_f32_16x16x32_bf16 v[80:83], v[168:171], v[192:195], v[80:83]
	v_mfma_f32_16x16x32_bf16 v[68:71], v[160:163], v[200:203], v[68:71]
	v_mfma_f32_16x16x32_bf16 v[64:67], v[168:171], v[200:203], v[64:67]
	v_mfma_f32_16x16x32_bf16 v[116:119], v[164:167], v[180:183], v[116:119]
	v_mfma_f32_16x16x32_bf16 v[112:115], v[172:175], v[180:183], v[112:115]
	v_mfma_f32_16x16x32_bf16 v[100:103], v[164:167], v[188:191], v[100:103]
	v_mfma_f32_16x16x32_bf16 v[96:99], v[172:175], v[188:191], v[96:99]
	v_mfma_f32_16x16x32_bf16 v[84:87], v[164:167], v[196:199], v[84:87]
	v_mfma_f32_16x16x32_bf16 v[80:83], v[172:175], v[196:199], v[80:83]
	v_mfma_f32_16x16x32_bf16 v[68:71], v[164:167], v[204:207], v[68:71]
	v_mfma_f32_16x16x32_bf16 v[64:67], v[172:175], v[204:207], v[64:67]
	s_barrier
	s_add_i32 s28, s28, s18
	v_lshl_add_u64 v[138:139], s[22:23], 0, v[208:209]
	s_mov_b32 m0, s28
	ds_read_b128 v[176:179], v143 offset:16384
	ds_read_b128 v[180:183], v143 offset:17408
	ds_read_b128 v[184:187], v143 offset:18432
	ds_read_b128 v[188:191], v143 offset:19456
	ds_read_b128 v[192:195], v143 offset:20480
	ds_read_b128 v[196:199], v143 offset:21504
	ds_read_b128 v[200:203], v143 offset:22528
	ds_read_b128 v[204:207], v143 offset:23552
	global_load_lds_dwordx4 v208, s[22:23]
	s_add_i32 m0, s28, 0x2000
	s_add_u32 s28, s22, 0x40000
	v_lshl_add_u64 v[210:211], s[22:23], 0, v[128:129]
	s_addc_u32 s29, s23, 0
	s_add_i32 s30, s30, s18
	global_load_lds_dwordx4 v128, s[22:23]
	s_mov_b32 m0, s30
	v_lshl_add_u64 v[222:223], s[24:25], 0, v[130:131]
	global_load_lds_dwordx4 v208, s[28:29]
	s_add_i32 m0, s30, 0x2000
	s_nop 0
	global_load_lds_dwordx4 v128, s[28:29]
	v_lshl_add_u64 v[212:213], s[24:25], 0, v[132:133]
	s_mov_b32 m0, s21
	s_nop 0
	global_load_lds_dwordx4 v132, s[24:25]
	s_mov_b32 m0, s26
	s_nop 0
	global_load_lds_dwordx4 v130, s[24:25]
	s_waitcnt vmcnt(8)
	s_waitcnt lgkmcnt(0)
	s_barrier
; #define PG8_STAGE(bufoff, gbase, voff) do { _Pragma("unroll") for (int _i = 0; _i < 2; ++_i) \
;         __builtin_amdgcn_global_load_lds((const unsigned*)((const char*)(gbase) + (voff)[_i]), (PG8_LAS unsigned*)(lds + (bufoff) + ldsw + _i * 8192), 16, 0, 0); } while (0)
; #define PG8_LDA(dst, b, h) do { _Pragma("unroll") for (int m = 0; m < 4; ++m) _Pragma("unroll") for (int k = 0; k < 2; ++k) dst[m][k] = *(const PG8_LAS bf16x8*)(lds + PG8_SA(b, h) + aoff + m * 2048 + k * 1024); } while (0)
; #define PG8_LDB(dst, b, h) do { _Pragma("unroll") for (int n = 0; n < 2; ++n) _Pragma("unroll") for (int k = 0; k < 2; ++k) dst[n][k] = *(const PG8_LAS bf16x8*)(lds + PG8_SB(b, h) + boff + n * 2048 + k * 1024); } while (0)
; #define PG8_MMA(ai, bj, At, Bt) do { __builtin_amdgcn_s_setprio(1); _Pragma("unroll") for (int m = 0; m < 4; ++m) _Pragma("unroll") for (int n = 0; n < 2; ++n) _Pragma("unroll") for (int k = 0; k < 2; ++k) \
;         acc[ai][bj][m][n] = __builtin_amdgcn_mfma_f32_16x16x32_bf16(Bt[n][k], At[m][k], acc[ai][bj][m][n], 0, 0, 0); __builtin_amdgcn_s_setprio(0); } while (0)
; #define PG8_WAIT_V(n) asm volatile("s_waitcnt vmcnt(" #n ")" ::: "memory")
; #define PG8_WAIT_L(n) asm volatile("s_waitcnt lgkmcnt(" #n ")" ::: "memory")
; #define PG8_BAR __builtin_amdgcn_s_barrier()
; #define PG8_SCHED __builtin_amdgcn_sched_barrier(0)
; template <class Epi, class Sched, bool ALIGN_EPI = false, bool SP2 = false>
; __device__ __forceinline__ void gemm_phase(PG8_LAS unsigned char* lds, const Gemm g, const Sched& S, const Epi& E) {
;     ...
;             PG8_WAIT_V(8); PG8_WAIT_L(0); PG8_BAR; PG8_MMA(1, 0, At, B0); PG8_MMA(1, 1, At, B1); PG8_BAR; PG8_SCHED;
;             PG8_LDB(B0, 1, 0); PG8_LDB(B1, 1, 1); PG8_SCHED; PG8_LDA(At, 1, 0); PG8_STAGE(PG8_SA(0, 1), a2 + hstepA, voffA);
;             PG8_WAIT_V(8); PG8_WAIT_L(0); PG8_BAR; PG8_MMA(0, 0, At, B0); PG8_MMA(0, 1, At, B1); PG8_BAR; PG8_SCHED;
	s_waitcnt lgkmcnt(0)
	v_mfma_f32_16x16x32_bf16 v[60:63], v[144:147], v[176:179], v[60:63]
	v_mfma_f32_16x16x32_bf16 v[56:59], v[152:155], v[176:179], v[56:59]
	v_mfma_f32_16x16x32_bf16 v[44:47], v[144:147], v[184:187], v[44:47]
	v_mfma_f32_16x16x32_bf16 v[40:43], v[152:155], v[184:187], v[40:43]
	v_mfma_f32_16x16x32_bf16 v[28:31], v[144:147], v[192:195], v[28:31]
	v_mfma_f32_16x16x32_bf16 v[24:27], v[152:155], v[192:195], v[24:27]
	v_mfma_f32_16x16x32_bf16 v[12:15], v[144:147], v[200:203], v[12:15]
	v_mfma_f32_16x16x32_bf16 v[8:11], v[152:155], v[200:203], v[8:11]
	v_mfma_f32_16x16x32_bf16 v[60:63], v[148:151], v[180:183], v[60:63]
	v_mfma_f32_16x16x32_bf16 v[56:59], v[156:159], v[180:183], v[56:59]
	v_mfma_f32_16x16x32_bf16 v[44:47], v[148:151], v[188:191], v[44:47]
	v_mfma_f32_16x16x32_bf16 v[40:43], v[156:159], v[188:191], v[40:43]
	v_mfma_f32_16x16x32_bf16 v[28:31], v[148:151], v[196:199], v[28:31]
	v_mfma_f32_16x16x32_bf16 v[24:27], v[156:159], v[196:199], v[24:27]
	v_mfma_f32_16x16x32_bf16 v[12:15], v[148:151], v[204:207], v[12:15]
	v_mfma_f32_16x16x32_bf16 v[8:11], v[156:159], v[204:207], v[8:11]
	v_mfma_f32_16x16x32_bf16 v[52:55], v[160:163], v[176:179], v[52:55]
	v_mfma_f32_16x16x32_bf16 v[48:51], v[168:171], v[176:179], v[48:51]
	v_mfma_f32_16x16x32_bf16 v[36:39], v[160:163], v[184:187], v[36:39]
	v_mfma_f32_16x16x32_bf16 v[32:35], v[168:171], v[184:187], v[32:35]
	v_mfma_f32_16x16x32_bf16 v[20:23], v[160:163], v[192:195], v[20:23]
	v_mfma_f32_16x16x32_bf16 v[16:19], v[168:171], v[192:195], v[16:19]
	v_mfma_f32_16x16x32_bf16 v[4:7], v[160:163], v[200:203], v[4:7]
	v_mfma_f32_16x16x32_bf16 v[0:3], v[168:171], v[200:203], v[0:3]
	v_mfma_f32_16x16x32_bf16 v[52:55], v[164:167], v[180:183], v[52:55]
	v_mfma_f32_16x16x32_bf16 v[48:51], v[172:175], v[180:183], v[48:51]
	v_mfma_f32_16x16x32_bf16 v[36:39], v[164:167], v[188:191], v[36:39]
	v_mfma_f32_16x16x32_bf16 v[32:35], v[172:175], v[188:191], v[32:35]
	v_mfma_f32_16x16x32_bf16 v[20:23], v[164:167], v[196:199], v[20:23]
	v_mfma_f32_16x16x32_bf16 v[16:19], v[172:175], v[196:199], v[16:19]
	v_mfma_f32_16x16x32_bf16 v[4:7], v[164:167], v[204:207], v[4:7]
	v_mfma_f32_16x16x32_bf16 v[0:3], v[172:175], v[204:207], v[0:3]
	s_barrier
	s_add_i32 s28, 0, 0x18000
	s_add_i32 s29, 0, 0x1c000
	v_add_u32_e32 v156, s28, v141
	v_add_u32_e32 v172, s29, v141
	ds_read_b128 v[144:147], v156
	ds_read_b128 v[148:151], v156 offset:1024
	ds_read_b128 v[152:155], v156 offset:2048
	ds_read_b128 v[156:159], v156 offset:3072
	ds_read_b128 v[160:163], v172
	ds_read_b128 v[164:167], v172 offset:1024
	ds_read_b128 v[168:171], v172 offset:2048
	ds_read_b128 v[172:175], v172 offset:3072
	s_add_u32 s24, s24, 0x40000
	s_addc_u32 s25, s25, 0
	s_mov_b32 m0, s34
	ds_read_b128 v[176:179], v143 offset:32768
	ds_read_b128 v[180:183], v143 offset:33792
	ds_read_b128 v[184:187], v143 offset:34816
	ds_read_b128 v[188:191], v143 offset:35840
	ds_read_b128 v[192:195], v143 offset:36864
	ds_read_b128 v[196:199], v143 offset:37888
	ds_read_b128 v[200:203], v143 offset:38912
	ds_read_b128 v[204:207], v143 offset:39936
	global_load_lds_dwordx4 v132, s[24:25]
	v_lshl_add_u64 v[224:225], s[24:25], 0, v[130:131]
	s_mov_b32 m0, s35
	s_nop 0
	global_load_lds_dwordx4 v130, s[24:25]
	s_waitcnt vmcnt(8)
	s_waitcnt lgkmcnt(0)
	s_barrier
	s_waitcnt lgkmcnt(0)
	v_mfma_f32_16x16x32_bf16 v[124:127], v[144:147], v[176:179], v[124:127]
	v_mfma_f32_16x16x32_bf16 v[120:123], v[152:155], v[176:179], v[120:123]
	v_mfma_f32_16x16x32_bf16 v[108:111], v[144:147], v[184:187], v[108:111]
	v_mfma_f32_16x16x32_bf16 v[104:107], v[152:155], v[184:187], v[104:107]
	v_mfma_f32_16x16x32_bf16 v[92:95], v[144:147], v[192:195], v[92:95]
	v_mfma_f32_16x16x32_bf16 v[88:91], v[152:155], v[192:195], v[88:91]
	v_mfma_f32_16x16x32_bf16 v[76:79], v[144:147], v[200:203], v[76:79]
	v_mfma_f32_16x16x32_bf16 v[72:75], v[152:155], v[200:203], v[72:75]
	v_mfma_f32_16x16x32_bf16 v[124:127], v[148:151], v[180:183], v[124:127]
	v_mfma_f32_16x16x32_bf16 v[120:123], v[156:159], v[180:183], v[120:123]
	v_mfma_f32_16x16x32_bf16 v[108:111], v[148:151], v[188:191], v[108:111]
	v_mfma_f32_16x16x32_bf16 v[104:107], v[156:159], v[188:191], v[104:107]
	v_mfma_f32_16x16x32_bf16 v[92:95], v[148:151], v[196:199], v[92:95]
	v_mfma_f32_16x16x32_bf16 v[88:91], v[156:159], v[196:199], v[88:91]
	v_mfma_f32_16x16x32_bf16 v[76:79], v[148:151], v[204:207], v[76:79]
	v_mfma_f32_16x16x32_bf16 v[72:75], v[156:159], v[204:207], v[72:75]
	v_mfma_f32_16x16x32_bf16 v[116:119], v[160:163], v[176:179], v[116:119]
	v_mfma_f32_16x16x32_bf16 v[112:115], v[168:171], v[176:179], v[112:115]
	v_mfma_f32_16x16x32_bf16 v[100:103], v[160:163], v[184:187], v[100:103]
	v_mfma_f32_16x16x32_bf16 v[96:99], v[168:171], v[184:187], v[96:99]
	v_mfma_f32_16x16x32_bf16 v[84:87], v[160:163], v[192:195], v[84:87]
	v_mfma_f32_16x16x32_bf16 v[80:83], v[168:171], v[192:195], v[80:83]
	v_mfma_f32_16x16x32_bf16 v[68:71], v[160:163], v[200:203], v[68:71]
	v_mfma_f32_16x16x32_bf16 v[64:67], v[168:171], v[200:203], v[64:67]
	v_mfma_f32_16x16x32_bf16 v[116:119], v[164:167], v[180:183], v[116:119]
	v_mfma_f32_16x16x32_bf16 v[112:115], v[172:175], v[180:183], v[112:115]
	v_mfma_f32_16x16x32_bf16 v[100:103], v[164:167], v[188:191], v[100:103]
	v_mfma_f32_16x16x32_bf16 v[96:99], v[172:175], v[188:191], v[96:99]
	v_mfma_f32_16x16x32_bf16 v[84:87], v[164:167], v[196:199], v[84:87]
	v_mfma_f32_16x16x32_bf16 v[80:83], v[172:175], v[196:199], v[80:83]
	v_mfma_f32_16x16x32_bf16 v[68:71], v[164:167], v[204:207], v[68:71]
	v_mfma_f32_16x16x32_bf16 v[64:67], v[172:175], v[204:207], v[64:67]
	s_barrier
; #define PG8_STAGE(bufoff, gbase, voff) do { _Pragma("unroll") for (int _i = 0; _i < 2; ++_i) \
;         __builtin_amdgcn_global_load_lds((const unsigned*)((const char*)(gbase) + (voff)[_i]), (PG8_LAS unsigned*)(lds + (bufoff) + ldsw + _i * 8192), 16, 0, 0); } while (0)
; #define PG8_LDA(dst, b, h) do { _Pragma("unroll") for (int m = 0; m < 4; ++m) _Pragma("unroll") for (int k = 0; k < 2; ++k) dst[m][k] = *(const PG8_LAS bf16x8*)(lds + PG8_SA(b, h) + aoff + m * 2048 + k * 1024); } while (0)
; #define PG8_MMA(ai, bj, At, Bt) do { __builtin_amdgcn_s_setprio(1); _Pragma("unroll") for (int m = 0; m < 4; ++m) _Pragma("unroll") for (int n = 0; n < 2; ++n) _Pragma("unroll") for (int k = 0; k < 2; ++k) \
;         acc[ai][bj][m][n] = __builtin_amdgcn_mfma_f32_16x16x32_bf16(Bt[n][k], At[m][k], acc[ai][bj][m][n], 0, 0, 0); __builtin_amdgcn_s_setprio(0); } while (0)
; #define PG8_WAIT_V(n) asm volatile("s_waitcnt vmcnt(" #n ")" ::: "memory")
; #define PG8_WAIT_L(n) asm volatile("s_waitcnt lgkmcnt(" #n ")" ::: "memory")
; #define PG8_BAR __builtin_amdgcn_s_barrier()
; #define PG8_SCHED __builtin_amdgcn_sched_barrier(0)
; template <class Epi, class Sched, bool ALIGN_EPI = false, bool SP2 = false>
; __device__ __forceinline__ void gemm_phase(PG8_LAS unsigned char* lds, const Gemm g, const Sched& S, const Epi& E) {
;     ...
;             PG8_LDA(At, 1, 1); PG8_STAGE(PG8_SB(1, 0), b3, voffB); PG8_STAGE(PG8_SB(1, 1), b3 + hstepB, voffB); PG8_STAGE(PG8_SA(1, 0), a3, voffA);
;             PG8_WAIT_V(8); PG8_WAIT_L(0); PG8_BAR; PG8_MMA(1, 0, At, B0); PG8_MMA(1, 1, At, B1); PG8_BAR; PG8_SCHED;
	s_add_i32 s24, s28, s18
	v_lshl_add_u64 v[138:139], v[138:139], 0, s[10:11]
	s_mov_b32 m0, s24
	ds_read_b128 v[176:179], v143 offset:49152
	ds_read_b128 v[180:183], v143 offset:50176
	ds_read_b128 v[184:187], v143 offset:51200
	ds_read_b128 v[188:191], v143 offset:52224
	ds_read_b128 v[192:195], v143 offset:53248
	ds_read_b128 v[196:199], v143 offset:54272
	ds_read_b128 v[200:203], v143 offset:55296
	ds_read_b128 v[204:207], v143 offset:56320
	global_load_lds_dwordx4 v[138:139], off
	s_add_i32 m0, s24, 0x2000
	s_add_u32 s22, s22, 0x40080
	v_lshl_add_u64 v[138:139], v[210:211], 0, s[10:11]
	s_addc_u32 s23, s23, 0
	s_add_i32 s24, s29, s18
	global_load_lds_dwordx4 v[138:139], off
	s_mov_b32 m0, s24
	s_nop 0
	global_load_lds_dwordx4 v208, s[22:23]
	s_add_i32 m0, s24, 0x2000
	s_nop 0
	global_load_lds_dwordx4 v128, s[22:23]
	v_lshl_add_u64 v[138:139], v[212:213], 0, s[10:11]
	s_mov_b32 m0, s39
	s_nop 0
	global_load_lds_dwordx4 v[138:139], off
	v_lshl_add_u64 v[138:139], v[222:223], 0, s[10:11]
	s_mov_b32 m0, s48
	s_nop 0
	global_load_lds_dwordx4 v[138:139], off
	s_waitcnt vmcnt(8)
	s_waitcnt lgkmcnt(0)
	s_barrier
	s_waitcnt lgkmcnt(0)
	v_mfma_f32_16x16x32_bf16 v[60:63], v[144:147], v[176:179], v[60:63]
	v_mfma_f32_16x16x32_bf16 v[56:59], v[152:155], v[176:179], v[56:59]
	v_mfma_f32_16x16x32_bf16 v[44:47], v[144:147], v[184:187], v[44:47]
	v_mfma_f32_16x16x32_bf16 v[40:43], v[152:155], v[184:187], v[40:43]
	v_mfma_f32_16x16x32_bf16 v[28:31], v[144:147], v[192:195], v[28:31]
	v_mfma_f32_16x16x32_bf16 v[24:27], v[152:155], v[192:195], v[24:27]
	v_mfma_f32_16x16x32_bf16 v[12:15], v[144:147], v[200:203], v[12:15]
	v_mfma_f32_16x16x32_bf16 v[8:11], v[152:155], v[200:203], v[8:11]
	v_mfma_f32_16x16x32_bf16 v[60:63], v[148:151], v[180:183], v[60:63]
	v_mfma_f32_16x16x32_bf16 v[56:59], v[156:159], v[180:183], v[56:59]
	v_mfma_f32_16x16x32_bf16 v[44:47], v[148:151], v[188:191], v[44:47]
	v_mfma_f32_16x16x32_bf16 v[40:43], v[156:159], v[188:191], v[40:43]
	v_mfma_f32_16x16x32_bf16 v[28:31], v[148:151], v[196:199], v[28:31]
	v_mfma_f32_16x16x32_bf16 v[24:27], v[156:159], v[196:199], v[24:27]
	v_mfma_f32_16x16x32_bf16 v[12:15], v[148:151], v[204:207], v[12:15]
	v_mfma_f32_16x16x32_bf16 v[8:11], v[156:159], v[204:207], v[8:11]
	v_mfma_f32_16x16x32_bf16 v[52:55], v[160:163], v[176:179], v[52:55]
	v_mfma_f32_16x16x32_bf16 v[48:51], v[168:171], v[176:179], v[48:51]
	v_mfma_f32_16x16x32_bf16 v[36:39], v[160:163], v[184:187], v[36:39]
	v_mfma_f32_16x16x32_bf16 v[32:35], v[168:171], v[184:187], v[32:35]
	v_mfma_f32_16x16x32_bf16 v[20:23], v[160:163], v[192:195], v[20:23]
	v_mfma_f32_16x16x32_bf16 v[16:19], v[168:171], v[192:195], v[16:19]
	v_mfma_f32_16x16x32_bf16 v[4:7], v[160:163], v[200:203], v[4:7]
	v_mfma_f32_16x16x32_bf16 v[0:3], v[168:171], v[200:203], v[0:3]
	v_mfma_f32_16x16x32_bf16 v[52:55], v[164:167], v[180:183], v[52:55]
	v_mfma_f32_16x16x32_bf16 v[48:51], v[172:175], v[180:183], v[48:51]
	v_mfma_f32_16x16x32_bf16 v[36:39], v[164:167], v[188:191], v[36:39]
	v_mfma_f32_16x16x32_bf16 v[32:35], v[172:175], v[188:191], v[32:35]
	v_mfma_f32_16x16x32_bf16 v[20:23], v[164:167], v[196:199], v[20:23]
	v_mfma_f32_16x16x32_bf16 v[16:19], v[172:175], v[196:199], v[16:19]
	v_mfma_f32_16x16x32_bf16 v[4:7], v[164:167], v[204:207], v[4:7]
	v_mfma_f32_16x16x32_bf16 v[0:3], v[172:175], v[204:207], v[0:3]
	s_barrier
	s_add_i32 s51, s51, 2
	s_add_u32 s0, s0, 0x100
	s_addc_u32 s1, s1, 0
	s_add_u32 s43, s43, 0x100
	s_addc_u32 s50, s50, 0
	s_cmp_gt_u32 s51, 13
	s_cbranch_scc0 .LBB0_920
	s_and_b64 vcc, exec, s[6:7]
	s_cbranch_vccz .LBB0_923
	s_barrier

; #define PG8_STAGE(bufoff, gbase, voff) do { _Pragma("unroll") for (int _i = 0; _i < 2; ++_i) \
;         __builtin_amdgcn_global_load_lds((const unsigned*)((const char*)(gbase) + (voff)[_i]), (PG8_LAS unsigned*)(lds + (bufoff) + ldsw + _i * 8192), 16, 0, 0); } while (0)
; #define PG8_WAIT_V(n) asm volatile("s_waitcnt vmcnt(" #n ")" ::: "memory")
; #define PG8_BAR __builtin_amdgcn_s_barrier()
; template <class Epi, class Sched, bool ALIGN_EPI = false, bool SP2 = false>
; __device__ __forceinline__ void gemm_phase(PG8_LAS unsigned char* lds, const Gemm g, const Sched& S, const Epi& E) {
;     ...
;     for (int i = 0; i < 2; ++i) { int R, C; stage_rc(tid * 16 + i * 8192, R, C); const int Rb = Epi::PERM ? ((R & ~31) + perm32(R & 31)) : R;
;         voffA[i] = (unsigned)(R * g.lda + C) * 2u; voffB[i] = (unsigned)(Rb * g.ldb + C) * 2u; }
;     const size_t kstep = (size_t)(BK * 2);
;     const size_t hstepA = (size_t)HALF * g.lda * 2, hstepB = (size_t)HALF * g.ldb * 2;
;     const size_t tstepA = 2 * hstepA, tstepB = 2 * hstepB;
;     const unsigned ldsw = (unsigned)wid * 1024u;
;     const int aoff = lds_byte(wr * 64 + fr, fq * 8), boff = lds_byte(wc * 32 + fr, fq * 8);
;     ...
;         PG8_STAGE(PG8_SB(0, 0), cB, voffB); PG8_STAGE(PG8_SB(0, 1), cB + hstepB, voffB); PG8_STAGE(PG8_SA(0, 0), cA, voffA); PG8_STAGE(PG8_SA(0, 1), cA + hstepA, voffA);
;         if (wr == 1) PG8_BAR;
;         PG8_WAIT_V(2); PG8_BAR;
;         PG8_STAGE(PG8_SB(1, 0), cB + kstep, voffB); PG8_STAGE(PG8_SA(1, 0), cA + kstep, voffA); PG8_STAGE(PG8_SB(1, 1), cB + hstepB + kstep, voffB);
;         PG8_WAIT_V(6); PG8_BAR;
.LBB0_986:
	v_bfe_u32 v17, v16, 4, 2
	v_and_b32_e32 v18, 15, v16
	v_lshlrev_b32_e32 v19, 4, v17
	v_lshlrev_b32_e32 v16, 2, v16
	v_lshl_or_b32 v140, s5, 6, v18
	v_lshl_or_b32 v18, v18, 6, v19
	s_lshl_b32 s5, s5, 13
	v_and_b32_e32 v16, 32, v16
	v_bitop3_b32 v19, v18, s5, v16 bitop3:0xde
	s_lshl_b32 s5, s8, 5
	s_and_b32 s5, s5, 0x60
	s_add_i32 m0, s26, 0x18000
	v_lshl_add_u64 v[6:7], v[6:7], 0, s[10:11]
	s_lshl_b32 s8, s5, 7
	s_waitcnt vmcnt(2)
	s_barrier
	global_load_lds_dwordx4 v[6:7], off
	v_lshl_add_u64 v[4:5], v[4:5], 0, s[10:11]
	s_add_i32 m0, s26, 0x1a000
	s_add_i32 s44, s26, 0x8000
	s_add_i32 s45, s26, 0xa000
	v_bitop3_b32 v141, v18, s8, v16 bitop3:0xde
	global_load_lds_dwordx4 v[4:5], off
	v_lshl_add_u64 v[0:1], v[0:1], 0, s[10:11]
	s_mov_b32 m0, s44
	s_add_u32 s8, s20, 0xb0080
	s_sext_i32_i8 s38, s9
	global_load_lds_dwordx4 v[0:1], off
	v_lshl_add_u64 v[0:1], v[2:3], 0, s[10:11]
	s_mov_b32 m0, s45
	s_addc_u32 s9, s21, 0
	global_load_lds_dwordx4 v[0:1], off
	s_add_i32 m0, s26, 0x1c000
	v_lshl_add_u64 v[0:1], s[8:9], 0, v[208:209]
	global_load_lds_dwordx4 v208, s[8:9]
	v_lshl_add_u64 v[0:1], s[8:9], 0, v[128:129]
	s_add_i32 m0, s26, 0x1e000
	s_movk_i32 s14, 0xb00
	global_load_lds_dwordx4 v128, s[8:9]
	v_lshrrev_b32_e32 v1, 1, v8
	v_mul_lo_u32 v0, v10, s14
	s_mov_b32 s15, 0xb000
	s_cmpk_lt_u32 s4, 0x100
	v_lshl_or_b32 v142, v17, 2, s5
	v_mad_u64_u32 v[0:1], s[4:5], v1, s15, v[0:1]
	v_or_b32_e32 v0, v0, v9
	v_add_lshl_u32 v0, v0, v11, 1
	v_mov_b32_e32 v1, v209
	s_mov_b64 s[22:23], 0xb0080
	v_lshl_add_u64 v[130:131], v[0:1], 0, s[22:23]
	v_lshrrev_b32_e32 v1, 1, v12
	v_mul_lo_u32 v0, v14, s14
	v_mad_u64_u32 v[0:1], s[4:5], v1, s15, v[0:1]
	s_waitcnt vmcnt(6)
	v_or_b32_e32 v0, v0, v13
	v_add_lshl_u32 v0, v0, v15, 1
	v_mov_b32_e32 v1, v209
	s_cselect_b64 s[8:9], -1, 0
	v_lshl_add_u64 v[132:133], v[0:1], 0, s[22:23]
	s_mov_b32 s46, 0
	v_add_u32_e32 v143, 0, v19
	s_barrier
	s_branch .LBB0_989

; #define PG8_STAGE(bufoff, gbase, voff) do { _Pragma("unroll") for (int _i = 0; _i < 2; ++_i) \
;         __builtin_amdgcn_global_load_lds((const unsigned*)((const char*)(gbase) + (voff)[_i]), (PG8_LAS unsigned*)(lds + (bufoff) + ldsw + _i * 8192), 16, 0, 0); } while (0)
; #define PG8_LDA(dst, b, h) do { _Pragma("unroll") for (int m = 0; m < 4; ++m) _Pragma("unroll") for (int k = 0; k < 2; ++k) dst[m][k] = *(const PG8_LAS bf16x8*)(lds + PG8_SA(b, h) + aoff + m * 2048 + k * 1024); } while (0)
; #define PG8_LDB(dst, b, h) do { _Pragma("unroll") for (int n = 0; n < 2; ++n) _Pragma("unroll") for (int k = 0; k < 2; ++k) dst[n][k] = *(const PG8_LAS bf16x8*)(lds + PG8_SB(b, h) + boff + n * 2048 + k * 1024); } while (0)
; #define PG8_MMA(ai, bj, At, Bt) do { __builtin_amdgcn_s_setprio(1); _Pragma("unroll") for (int m = 0; m < 4; ++m) _Pragma("unroll") for (int n = 0; n < 2; ++n) _Pragma("unroll") for (int k = 0; k < 2; ++k) \
;         acc[ai][bj][m][n] = __builtin_amdgcn_mfma_f32_16x16x32_bf16(Bt[n][k], At[m][k], acc[ai][bj][m][n], 0, 0, 0); __builtin_amdgcn_s_setprio(0); } while (0)
; #define PG8_WAIT_V(n) asm volatile("s_waitcnt vmcnt(" #n ")" ::: "memory")
; #define PG8_WAIT_L(n) asm volatile("s_waitcnt lgkmcnt(" #n ")" ::: "memory")
; #define PG8_BAR __builtin_amdgcn_s_barrier()
; #define PG8_SCHED __builtin_amdgcn_sched_barrier(0)
; template <class Epi, class Sched, bool ALIGN_EPI = false, bool SP2 = false>
; __device__ __forceinline__ void gemm_phase(PG8_LAS unsigned char* lds, const Gemm g, const Sched& S, const Epi& E) {
;     ...
;             PG8_LDB(B0, 0, 0); PG8_LDB(B1, 0, 1); PG8_SCHED; PG8_LDA(At, 0, 0); PG8_STAGE(PG8_SA(1, 1), a1 + hstepA, voffA);
;             PG8_WAIT_V(8); PG8_WAIT_L(0); PG8_BAR; PG8_MMA(0, 0, At, B0); PG8_MMA(0, 1, At, B1); PG8_BAR; PG8_SCHED;
;             PG8_LDA(At, 0, 1); PG8_STAGE(PG8_SB(0, 0), b2, voffB); PG8_STAGE(PG8_SB(0, 1), b2 + hstepB, voffB); PG8_STAGE(PG8_SA(0, 0), a2, voffA);
;             PG8_WAIT_V(8); PG8_WAIT_L(0); PG8_BAR; PG8_MMA(1, 0, At, B0); PG8_MMA(1, 1, At, B1); PG8_BAR; PG8_SCHED;
.LBB0_1000:
	s_add_u32 s20, s0, 0x100
	s_addc_u32 s21, s1, 0
	s_add_i32 s28, 0, 0x10000
	s_cmp_eq_u32 s49, 40
	s_cselect_b32 s25, s5, s21
	s_cselect_b32 s24, s4, s20
	v_add_u32_e32 v138, s28, v141
	s_cselect_b32 s23, s43, s15
	s_cselect_b32 s22, s42, s14
	s_add_i32 s29, 0, 0x14000
	ds_read_b128 v[134:137], v138
	ds_read_b128 v[144:147], v138 offset:1024
	ds_read_b128 v[148:151], v138 offset:2048
	ds_read_b128 v[152:155], v138 offset:3072
	v_add_u32_e32 v138, s29, v141
	ds_read_b128 v[156:159], v138
	ds_read_b128 v[160:163], v138 offset:1024
	ds_read_b128 v[164:167], v138 offset:2048
	ds_read_b128 v[168:171], v138 offset:3072
	v_lshl_add_u64 v[138:139], s[0:1], 0, v[130:131]
	s_add_i32 m0, s26, 0xc000
	ds_read_b128 v[172:175], v143
	ds_read_b128 v[176:179], v143 offset:1024
	ds_read_b128 v[180:183], v143 offset:2048
	ds_read_b128 v[184:187], v143 offset:3072
	ds_read_b128 v[188:191], v143 offset:4096
	ds_read_b128 v[192:195], v143 offset:5120
	ds_read_b128 v[196:199], v143 offset:6144
	ds_read_b128 v[200:203], v143 offset:7168
	global_load_lds_dwordx4 v[138:139], off
	v_lshl_add_u64 v[138:139], s[0:1], 0, v[132:133]
	s_add_i32 m0, s26, 0xe000
	s_nop 0
	global_load_lds_dwordx4 v[138:139], off
	s_waitcnt vmcnt(8)
	s_waitcnt lgkmcnt(0)
	s_barrier
	s_waitcnt lgkmcnt(0)
	v_mfma_f32_16x16x32_bf16 v[124:127], v[134:137], v[172:175], v[124:127]
	v_mfma_f32_16x16x32_bf16 v[120:123], v[148:151], v[172:175], v[120:123]
	v_mfma_f32_16x16x32_bf16 v[116:119], v[134:137], v[180:183], v[116:119]
	v_mfma_f32_16x16x32_bf16 v[112:115], v[148:151], v[180:183], v[112:115]
	v_mfma_f32_16x16x32_bf16 v[108:111], v[134:137], v[188:191], v[108:111]
	v_mfma_f32_16x16x32_bf16 v[100:103], v[148:151], v[188:191], v[100:103]
	v_mfma_f32_16x16x32_bf16 v[92:95], v[134:137], v[196:199], v[92:95]
	v_mfma_f32_16x16x32_bf16 v[80:83], v[148:151], v[196:199], v[80:83]
	v_mfma_f32_16x16x32_bf16 v[124:127], v[144:147], v[176:179], v[124:127]
	v_mfma_f32_16x16x32_bf16 v[120:123], v[152:155], v[176:179], v[120:123]
	v_mfma_f32_16x16x32_bf16 v[116:119], v[144:147], v[184:187], v[116:119]
	v_mfma_f32_16x16x32_bf16 v[112:115], v[152:155], v[184:187], v[112:115]
	v_mfma_f32_16x16x32_bf16 v[108:111], v[144:147], v[192:195], v[108:111]
	v_mfma_f32_16x16x32_bf16 v[100:103], v[152:155], v[192:195], v[100:103]
	v_mfma_f32_16x16x32_bf16 v[92:95], v[144:147], v[200:203], v[92:95]
	v_mfma_f32_16x16x32_bf16 v[80:83], v[152:155], v[200:203], v[80:83]
	v_mfma_f32_16x16x32_bf16 v[104:107], v[156:159], v[172:175], v[104:107]
	v_mfma_f32_16x16x32_bf16 v[96:99], v[164:167], v[172:175], v[96:99]
	v_mfma_f32_16x16x32_bf16 v[88:91], v[156:159], v[180:183], v[88:91]
	v_mfma_f32_16x16x32_bf16 v[84:87], v[164:167], v[180:183], v[84:87]
	v_mfma_f32_16x16x32_bf16 v[76:79], v[156:159], v[188:191], v[76:79]
	v_mfma_f32_16x16x32_bf16 v[72:75], v[164:167], v[188:191], v[72:75]
	v_mfma_f32_16x16x32_bf16 v[68:71], v[156:159], v[196:199], v[68:71]
	v_mfma_f32_16x16x32_bf16 v[64:67], v[164:167], v[196:199], v[64:67]
	v_mfma_f32_16x16x32_bf16 v[104:107], v[160:163], v[176:179], v[104:107]
	v_mfma_f32_16x16x32_bf16 v[96:99], v[168:171], v[176:179], v[96:99]
	v_mfma_f32_16x16x32_bf16 v[88:91], v[160:163], v[184:187], v[88:91]
	v_mfma_f32_16x16x32_bf16 v[84:87], v[168:171], v[184:187], v[84:87]
	v_mfma_f32_16x16x32_bf16 v[76:79], v[160:163], v[192:195], v[76:79]
	v_mfma_f32_16x16x32_bf16 v[72:75], v[168:171], v[192:195], v[72:75]
	v_mfma_f32_16x16x32_bf16 v[68:71], v[160:163], v[200:203], v[68:71]
	v_mfma_f32_16x16x32_bf16 v[64:67], v[168:171], v[200:203], v[64:67]
	s_barrier
	s_add_i32 s0, s28, s19
	v_lshl_add_u64 v[138:139], s[22:23], 0, v[208:209]
	s_mov_b32 m0, s0
	ds_read_b128 v[172:175], v143 offset:16384
	ds_read_b128 v[176:179], v143 offset:17408
	ds_read_b128 v[180:183], v143 offset:18432
	ds_read_b128 v[184:187], v143 offset:19456
	ds_read_b128 v[188:191], v143 offset:20480
	ds_read_b128 v[192:195], v143 offset:21504
	ds_read_b128 v[196:199], v143 offset:22528
	ds_read_b128 v[200:203], v143 offset:23552
	global_load_lds_dwordx4 v208, s[22:23]
	s_add_i32 m0, s0, 0x2000
	s_add_u32 s0, s22, 0xb0000
	v_lshl_add_u64 v[204:205], s[22:23], 0, v[128:129]
	s_addc_u32 s1, s23, 0
	s_add_i32 s28, s29, s19
	global_load_lds_dwordx4 v128, s[22:23]
	s_mov_b32 m0, s28
	v_lshl_add_u64 v[210:211], s[24:25], 0, v[128:129]
	global_load_lds_dwordx4 v208, s[0:1]
	s_add_i32 m0, s28, 0x2000
	s_nop 0
	global_load_lds_dwordx4 v128, s[0:1]
	v_lshl_add_u64 v[206:207], s[24:25], 0, v[208:209]
	s_mov_b32 m0, s26
	s_nop 0
	global_load_lds_dwordx4 v208, s[24:25]
	s_mov_b32 m0, s34
	s_nop 0
	global_load_lds_dwordx4 v128, s[24:25]
	s_waitcnt vmcnt(8)
	s_waitcnt lgkmcnt(0)
	s_barrier
; #define PG8_STAGE(bufoff, gbase, voff) do { _Pragma("unroll") for (int _i = 0; _i < 2; ++_i) \
;         __builtin_amdgcn_global_load_lds((const unsigned*)((const char*)(gbase) + (voff)[_i]), (PG8_LAS unsigned*)(lds + (bufoff) + ldsw + _i * 8192), 16, 0, 0); } while (0)
; #define PG8_LDA(dst, b, h) do { _Pragma("unroll") for (int m = 0; m < 4; ++m) _Pragma("unroll") for (int k = 0; k < 2; ++k) dst[m][k] = *(const PG8_LAS bf16x8*)(lds + PG8_SA(b, h) + aoff + m * 2048 + k * 1024); } while (0)
; #define PG8_LDB(dst, b, h) do { _Pragma("unroll") for (int n = 0; n < 2; ++n) _Pragma("unroll") for (int k = 0; k < 2; ++k) dst[n][k] = *(const PG8_LAS bf16x8*)(lds + PG8_SB(b, h) + boff + n * 2048 + k * 1024); } while (0)
; #define PG8_MMA(ai, bj, At, Bt) do { __builtin_amdgcn_s_setprio(1); _Pragma("unroll") for (int m = 0; m < 4; ++m) _Pragma("unroll") for (int n = 0; n < 2; ++n) _Pragma("unroll") for (int k = 0; k < 2; ++k) \
;         acc[ai][bj][m][n] = __builtin_amdgcn_mfma_f32_16x16x32_bf16(Bt[n][k], At[m][k], acc[ai][bj][m][n], 0, 0, 0); __builtin_amdgcn_s_setprio(0); } while (0)
; #define PG8_WAIT_V(n) asm volatile("s_waitcnt vmcnt(" #n ")" ::: "memory")
; #define PG8_WAIT_L(n) asm volatile("s_waitcnt lgkmcnt(" #n ")" ::: "memory")
; #define PG8_BAR __builtin_amdgcn_s_barrier()
; #define PG8_SCHED __builtin_amdgcn_sched_barrier(0)
; template <class Epi, class Sched, bool ALIGN_EPI = false, bool SP2 = false>
; __device__ __forceinline__ void gemm_phase(PG8_LAS unsigned char* lds, const Gemm g, const Sched& S, const Epi& E) {
;     ...
;             PG8_WAIT_V(8); PG8_WAIT_L(0); PG8_BAR; PG8_MMA(1, 0, At, B0); PG8_MMA(1, 1, At, B1); PG8_BAR; PG8_SCHED;
;             PG8_LDB(B0, 1, 0); PG8_LDB(B1, 1, 1); PG8_SCHED; PG8_LDA(At, 1, 0); PG8_STAGE(PG8_SA(0, 1), a2 + hstepA, voffA);
;             PG8_WAIT_V(8); PG8_WAIT_L(0); PG8_BAR; PG8_MMA(0, 0, At, B0); PG8_MMA(0, 1, At, B1); PG8_BAR; PG8_SCHED;
	s_waitcnt lgkmcnt(0)
	v_mfma_f32_16x16x32_bf16 v[60:63], v[134:137], v[172:175], v[60:63]
	v_mfma_f32_16x16x32_bf16 v[56:59], v[148:151], v[172:175], v[56:59]
	v_mfma_f32_16x16x32_bf16 v[52:55], v[134:137], v[180:183], v[52:55]
	v_mfma_f32_16x16x32_bf16 v[48:51], v[148:151], v[180:183], v[48:51]
	v_mfma_f32_16x16x32_bf16 v[44:47], v[134:137], v[188:191], v[44:47]
	v_mfma_f32_16x16x32_bf16 v[32:35], v[148:151], v[188:191], v[32:35]
	v_mfma_f32_16x16x32_bf16 v[16:19], v[134:137], v[196:199], v[16:19]
	v_mfma_f32_16x16x32_bf16 v[8:11], v[148:151], v[196:199], v[8:11]
	v_mfma_f32_16x16x32_bf16 v[60:63], v[144:147], v[176:179], v[60:63]
	v_mfma_f32_16x16x32_bf16 v[56:59], v[152:155], v[176:179], v[56:59]
	v_mfma_f32_16x16x32_bf16 v[52:55], v[144:147], v[184:187], v[52:55]
	v_mfma_f32_16x16x32_bf16 v[48:51], v[152:155], v[184:187], v[48:51]
	v_mfma_f32_16x16x32_bf16 v[44:47], v[144:147], v[192:195], v[44:47]
	v_mfma_f32_16x16x32_bf16 v[32:35], v[152:155], v[192:195], v[32:35]
	v_mfma_f32_16x16x32_bf16 v[16:19], v[144:147], v[200:203], v[16:19]
	v_mfma_f32_16x16x32_bf16 v[8:11], v[152:155], v[200:203], v[8:11]
	v_mfma_f32_16x16x32_bf16 v[40:43], v[156:159], v[172:175], v[40:43]
	v_mfma_f32_16x16x32_bf16 v[36:39], v[164:167], v[172:175], v[36:39]
	v_mfma_f32_16x16x32_bf16 v[28:31], v[156:159], v[180:183], v[28:31]
	v_mfma_f32_16x16x32_bf16 v[24:27], v[164:167], v[180:183], v[24:27]
	v_mfma_f32_16x16x32_bf16 v[20:23], v[156:159], v[188:191], v[20:23]
	v_mfma_f32_16x16x32_bf16 v[12:15], v[164:167], v[188:191], v[12:15]
	v_mfma_f32_16x16x32_bf16 v[4:7], v[156:159], v[196:199], v[4:7]
	v_mfma_f32_16x16x32_bf16 v[0:3], v[164:167], v[196:199], v[0:3]
	v_mfma_f32_16x16x32_bf16 v[40:43], v[160:163], v[176:179], v[40:43]
	v_mfma_f32_16x16x32_bf16 v[36:39], v[168:171], v[176:179], v[36:39]
	v_mfma_f32_16x16x32_bf16 v[28:31], v[160:163], v[184:187], v[28:31]
	v_mfma_f32_16x16x32_bf16 v[24:27], v[168:171], v[184:187], v[24:27]
	v_mfma_f32_16x16x32_bf16 v[20:23], v[160:163], v[192:195], v[20:23]
	v_mfma_f32_16x16x32_bf16 v[12:15], v[168:171], v[192:195], v[12:15]
	v_mfma_f32_16x16x32_bf16 v[4:7], v[160:163], v[200:203], v[4:7]
	v_mfma_f32_16x16x32_bf16 v[0:3], v[168:171], v[200:203], v[0:3]
	s_barrier
	s_add_i32 s28, 0, 0x18000
	s_add_i32 s29, 0, 0x1c000
	v_add_u32_e32 v152, s28, v141
	v_add_u32_e32 v168, s29, v141
	ds_read_b128 v[134:137], v152
	ds_read_b128 v[144:147], v152 offset:1024
	ds_read_b128 v[148:151], v152 offset:2048
	ds_read_b128 v[152:155], v152 offset:3072
	ds_read_b128 v[156:159], v168
	ds_read_b128 v[160:163], v168 offset:1024
	ds_read_b128 v[164:167], v168 offset:2048
	ds_read_b128 v[168:171], v168 offset:3072
	s_add_u32 s0, s24, 0xb0000
	s_addc_u32 s1, s25, 0
	s_mov_b32 m0, s35
	ds_read_b128 v[172:175], v143 offset:32768
	ds_read_b128 v[176:179], v143 offset:33792
	ds_read_b128 v[180:183], v143 offset:34816
	ds_read_b128 v[184:187], v143 offset:35840
	ds_read_b128 v[188:191], v143 offset:36864
	ds_read_b128 v[192:195], v143 offset:37888
	ds_read_b128 v[196:199], v143 offset:38912
	ds_read_b128 v[200:203], v143 offset:39936
	global_load_lds_dwordx4 v208, s[0:1]
	s_mov_b32 m0, s39
	s_nop 0
	global_load_lds_dwordx4 v128, s[0:1]
	s_waitcnt vmcnt(8)
	s_waitcnt lgkmcnt(0)
	s_barrier
	s_waitcnt lgkmcnt(0)
	v_mfma_f32_16x16x32_bf16 v[124:127], v[134:137], v[172:175], v[124:127]
	v_mfma_f32_16x16x32_bf16 v[120:123], v[148:151], v[172:175], v[120:123]
	v_mfma_f32_16x16x32_bf16 v[116:119], v[134:137], v[180:183], v[116:119]
	v_mfma_f32_16x16x32_bf16 v[112:115], v[148:151], v[180:183], v[112:115]
	v_mfma_f32_16x16x32_bf16 v[108:111], v[134:137], v[188:191], v[108:111]
	v_mfma_f32_16x16x32_bf16 v[100:103], v[148:151], v[188:191], v[100:103]
	v_mfma_f32_16x16x32_bf16 v[92:95], v[134:137], v[196:199], v[92:95]
	v_mfma_f32_16x16x32_bf16 v[80:83], v[148:151], v[196:199], v[80:83]
	v_mfma_f32_16x16x32_bf16 v[124:127], v[144:147], v[176:179], v[124:127]
	v_mfma_f32_16x16x32_bf16 v[120:123], v[152:155], v[176:179], v[120:123]
	v_mfma_f32_16x16x32_bf16 v[116:119], v[144:147], v[184:187], v[116:119]
	v_mfma_f32_16x16x32_bf16 v[112:115], v[152:155], v[184:187], v[112:115]
	v_mfma_f32_16x16x32_bf16 v[108:111], v[144:147], v[192:195], v[108:111]
	v_mfma_f32_16x16x32_bf16 v[100:103], v[152:155], v[192:195], v[100:103]
	v_mfma_f32_16x16x32_bf16 v[92:95], v[144:147], v[200:203], v[92:95]
	v_mfma_f32_16x16x32_bf16 v[80:83], v[152:155], v[200:203], v[80:83]
	v_mfma_f32_16x16x32_bf16 v[104:107], v[156:159], v[172:175], v[104:107]
	v_mfma_f32_16x16x32_bf16 v[96:99], v[164:167], v[172:175], v[96:99]
	v_mfma_f32_16x16x32_bf16 v[88:91], v[156:159], v[180:183], v[88:91]
	v_mfma_f32_16x16x32_bf16 v[84:87], v[164:167], v[180:183], v[84:87]
	v_mfma_f32_16x16x32_bf16 v[76:79], v[156:159], v[188:191], v[76:79]
	v_mfma_f32_16x16x32_bf16 v[72:75], v[164:167], v[188:191], v[72:75]
	v_mfma_f32_16x16x32_bf16 v[68:71], v[156:159], v[196:199], v[68:71]
	v_mfma_f32_16x16x32_bf16 v[64:67], v[164:167], v[196:199], v[64:67]
	v_mfma_f32_16x16x32_bf16 v[104:107], v[160:163], v[176:179], v[104:107]
	v_mfma_f32_16x16x32_bf16 v[96:99], v[168:171], v[176:179], v[96:99]
	v_mfma_f32_16x16x32_bf16 v[88:91], v[160:163], v[184:187], v[88:91]
	v_mfma_f32_16x16x32_bf16 v[84:87], v[168:171], v[184:187], v[84:87]
	v_mfma_f32_16x16x32_bf16 v[76:79], v[160:163], v[192:195], v[76:79]
	v_mfma_f32_16x16x32_bf16 v[72:75], v[168:171], v[192:195], v[72:75]
	v_mfma_f32_16x16x32_bf16 v[68:71], v[160:163], v[200:203], v[68:71]
	v_mfma_f32_16x16x32_bf16 v[64:67], v[168:171], v[200:203], v[64:67]
	s_barrier
; #define PG8_STAGE(bufoff, gbase, voff) do { _Pragma("unroll") for (int _i = 0; _i < 2; ++_i) \
;         __builtin_amdgcn_global_load_lds((const unsigned*)((const char*)(gbase) + (voff)[_i]), (PG8_LAS unsigned*)(lds + (bufoff) + ldsw + _i * 8192), 16, 0, 0); } while (0)
; #define PG8_LDA(dst, b, h) do { _Pragma("unroll") for (int m = 0; m < 4; ++m) _Pragma("unroll") for (int k = 0; k < 2; ++k) dst[m][k] = *(const PG8_LAS bf16x8*)(lds + PG8_SA(b, h) + aoff + m * 2048 + k * 1024); } while (0)
; #define PG8_MMA(ai, bj, At, Bt) do { __builtin_amdgcn_s_setprio(1); _Pragma("unroll") for (int m = 0; m < 4; ++m) _Pragma("unroll") for (int n = 0; n < 2; ++n) _Pragma("unroll") for (int k = 0; k < 2; ++k) \
;         acc[ai][bj][m][n] = __builtin_amdgcn_mfma_f32_16x16x32_bf16(Bt[n][k], At[m][k], acc[ai][bj][m][n], 0, 0, 0); __builtin_amdgcn_s_setprio(0); } while (0)
; #define PG8_WAIT_V(n) asm volatile("s_waitcnt vmcnt(" #n ")" ::: "memory")
; #define PG8_WAIT_L(n) asm volatile("s_waitcnt lgkmcnt(" #n ")" ::: "memory")
; #define PG8_BAR __builtin_amdgcn_s_barrier()
; #define PG8_SCHED __builtin_amdgcn_sched_barrier(0)
; template <class Epi, class Sched, bool ALIGN_EPI = false, bool SP2 = false>
; __device__ __forceinline__ void gemm_phase(PG8_LAS unsigned char* lds, const Gemm g, const Sched& S, const Epi& E) {
;     ...
;             PG8_LDA(At, 1, 1); PG8_STAGE(PG8_SB(1, 0), b3, voffB); PG8_STAGE(PG8_SB(1, 1), b3 + hstepB, voffB); PG8_STAGE(PG8_SA(1, 0), a3, voffA);
;             PG8_WAIT_V(8); PG8_WAIT_L(0); PG8_BAR; PG8_MMA(1, 0, At, B0); PG8_MMA(1, 1, At, B1); PG8_BAR; PG8_SCHED;
	s_add_i32 s0, s28, s19
	v_lshl_add_u64 v[138:139], v[138:139], 0, s[10:11]
	s_mov_b32 m0, s0
	ds_read_b128 v[172:175], v143 offset:49152
	ds_read_b128 v[176:179], v143 offset:50176
	ds_read_b128 v[180:183], v143 offset:51200
	ds_read_b128 v[184:187], v143 offset:52224
	ds_read_b128 v[188:191], v143 offset:53248
	ds_read_b128 v[192:195], v143 offset:54272
	ds_read_b128 v[196:199], v143 offset:55296
	ds_read_b128 v[200:203], v143 offset:56320
	global_load_lds_dwordx4 v[138:139], off
	s_add_i32 m0, s0, 0x2000
	s_add_u32 s0, s22, 0xb0080
	v_lshl_add_u64 v[138:139], v[204:205], 0, s[10:11]
	s_addc_u32 s1, s23, 0
	s_add_i32 s22, s29, s19
	global_load_lds_dwordx4 v[138:139], off
	s_mov_b32 m0, s22
	s_nop 0
	global_load_lds_dwordx4 v208, s[0:1]
	s_add_i32 m0, s22, 0x2000
	s_nop 0
	global_load_lds_dwordx4 v128, s[0:1]
	v_lshl_add_u64 v[138:139], v[206:207], 0, s[10:11]
	s_mov_b32 m0, s44
	s_nop 0
	global_load_lds_dwordx4 v[138:139], off
	v_lshl_add_u64 v[138:139], v[210:211], 0, s[10:11]
	s_mov_b32 m0, s45
	s_nop 0
	global_load_lds_dwordx4 v[138:139], off
	s_waitcnt vmcnt(8)
	s_waitcnt lgkmcnt(0)
	s_barrier
	s_waitcnt lgkmcnt(0)
	v_mfma_f32_16x16x32_bf16 v[60:63], v[134:137], v[172:175], v[60:63]
	v_mfma_f32_16x16x32_bf16 v[56:59], v[148:151], v[172:175], v[56:59]
	v_mfma_f32_16x16x32_bf16 v[52:55], v[134:137], v[180:183], v[52:55]
	v_mfma_f32_16x16x32_bf16 v[48:51], v[148:151], v[180:183], v[48:51]
	v_mfma_f32_16x16x32_bf16 v[44:47], v[134:137], v[188:191], v[44:47]
	v_mfma_f32_16x16x32_bf16 v[32:35], v[148:151], v[188:191], v[32:35]
	v_mfma_f32_16x16x32_bf16 v[16:19], v[134:137], v[196:199], v[16:19]
	v_mfma_f32_16x16x32_bf16 v[8:11], v[148:151], v[196:199], v[8:11]
	v_mfma_f32_16x16x32_bf16 v[60:63], v[144:147], v[176:179], v[60:63]
	v_mfma_f32_16x16x32_bf16 v[56:59], v[152:155], v[176:179], v[56:59]
	v_mfma_f32_16x16x32_bf16 v[52:55], v[144:147], v[184:187], v[52:55]
	v_mfma_f32_16x16x32_bf16 v[48:51], v[152:155], v[184:187], v[48:51]
	v_mfma_f32_16x16x32_bf16 v[44:47], v[144:147], v[192:195], v[44:47]
	v_mfma_f32_16x16x32_bf16 v[32:35], v[152:155], v[192:195], v[32:35]
	v_mfma_f32_16x16x32_bf16 v[16:19], v[144:147], v[200:203], v[16:19]
	v_mfma_f32_16x16x32_bf16 v[8:11], v[152:155], v[200:203], v[8:11]
	v_mfma_f32_16x16x32_bf16 v[40:43], v[156:159], v[172:175], v[40:43]
	v_mfma_f32_16x16x32_bf16 v[36:39], v[164:167], v[172:175], v[36:39]
	v_mfma_f32_16x16x32_bf16 v[28:31], v[156:159], v[180:183], v[28:31]
	v_mfma_f32_16x16x32_bf16 v[24:27], v[164:167], v[180:183], v[24:27]
	v_mfma_f32_16x16x32_bf16 v[20:23], v[156:159], v[188:191], v[20:23]
	v_mfma_f32_16x16x32_bf16 v[12:15], v[164:167], v[188:191], v[12:15]
	v_mfma_f32_16x16x32_bf16 v[4:7], v[156:159], v[196:199], v[4:7]
	v_mfma_f32_16x16x32_bf16 v[0:3], v[164:167], v[196:199], v[0:3]
	v_mfma_f32_16x16x32_bf16 v[40:43], v[160:163], v[176:179], v[40:43]
	v_mfma_f32_16x16x32_bf16 v[36:39], v[168:171], v[176:179], v[36:39]
	v_mfma_f32_16x16x32_bf16 v[28:31], v[160:163], v[184:187], v[28:31]
	v_mfma_f32_16x16x32_bf16 v[24:27], v[168:171], v[184:187], v[24:27]
	v_mfma_f32_16x16x32_bf16 v[20:23], v[160:163], v[192:195], v[20:23]
	v_mfma_f32_16x16x32_bf16 v[12:15], v[168:171], v[192:195], v[12:15]
	v_mfma_f32_16x16x32_bf16 v[4:7], v[160:163], v[200:203], v[4:7]
	v_mfma_f32_16x16x32_bf16 v[0:3], v[168:171], v[200:203], v[0:3]
	s_barrier
	s_add_i32 s49, s49, 2
	s_add_u32 s14, s14, 0x100
	s_addc_u32 s15, s15, 0
	s_cmp_gt_u32 s49, 41
	s_mov_b64 s[0:1], s[20:21]
	s_cbranch_scc0 .LBB0_1000
	s_and_b64 vcc, exec, s[8:9]
	s_cbranch_vccz .LBB0_1003
	s_barrier
